# peer_out final output stores with nt (non-temporal) hint
# baseline (speedup 1.0000x reference)
; DI void phase_peer_out(const Params& p, char* lds) {
;     ...
;     float coefv[2];
; #pragma unroll
;     for (int grp = 0; grp < 2; ++grp) {
;       const float dt = sw[grp * 64 + lane] * USC[el[grp]];
;       const float ge = 0.5f * dt * (1.f + erff(dt * 0.7071067811865476f));
;       coefv[grp] = gl[grp] * ge * VSC[el[grp]];
;     }
;     f32x2 o2[16];
; #pragma unroll
;     for (int i = 0; i < 16; ++i) o2[i] = f32x2{0.f, 0.f};
; #pragma unroll
;     for (int kb = 0; kb < 8; ++kb) {
;       v6u qb[8];
; #pragma unroll
;       for (int k = 0; k < 8; ++k) {
;         const int e0 = __builtin_amdgcn_readlane(el[0], kb * 8 + k), e1 = __builtin_amdgcn_readlane(el[1], kb * 8 + k);
;         qb[k] = load6(V6 + (size_t)(hb ? e1 : e0) * 768);
;       }
; #pragma unroll
;       for (int k = 0; k < 8; ++k) {
;         const float c0 = __uint_as_float(__builtin_amdgcn_readlane(__float_as_uint(coefv[0]), kb * 8 + k)), c1 = __uint_as_float(__builtin_amdgcn_readlane(__float_as_uint(coefv[1]), kb * 8 + k));
;         const float cf = hb ? c1 : c0;
;         const f32x2 c2 = {cf, cf};
;         const v32f f = __builtin_amdgcn_cvt_scalef32_pk32_f32_fp6(qb[k], 1.0f);
; #pragma unroll
;         for (int i = 0; i < 16; ++i) o2[i] = f32x2{f[2 * i], f[2 * i + 1]} * c2 + o2[i];
;       }
.LBB0_1186:
	s_or_b64 exec, exec, s[12:13]
	v_lshl_add_u64 v[0:1], v[0:1], 2, s[56:57]
	global_load_dword v12, v[0:1], off
	v_readlane_b32 s12, v108, 0
	v_readlane_b32 s13, v107, 0
	v_readlane_b32 s16, v108, 1
	v_mov_b32_e32 v1, s12
	v_mov_b32_e32 v0, s13
	v_cndmask_b32_e64 v0, v0, v1, s[0:1]
	v_mad_i64_i32 v[0:1], s[12:13], v0, s23, v[64:65]
	v_readlane_b32 s12, v107, 1
	v_add_f32_e32 v5, v128, v5
	global_load_dwordx2 v[132:133], v[0:1], off offset:16
	global_load_dwordx4 v[128:131], v[0:1], off
	v_mov_b32_e32 v0, s12
	v_mov_b32_e32 v1, s16
	v_cndmask_b32_e64 v0, v0, v1, s[0:1]
	v_readlane_b32 s17, v108, 2
	v_readlane_b32 s37, v107, 2
	v_mad_i64_i32 v[0:1], s[12:13], v0, s23, v[64:65]
	global_load_dwordx2 v[138:139], v[0:1], off offset:16
	global_load_dwordx4 v[134:137], v[0:1], off
	v_mov_b32_e32 v0, s37
	v_mov_b32_e32 v1, s17
	v_cndmask_b32_e64 v0, v0, v1, s[0:1]
	v_add_f32_e32 v3, v3, v4
	v_mad_i64_i32 v[0:1], s[12:13], v0, s23, v[64:65]
	v_bfi_b32 v7, s34, v8, v7
	v_mul_f32_e32 v8, 0.5, v10
	v_bfi_b32 v4, s34, v11, v9
	v_readlane_b32 s38, v108, 3
	v_readlane_b32 s39, v107, 3
	v_rcp_f32_e32 v10, v5
	v_rcp_f32_e32 v3, v3
	global_load_dwordx2 v[144:145], v[0:1], off offset:16
	global_load_dwordx4 v[140:143], v[0:1], off
	v_readlane_b32 s40, v108, 4
	v_readlane_b32 s41, v107, 4
	v_readlane_b32 s42, v108, 5
	v_readlane_b32 s43, v107, 5
	v_readlane_b32 s44, v108, 6
	v_readlane_b32 s45, v107, 6
	v_add_f32_e32 v5, 1.0, v7
	v_add_f32_e32 v4, 1.0, v4
	v_mov_b32_e32 v7, s39
	v_mov_b32_e32 v9, s38
	v_mul_f32_e32 v6, 0.5, v6
	v_mov_b32_e32 v11, s41
	v_mov_b32_e32 v13, s40
	v_mov_b32_e32 v14, s43
	v_mov_b32_e32 v15, s42
	v_mov_b32_e32 v16, s45
	v_mov_b32_e32 v17, s44
	v_mul_f32_e32 v19, v8, v4
	v_cndmask_b32_e64 v4, v7, v9, s[0:1]
	v_mul_f32_e32 v18, v6, v5
	v_cndmask_b32_e64 v5, v11, v13, s[0:1]
	v_cndmask_b32_e64 v6, v14, v15, s[0:1]
	v_cndmask_b32_e64 v8, v16, v17, s[0:1]
	v_mad_i64_i32 v[0:1], s[12:13], v4, s23, v[64:65]
	v_mad_i64_i32 v[4:5], s[12:13], v5, s23, v[64:65]
	v_mad_i64_i32 v[6:7], s[12:13], v6, s23, v[64:65]
	v_mad_i64_i32 v[8:9], s[12:13], v8, s23, v[64:65]
	global_load_dwordx4 v[146:149], v[0:1], off
	global_load_dwordx2 v[150:151], v[0:1], off offset:16
	global_load_dwordx4 v[50:53], v[4:5], off
	global_load_dwordx2 v[54:55], v[4:5], off offset:16
	global_load_dwordx4 v[44:47], v[6:7], off
	global_load_dwordx2 v[48:49], v[6:7], off offset:16
	global_load_dwordx4 v[38:41], v[8:9], off
	v_mul_f32_e32 v0, v126, v10
	v_mul_f32_e32 v1, v127, v3
	v_mul_f32_e32 v0, v0, v18
	v_mul_f32_e32 v1, v1, v19
	v_readlane_b32 s12, v108, 7
	v_readlane_b32 s13, v107, 7
	s_waitcnt vmcnt(14)
	v_mul_f32_e32 v106, v2, v0
	s_waitcnt vmcnt(13)
	v_mul_f32_e32 v109, v12, v1
	v_mov_b32_e32 v0, s13
	v_mov_b32_e32 v1, s12
	v_cndmask_b32_e64 v0, v0, v1, s[0:1]
	v_mad_i64_i32 v[0:1], s[12:13], v0, s23, v[64:65]
	global_load_dwordx2 v[36:37], v[0:1], off offset:16
	global_load_dwordx2 v[42:43], v[8:9], off offset:16
	global_load_dwordx4 v[32:35], v[0:1], off
	v_readlane_b32 s12, v106, 0
	v_readlane_b32 s13, v109, 0
	s_nop 0
	v_mov_b32_e32 v1, s12
	v_mov_b32_e32 v0, s13
	v_cndmask_b32_e64 v126, v0, v1, s[0:1]
	s_waitcnt vmcnt(14)
	v_cvt_scalef32_pk32_f32_fp6 v[0:31], v[128:133], 1.0
	v_readlane_b32 s12, v106, 1
	v_readlane_b32 s13, v109, 1
	v_pk_fma_f32 v[128:129], v[0:1], v[126:127], 0 op_sel_hi:[1,0,0]
	v_mov_b32_e32 v1, s12
	v_mov_b32_e32 v0, s13
	v_pk_fma_f32 v[130:131], v[2:3], v[126:127], 0 op_sel_hi:[1,0,0]
	v_pk_fma_f32 v[132:133], v[4:5], v[126:127], 0 op_sel_hi:[1,0,0]
	v_pk_fma_f32 v[152:153], v[6:7], v[126:127], 0 op_sel_hi:[1,0,0]
	v_pk_fma_f32 v[154:155], v[8:9], v[126:127], 0 op_sel_hi:[1,0,0]
	v_pk_fma_f32 v[156:157], v[10:11], v[126:127], 0 op_sel_hi:[1,0,0]
	v_pk_fma_f32 v[158:159], v[12:13], v[126:127], 0 op_sel_hi:[1,0,0]
	v_pk_fma_f32 v[160:161], v[14:15], v[126:127], 0 op_sel_hi:[1,0,0]
	v_pk_fma_f32 v[162:163], v[16:17], v[126:127], 0 op_sel_hi:[1,0,0]
	v_pk_fma_f32 v[164:165], v[18:19], v[126:127], 0 op_sel_hi:[1,0,0]
	v_pk_fma_f32 v[166:167], v[20:21], v[126:127], 0 op_sel_hi:[1,0,0]
	v_pk_fma_f32 v[168:169], v[22:23], v[126:127], 0 op_sel_hi:[1,0,0]
	v_pk_fma_f32 v[170:171], v[24:25], v[126:127], 0 op_sel_hi:[1,0,0]
	v_pk_fma_f32 v[172:173], v[26:27], v[126:127], 0 op_sel_hi:[1,0,0]
	v_pk_fma_f32 v[174:175], v[28:29], v[126:127], 0 op_sel_hi:[1,0,0]
	v_pk_fma_f32 v[126:127], v[30:31], v[126:127], 0 op_sel_hi:[1,0,0]
	v_cndmask_b32_e64 v176, v0, v1, s[0:1]
	s_waitcnt vmcnt(12)
	v_cvt_scalef32_pk32_f32_fp6 v[0:31], v[134:139], 1.0
	v_readlane_b32 s12, v106, 2
	v_readlane_b32 s13, v109, 2
	v_pk_fma_f32 v[128:129], v[0:1], v[176:177], v[128:129] op_sel_hi:[1,0,1]
	v_mov_b32_e32 v1, s12
	v_mov_b32_e32 v0, s13
	v_pk_fma_f32 v[130:131], v[2:3], v[176:177], v[130:131] op_sel_hi:[1,0,1]
	v_pk_fma_f32 v[132:133], v[4:5], v[176:177], v[132:133] op_sel_hi:[1,0,1]
	v_pk_fma_f32 v[134:135], v[6:7], v[176:177], v[152:153] op_sel_hi:[1,0,1]
	v_pk_fma_f32 v[136:137], v[8:9], v[176:177], v[154:155] op_sel_hi:[1,0,1]
	v_pk_fma_f32 v[138:139], v[10:11], v[176:177], v[156:157] op_sel_hi:[1,0,1]
	v_pk_fma_f32 v[152:153], v[12:13], v[176:177], v[158:159] op_sel_hi:[1,0,1]
	v_pk_fma_f32 v[154:155], v[14:15], v[176:177], v[160:161] op_sel_hi:[1,0,1]
	v_pk_fma_f32 v[156:157], v[16:17], v[176:177], v[162:163] op_sel_hi:[1,0,1]
	v_pk_fma_f32 v[158:159], v[18:19], v[176:177], v[164:165] op_sel_hi:[1,0,1]
	v_pk_fma_f32 v[160:161], v[20:21], v[176:177], v[166:167] op_sel_hi:[1,0,1]
	v_pk_fma_f32 v[162:163], v[22:23], v[176:177], v[168:169] op_sel_hi:[1,0,1]
	v_pk_fma_f32 v[164:165], v[24:25], v[176:177], v[170:171] op_sel_hi:[1,0,1]
	v_pk_fma_f32 v[166:167], v[26:27], v[176:177], v[172:173] op_sel_hi:[1,0,1]
	v_pk_fma_f32 v[168:169], v[28:29], v[176:177], v[174:175] op_sel_hi:[1,0,1]
	v_pk_fma_f32 v[126:127], v[30:31], v[176:177], v[126:127] op_sel_hi:[1,0,1]
	v_cndmask_b32_e64 v170, v0, v1, s[0:1]
	s_waitcnt vmcnt(10)
; DI void phase_peer_out(const Params& p, char* lds) {
;     ...
;       for (int k = 0; k < 8; ++k) {
;         const float c0 = __uint_as_float(__builtin_amdgcn_readlane(__float_as_uint(coefv[0]), kb * 8 + k)), c1 = __uint_as_float(__builtin_amdgcn_readlane(__float_as_uint(coefv[1]), kb * 8 + k));
;         const float cf = hb ? c1 : c0;
;         const f32x2 c2 = {cf, cf};
;         const v32f f = __builtin_amdgcn_cvt_scalef32_pk32_f32_fp6(qb[k], 1.0f);
; #pragma unroll
;         for (int i = 0; i < 16; ++i) o2[i] = f32x2{f[2 * i], f[2 * i + 1]} * c2 + o2[i];
	v_cvt_scalef32_pk32_f32_fp6 v[0:31], v[140:145], 1.0
	v_readlane_b32 s12, v106, 3
	v_readlane_b32 s13, v109, 3
	v_pk_fma_f32 v[128:129], v[0:1], v[170:171], v[128:129] op_sel_hi:[1,0,1]
	v_mov_b32_e32 v1, s12
	v_mov_b32_e32 v0, s13
	v_pk_fma_f32 v[130:131], v[2:3], v[170:171], v[130:131] op_sel_hi:[1,0,1]
	v_pk_fma_f32 v[132:133], v[4:5], v[170:171], v[132:133] op_sel_hi:[1,0,1]
	v_pk_fma_f32 v[134:135], v[6:7], v[170:171], v[134:135] op_sel_hi:[1,0,1]
	v_pk_fma_f32 v[136:137], v[8:9], v[170:171], v[136:137] op_sel_hi:[1,0,1]
	v_pk_fma_f32 v[138:139], v[10:11], v[170:171], v[138:139] op_sel_hi:[1,0,1]
	v_pk_fma_f32 v[140:141], v[12:13], v[170:171], v[152:153] op_sel_hi:[1,0,1]
	v_pk_fma_f32 v[142:143], v[14:15], v[170:171], v[154:155] op_sel_hi:[1,0,1]
	v_pk_fma_f32 v[144:145], v[16:17], v[170:171], v[156:157] op_sel_hi:[1,0,1]
	v_pk_fma_f32 v[152:153], v[18:19], v[170:171], v[158:159] op_sel_hi:[1,0,1]
	v_pk_fma_f32 v[154:155], v[20:21], v[170:171], v[160:161] op_sel_hi:[1,0,1]
	v_pk_fma_f32 v[156:157], v[22:23], v[170:171], v[162:163] op_sel_hi:[1,0,1]
	v_pk_fma_f32 v[158:159], v[24:25], v[170:171], v[164:165] op_sel_hi:[1,0,1]
	v_pk_fma_f32 v[160:161], v[26:27], v[170:171], v[166:167] op_sel_hi:[1,0,1]
	v_pk_fma_f32 v[162:163], v[28:29], v[170:171], v[168:169] op_sel_hi:[1,0,1]
	v_pk_fma_f32 v[126:127], v[30:31], v[170:171], v[126:127] op_sel_hi:[1,0,1]
	v_cndmask_b32_e64 v164, v0, v1, s[0:1]
	s_waitcnt vmcnt(8)
	v_cvt_scalef32_pk32_f32_fp6 v[0:31], v[146:151], 1.0
	v_readlane_b32 s12, v106, 4
	v_readlane_b32 s13, v109, 4
	v_pk_fma_f32 v[128:129], v[0:1], v[164:165], v[128:129] op_sel_hi:[1,0,1]
	v_mov_b32_e32 v1, s12
	v_mov_b32_e32 v0, s13
	v_pk_fma_f32 v[130:131], v[2:3], v[164:165], v[130:131] op_sel_hi:[1,0,1]
	v_pk_fma_f32 v[132:133], v[4:5], v[164:165], v[132:133] op_sel_hi:[1,0,1]
	v_pk_fma_f32 v[134:135], v[6:7], v[164:165], v[134:135] op_sel_hi:[1,0,1]
	v_pk_fma_f32 v[136:137], v[8:9], v[164:165], v[136:137] op_sel_hi:[1,0,1]
	v_pk_fma_f32 v[138:139], v[10:11], v[164:165], v[138:139] op_sel_hi:[1,0,1]
	v_pk_fma_f32 v[140:141], v[12:13], v[164:165], v[140:141] op_sel_hi:[1,0,1]
	v_pk_fma_f32 v[142:143], v[14:15], v[164:165], v[142:143] op_sel_hi:[1,0,1]
	v_pk_fma_f32 v[144:145], v[16:17], v[164:165], v[144:145] op_sel_hi:[1,0,1]
	v_pk_fma_f32 v[146:147], v[18:19], v[164:165], v[152:153] op_sel_hi:[1,0,1]
	v_pk_fma_f32 v[148:149], v[20:21], v[164:165], v[154:155] op_sel_hi:[1,0,1]
	v_pk_fma_f32 v[150:151], v[22:23], v[164:165], v[156:157] op_sel_hi:[1,0,1]
	v_pk_fma_f32 v[152:153], v[24:25], v[164:165], v[158:159] op_sel_hi:[1,0,1]
	v_pk_fma_f32 v[154:155], v[26:27], v[164:165], v[160:161] op_sel_hi:[1,0,1]
	v_pk_fma_f32 v[156:157], v[28:29], v[164:165], v[162:163] op_sel_hi:[1,0,1]
	v_pk_fma_f32 v[126:127], v[30:31], v[164:165], v[126:127] op_sel_hi:[1,0,1]
	v_cndmask_b32_e64 v158, v0, v1, s[0:1]
	s_waitcnt vmcnt(6)
	v_cvt_scalef32_pk32_f32_fp6 v[0:31], v[50:55], 1.0
	v_readlane_b32 s12, v106, 5
	v_readlane_b32 s13, v109, 5
	v_pk_fma_f32 v[50:51], v[0:1], v[158:159], v[128:129] op_sel_hi:[1,0,1]
	v_mov_b32_e32 v1, s12
	v_mov_b32_e32 v0, s13
	v_pk_fma_f32 v[52:53], v[2:3], v[158:159], v[130:131] op_sel_hi:[1,0,1]
	v_pk_fma_f32 v[54:55], v[4:5], v[158:159], v[132:133] op_sel_hi:[1,0,1]
	v_pk_fma_f32 v[128:129], v[6:7], v[158:159], v[134:135] op_sel_hi:[1,0,1]
	v_pk_fma_f32 v[130:131], v[8:9], v[158:159], v[136:137] op_sel_hi:[1,0,1]
	v_pk_fma_f32 v[132:133], v[10:11], v[158:159], v[138:139] op_sel_hi:[1,0,1]
	v_pk_fma_f32 v[134:135], v[12:13], v[158:159], v[140:141] op_sel_hi:[1,0,1]
	v_pk_fma_f32 v[136:137], v[14:15], v[158:159], v[142:143] op_sel_hi:[1,0,1]
	v_pk_fma_f32 v[138:139], v[16:17], v[158:159], v[144:145] op_sel_hi:[1,0,1]
	v_pk_fma_f32 v[140:141], v[18:19], v[158:159], v[146:147] op_sel_hi:[1,0,1]
	v_pk_fma_f32 v[142:143], v[20:21], v[158:159], v[148:149] op_sel_hi:[1,0,1]
	v_pk_fma_f32 v[144:145], v[22:23], v[158:159], v[150:151] op_sel_hi:[1,0,1]
	v_pk_fma_f32 v[146:147], v[24:25], v[158:159], v[152:153] op_sel_hi:[1,0,1]
	v_pk_fma_f32 v[148:149], v[26:27], v[158:159], v[154:155] op_sel_hi:[1,0,1]
	v_pk_fma_f32 v[150:151], v[28:29], v[158:159], v[156:157] op_sel_hi:[1,0,1]
	v_pk_fma_f32 v[126:127], v[30:31], v[158:159], v[126:127] op_sel_hi:[1,0,1]
	v_cndmask_b32_e64 v152, v0, v1, s[0:1]
	s_waitcnt vmcnt(4)
	v_cvt_scalef32_pk32_f32_fp6 v[0:31], v[44:49], 1.0
	v_readlane_b32 s12, v106, 6
	v_readlane_b32 s13, v109, 6
	v_pk_fma_f32 v[44:45], v[0:1], v[152:153], v[50:51] op_sel_hi:[1,0,1]
	v_mov_b32_e32 v1, s12
	v_mov_b32_e32 v0, s13
	v_pk_fma_f32 v[46:47], v[2:3], v[152:153], v[52:53] op_sel_hi:[1,0,1]
	v_pk_fma_f32 v[48:49], v[4:5], v[152:153], v[54:55] op_sel_hi:[1,0,1]
	v_pk_fma_f32 v[50:51], v[6:7], v[152:153], v[128:129] op_sel_hi:[1,0,1]
	v_pk_fma_f32 v[52:53], v[8:9], v[152:153], v[130:131] op_sel_hi:[1,0,1]
	v_pk_fma_f32 v[54:55], v[10:11], v[152:153], v[132:133] op_sel_hi:[1,0,1]
	v_pk_fma_f32 v[128:129], v[12:13], v[152:153], v[134:135] op_sel_hi:[1,0,1]
	v_pk_fma_f32 v[130:131], v[14:15], v[152:153], v[136:137] op_sel_hi:[1,0,1]
	v_pk_fma_f32 v[132:133], v[16:17], v[152:153], v[138:139] op_sel_hi:[1,0,1]
	v_pk_fma_f32 v[134:135], v[18:19], v[152:153], v[140:141] op_sel_hi:[1,0,1]
	v_pk_fma_f32 v[136:137], v[20:21], v[152:153], v[142:143] op_sel_hi:[1,0,1]
	v_pk_fma_f32 v[138:139], v[22:23], v[152:153], v[144:145] op_sel_hi:[1,0,1]
	v_pk_fma_f32 v[140:141], v[24:25], v[152:153], v[146:147] op_sel_hi:[1,0,1]
	v_pk_fma_f32 v[142:143], v[26:27], v[152:153], v[148:149] op_sel_hi:[1,0,1]
	v_pk_fma_f32 v[144:145], v[28:29], v[152:153], v[150:151] op_sel_hi:[1,0,1]
	v_pk_fma_f32 v[126:127], v[30:31], v[152:153], v[126:127] op_sel_hi:[1,0,1]
	v_cndmask_b32_e64 v146, v0, v1, s[0:1]
	s_waitcnt vmcnt(1)
; DI void phase_peer_out(const Params& p, char* lds) {
;     ...
;     for (int kb = 0; kb < 8; ++kb) {
;       v6u qb[8];
; #pragma unroll
;       for (int k = 0; k < 8; ++k) {
;         const int e0 = __builtin_amdgcn_readlane(el[0], kb * 8 + k), e1 = __builtin_amdgcn_readlane(el[1], kb * 8 + k);
;         qb[k] = load6(V6 + (size_t)(hb ? e1 : e0) * 768);
;       }
; #pragma unroll
;       for (int k = 0; k < 8; ++k) {
;         const float c0 = __uint_as_float(__builtin_amdgcn_readlane(__float_as_uint(coefv[0]), kb * 8 + k)), c1 = __uint_as_float(__builtin_amdgcn_readlane(__float_as_uint(coefv[1]), kb * 8 + k));
;         const float cf = hb ? c1 : c0;
;         const f32x2 c2 = {cf, cf};
;         const v32f f = __builtin_amdgcn_cvt_scalef32_pk32_f32_fp6(qb[k], 1.0f);
; #pragma unroll
;         for (int i = 0; i < 16; ++i) o2[i] = f32x2{f[2 * i], f[2 * i + 1]} * c2 + o2[i];
	v_cvt_scalef32_pk32_f32_fp6 v[0:31], v[38:43], 1.0
	v_readlane_b32 s12, v106, 7
	v_readlane_b32 s13, v109, 7
	v_pk_fma_f32 v[38:39], v[0:1], v[146:147], v[44:45] op_sel_hi:[1,0,1]
	v_mov_b32_e32 v1, s12
	v_mov_b32_e32 v0, s13
	v_readlane_b32 s12, v108, 8
	v_readlane_b32 s13, v107, 8
	v_pk_fma_f32 v[40:41], v[2:3], v[146:147], v[46:47] op_sel_hi:[1,0,1]
	v_pk_fma_f32 v[42:43], v[4:5], v[146:147], v[48:49] op_sel_hi:[1,0,1]
	v_pk_fma_f32 v[44:45], v[6:7], v[146:147], v[50:51] op_sel_hi:[1,0,1]
	v_pk_fma_f32 v[46:47], v[8:9], v[146:147], v[52:53] op_sel_hi:[1,0,1]
	v_pk_fma_f32 v[48:49], v[10:11], v[146:147], v[54:55] op_sel_hi:[1,0,1]
	v_pk_fma_f32 v[50:51], v[12:13], v[146:147], v[128:129] op_sel_hi:[1,0,1]
	v_pk_fma_f32 v[52:53], v[14:15], v[146:147], v[130:131] op_sel_hi:[1,0,1]
	v_pk_fma_f32 v[54:55], v[16:17], v[146:147], v[132:133] op_sel_hi:[1,0,1]
	v_pk_fma_f32 v[132:133], v[18:19], v[146:147], v[134:135] op_sel_hi:[1,0,1]
	v_pk_fma_f32 v[134:135], v[20:21], v[146:147], v[136:137] op_sel_hi:[1,0,1]
	v_pk_fma_f32 v[136:137], v[22:23], v[146:147], v[138:139] op_sel_hi:[1,0,1]
	v_pk_fma_f32 v[138:139], v[24:25], v[146:147], v[140:141] op_sel_hi:[1,0,1]
	v_pk_fma_f32 v[140:141], v[26:27], v[146:147], v[142:143] op_sel_hi:[1,0,1]
	v_pk_fma_f32 v[142:143], v[28:29], v[146:147], v[144:145] op_sel_hi:[1,0,1]
	v_pk_fma_f32 v[144:145], v[30:31], v[146:147], v[126:127] op_sel_hi:[1,0,1]
	v_cndmask_b32_e64 v146, v0, v1, s[0:1]
	v_mov_b32_e32 v0, s13
	v_mov_b32_e32 v1, s12
	v_cndmask_b32_e64 v0, v0, v1, s[0:1]
	v_mad_i64_i32 v[130:131], s[12:13], v0, s23, v[64:65]
	s_waitcnt vmcnt(0)
	v_cvt_scalef32_pk32_f32_fp6 v[0:31], v[32:37], 1.0
	v_readlane_b32 s12, v108, 9
	v_readlane_b32 s13, v107, 9
	v_pk_fma_f32 v[150:151], v[0:1], v[146:147], v[38:39] op_sel_hi:[1,0,1]
	v_mov_b32_e32 v1, s12
	v_mov_b32_e32 v0, s13
	v_cndmask_b32_e64 v0, v0, v1, s[0:1]
	v_mad_i64_i32 v[0:1], s[12:13], v0, s23, v[64:65]
	v_readlane_b32 s12, v108, 10
	v_readlane_b32 s13, v107, 10
	global_load_dwordx4 v[126:129], v[130:131], off
	v_pk_fma_f32 v[168:169], v[18:19], v[146:147], v[132:133] op_sel_hi:[1,0,1]
	global_load_dwordx2 v[130:131], v[130:131], off offset:16
	v_pk_fma_f32 v[170:171], v[20:21], v[146:147], v[134:135] op_sel_hi:[1,0,1]
	v_pk_fma_f32 v[172:173], v[22:23], v[146:147], v[136:137] op_sel_hi:[1,0,1]
	global_load_dwordx2 v[136:137], v[0:1], off offset:16
	global_load_dwordx4 v[132:135], v[0:1], off
	v_mov_b32_e32 v0, s13
	v_mov_b32_e32 v1, s12
	v_cndmask_b32_e64 v0, v0, v1, s[0:1]
	v_mad_i64_i32 v[0:1], s[12:13], v0, s23, v[64:65]
	v_readlane_b32 s12, v108, 11
	v_readlane_b32 s13, v107, 11
	v_pk_fma_f32 v[152:153], v[2:3], v[146:147], v[40:41] op_sel_hi:[1,0,1]
	v_mov_b32_e32 v3, s12
	v_mov_b32_e32 v2, s13
	v_cndmask_b32_e64 v2, v2, v3, s[0:1]
	v_mad_i64_i32 v[2:3], s[12:13], v2, s23, v[64:65]
	v_readlane_b32 s12, v108, 12
	v_readlane_b32 s13, v107, 12
	v_pk_fma_f32 v[154:155], v[4:5], v[146:147], v[42:43] op_sel_hi:[1,0,1]
	v_pk_fma_f32 v[156:157], v[6:7], v[146:147], v[44:45] op_sel_hi:[1,0,1]
	v_pk_fma_f32 v[158:159], v[8:9], v[146:147], v[46:47] op_sel_hi:[1,0,1]
	v_pk_fma_f32 v[160:161], v[10:11], v[146:147], v[48:49] op_sel_hi:[1,0,1]
	v_pk_fma_f32 v[162:163], v[12:13], v[146:147], v[50:51] op_sel_hi:[1,0,1]
	v_pk_fma_f32 v[164:165], v[14:15], v[146:147], v[52:53] op_sel_hi:[1,0,1]
	v_pk_fma_f32 v[166:167], v[16:17], v[146:147], v[54:55] op_sel_hi:[1,0,1]
	v_pk_fma_f32 v[174:175], v[24:25], v[146:147], v[138:139] op_sel_hi:[1,0,1]
	v_pk_fma_f32 v[176:177], v[26:27], v[146:147], v[140:141] op_sel_hi:[1,0,1]
	v_pk_fma_f32 v[178:179], v[28:29], v[146:147], v[142:143] op_sel_hi:[1,0,1]
	v_pk_fma_f32 v[180:181], v[30:31], v[146:147], v[144:145] op_sel_hi:[1,0,1]
	global_load_dwordx4 v[138:141], v[0:1], off
	global_load_dwordx2 v[142:143], v[0:1], off offset:16
	global_load_dwordx4 v[144:147], v[2:3], off
	v_mov_b32_e32 v0, s13
	v_mov_b32_e32 v1, s12
	v_cndmask_b32_e64 v0, v0, v1, s[0:1]
	v_mad_i64_i32 v[0:1], s[12:13], v0, s23, v[64:65]
	v_readlane_b32 s12, v108, 13
	v_readlane_b32 s13, v107, 13
	global_load_dwordx2 v[148:149], v[2:3], off offset:16
	global_load_dwordx4 v[50:53], v[0:1], off
	v_mov_b32_e32 v2, s13
	v_mov_b32_e32 v3, s12
	v_cndmask_b32_e64 v2, v2, v3, s[0:1]
	v_mad_i64_i32 v[2:3], s[12:13], v2, s23, v[64:65]
	v_readlane_b32 s12, v108, 14
	v_readlane_b32 s13, v107, 14
	global_load_dwordx2 v[54:55], v[0:1], off offset:16
	global_load_dwordx4 v[44:47], v[2:3], off
	v_mov_b32_e32 v0, s13
	v_mov_b32_e32 v1, s12
	v_cndmask_b32_e64 v0, v0, v1, s[0:1]
	v_mad_i64_i32 v[0:1], s[12:13], v0, s23, v[64:65]
	v_readlane_b32 s12, v108, 15
	v_readlane_b32 s13, v107, 15
	global_load_dwordx2 v[48:49], v[2:3], off offset:16
	global_load_dwordx4 v[38:41], v[0:1], off
	v_mov_b32_e32 v2, s13
	v_mov_b32_e32 v3, s12
	v_cndmask_b32_e64 v2, v2, v3, s[0:1]
	v_mad_i64_i32 v[2:3], s[12:13], v2, s23, v[64:65]
	global_load_dwordx2 v[36:37], v[2:3], off offset:16
	global_load_dwordx2 v[42:43], v[0:1], off offset:16
	global_load_dwordx4 v[32:35], v[2:3], off
	v_readlane_b32 s12, v106, 8
	v_readlane_b32 s13, v109, 8
	s_nop 0
	v_mov_b32_e32 v1, s12
	v_mov_b32_e32 v0, s13
	v_cndmask_b32_e64 v182, v0, v1, s[0:1]
	v_readlane_b32 s12, v106, 9
	v_readlane_b32 s13, v109, 9
	s_waitcnt vmcnt(14)
; DI void phase_peer_out(const Params& p, char* lds) {
;     ...
;       for (int k = 0; k < 8; ++k) {
;         const float c0 = __uint_as_float(__builtin_amdgcn_readlane(__float_as_uint(coefv[0]), kb * 8 + k)), c1 = __uint_as_float(__builtin_amdgcn_readlane(__float_as_uint(coefv[1]), kb * 8 + k));
;         const float cf = hb ? c1 : c0;
;         const f32x2 c2 = {cf, cf};
;         const v32f f = __builtin_amdgcn_cvt_scalef32_pk32_f32_fp6(qb[k], 1.0f);
; #pragma unroll
;         for (int i = 0; i < 16; ++i) o2[i] = f32x2{f[2 * i], f[2 * i + 1]} * c2 + o2[i];
	v_cvt_scalef32_pk32_f32_fp6 v[0:31], v[126:131], 1.0
	v_pk_fma_f32 v[126:127], v[0:1], v[182:183], v[150:151] op_sel_hi:[1,0,1]
	v_mov_b32_e32 v0, s13
	v_mov_b32_e32 v1, s12
	v_pk_fma_f32 v[128:129], v[2:3], v[182:183], v[152:153] op_sel_hi:[1,0,1]
	v_pk_fma_f32 v[130:131], v[4:5], v[182:183], v[154:155] op_sel_hi:[1,0,1]
	v_pk_fma_f32 v[150:151], v[6:7], v[182:183], v[156:157] op_sel_hi:[1,0,1]
	v_pk_fma_f32 v[152:153], v[8:9], v[182:183], v[158:159] op_sel_hi:[1,0,1]
	v_pk_fma_f32 v[154:155], v[10:11], v[182:183], v[160:161] op_sel_hi:[1,0,1]
	v_pk_fma_f32 v[156:157], v[12:13], v[182:183], v[162:163] op_sel_hi:[1,0,1]
	v_pk_fma_f32 v[158:159], v[14:15], v[182:183], v[164:165] op_sel_hi:[1,0,1]
	v_pk_fma_f32 v[160:161], v[16:17], v[182:183], v[166:167] op_sel_hi:[1,0,1]
	v_pk_fma_f32 v[162:163], v[18:19], v[182:183], v[168:169] op_sel_hi:[1,0,1]
	v_pk_fma_f32 v[164:165], v[20:21], v[182:183], v[170:171] op_sel_hi:[1,0,1]
	v_pk_fma_f32 v[166:167], v[22:23], v[182:183], v[172:173] op_sel_hi:[1,0,1]
	v_pk_fma_f32 v[168:169], v[24:25], v[182:183], v[174:175] op_sel_hi:[1,0,1]
	v_pk_fma_f32 v[170:171], v[26:27], v[182:183], v[176:177] op_sel_hi:[1,0,1]
	v_pk_fma_f32 v[172:173], v[28:29], v[182:183], v[178:179] op_sel_hi:[1,0,1]
	v_pk_fma_f32 v[174:175], v[30:31], v[182:183], v[180:181] op_sel_hi:[1,0,1]
	v_cndmask_b32_e64 v176, v0, v1, s[0:1]
	s_waitcnt vmcnt(12)
	v_cvt_scalef32_pk32_f32_fp6 v[0:31], v[132:137], 1.0
	v_readlane_b32 s12, v106, 10
	v_readlane_b32 s13, v109, 10
	v_pk_fma_f32 v[126:127], v[0:1], v[176:177], v[126:127] op_sel_hi:[1,0,1]
	v_mov_b32_e32 v1, s12
	v_mov_b32_e32 v0, s13
	v_pk_fma_f32 v[128:129], v[2:3], v[176:177], v[128:129] op_sel_hi:[1,0,1]
	v_pk_fma_f32 v[130:131], v[4:5], v[176:177], v[130:131] op_sel_hi:[1,0,1]
	v_pk_fma_f32 v[132:133], v[6:7], v[176:177], v[150:151] op_sel_hi:[1,0,1]
	v_pk_fma_f32 v[134:135], v[8:9], v[176:177], v[152:153] op_sel_hi:[1,0,1]
	v_pk_fma_f32 v[136:137], v[10:11], v[176:177], v[154:155] op_sel_hi:[1,0,1]
	v_pk_fma_f32 v[150:151], v[12:13], v[176:177], v[156:157] op_sel_hi:[1,0,1]
	v_pk_fma_f32 v[152:153], v[14:15], v[176:177], v[158:159] op_sel_hi:[1,0,1]
	v_pk_fma_f32 v[154:155], v[16:17], v[176:177], v[160:161] op_sel_hi:[1,0,1]
	v_pk_fma_f32 v[156:157], v[18:19], v[176:177], v[162:163] op_sel_hi:[1,0,1]
	v_pk_fma_f32 v[158:159], v[20:21], v[176:177], v[164:165] op_sel_hi:[1,0,1]
	v_pk_fma_f32 v[160:161], v[22:23], v[176:177], v[166:167] op_sel_hi:[1,0,1]
	v_pk_fma_f32 v[162:163], v[24:25], v[176:177], v[168:169] op_sel_hi:[1,0,1]
	v_pk_fma_f32 v[164:165], v[26:27], v[176:177], v[170:171] op_sel_hi:[1,0,1]
	v_pk_fma_f32 v[166:167], v[28:29], v[176:177], v[172:173] op_sel_hi:[1,0,1]
	v_pk_fma_f32 v[168:169], v[30:31], v[176:177], v[174:175] op_sel_hi:[1,0,1]
	v_cndmask_b32_e64 v170, v0, v1, s[0:1]
	s_waitcnt vmcnt(10)
	v_cvt_scalef32_pk32_f32_fp6 v[0:31], v[138:143], 1.0
	v_readlane_b32 s12, v106, 11
	v_readlane_b32 s13, v109, 11
	v_pk_fma_f32 v[126:127], v[0:1], v[170:171], v[126:127] op_sel_hi:[1,0,1]
	v_mov_b32_e32 v1, s12
	v_mov_b32_e32 v0, s13
	v_pk_fma_f32 v[128:129], v[2:3], v[170:171], v[128:129] op_sel_hi:[1,0,1]
	v_pk_fma_f32 v[130:131], v[4:5], v[170:171], v[130:131] op_sel_hi:[1,0,1]
	v_pk_fma_f32 v[132:133], v[6:7], v[170:171], v[132:133] op_sel_hi:[1,0,1]
	v_pk_fma_f32 v[134:135], v[8:9], v[170:171], v[134:135] op_sel_hi:[1,0,1]
	v_pk_fma_f32 v[136:137], v[10:11], v[170:171], v[136:137] op_sel_hi:[1,0,1]
	v_pk_fma_f32 v[138:139], v[12:13], v[170:171], v[150:151] op_sel_hi:[1,0,1]
	v_pk_fma_f32 v[140:141], v[14:15], v[170:171], v[152:153] op_sel_hi:[1,0,1]
	v_pk_fma_f32 v[142:143], v[16:17], v[170:171], v[154:155] op_sel_hi:[1,0,1]
	v_pk_fma_f32 v[150:151], v[18:19], v[170:171], v[156:157] op_sel_hi:[1,0,1]
	v_pk_fma_f32 v[152:153], v[20:21], v[170:171], v[158:159] op_sel_hi:[1,0,1]
	v_pk_fma_f32 v[154:155], v[22:23], v[170:171], v[160:161] op_sel_hi:[1,0,1]
	v_pk_fma_f32 v[156:157], v[24:25], v[170:171], v[162:163] op_sel_hi:[1,0,1]
	v_pk_fma_f32 v[158:159], v[26:27], v[170:171], v[164:165] op_sel_hi:[1,0,1]
	v_pk_fma_f32 v[160:161], v[28:29], v[170:171], v[166:167] op_sel_hi:[1,0,1]
	v_pk_fma_f32 v[162:163], v[30:31], v[170:171], v[168:169] op_sel_hi:[1,0,1]
	v_cndmask_b32_e64 v164, v0, v1, s[0:1]
	s_waitcnt vmcnt(8)
	v_cvt_scalef32_pk32_f32_fp6 v[0:31], v[144:149], 1.0
	v_readlane_b32 s12, v106, 12
	v_readlane_b32 s13, v109, 12
	v_pk_fma_f32 v[126:127], v[0:1], v[164:165], v[126:127] op_sel_hi:[1,0,1]
	v_mov_b32_e32 v1, s12
	v_mov_b32_e32 v0, s13
	v_pk_fma_f32 v[128:129], v[2:3], v[164:165], v[128:129] op_sel_hi:[1,0,1]
	v_pk_fma_f32 v[130:131], v[4:5], v[164:165], v[130:131] op_sel_hi:[1,0,1]
	v_pk_fma_f32 v[132:133], v[6:7], v[164:165], v[132:133] op_sel_hi:[1,0,1]
	v_pk_fma_f32 v[134:135], v[8:9], v[164:165], v[134:135] op_sel_hi:[1,0,1]
	v_pk_fma_f32 v[136:137], v[10:11], v[164:165], v[136:137] op_sel_hi:[1,0,1]
	v_pk_fma_f32 v[138:139], v[12:13], v[164:165], v[138:139] op_sel_hi:[1,0,1]
	v_pk_fma_f32 v[140:141], v[14:15], v[164:165], v[140:141] op_sel_hi:[1,0,1]
	v_pk_fma_f32 v[142:143], v[16:17], v[164:165], v[142:143] op_sel_hi:[1,0,1]
	v_pk_fma_f32 v[144:145], v[18:19], v[164:165], v[150:151] op_sel_hi:[1,0,1]
	v_pk_fma_f32 v[146:147], v[20:21], v[164:165], v[152:153] op_sel_hi:[1,0,1]
	v_pk_fma_f32 v[148:149], v[22:23], v[164:165], v[154:155] op_sel_hi:[1,0,1]
	v_pk_fma_f32 v[150:151], v[24:25], v[164:165], v[156:157] op_sel_hi:[1,0,1]
	v_pk_fma_f32 v[152:153], v[26:27], v[164:165], v[158:159] op_sel_hi:[1,0,1]
	v_pk_fma_f32 v[154:155], v[28:29], v[164:165], v[160:161] op_sel_hi:[1,0,1]
	v_pk_fma_f32 v[156:157], v[30:31], v[164:165], v[162:163] op_sel_hi:[1,0,1]
	v_cndmask_b32_e64 v158, v0, v1, s[0:1]
	s_waitcnt vmcnt(6)
; DI void phase_peer_out(const Params& p, char* lds) {
;     ...
;       for (int k = 0; k < 8; ++k) {
;         const float c0 = __uint_as_float(__builtin_amdgcn_readlane(__float_as_uint(coefv[0]), kb * 8 + k)), c1 = __uint_as_float(__builtin_amdgcn_readlane(__float_as_uint(coefv[1]), kb * 8 + k));
;         const float cf = hb ? c1 : c0;
;         const f32x2 c2 = {cf, cf};
;         const v32f f = __builtin_amdgcn_cvt_scalef32_pk32_f32_fp6(qb[k], 1.0f);
; #pragma unroll
;         for (int i = 0; i < 16; ++i) o2[i] = f32x2{f[2 * i], f[2 * i + 1]} * c2 + o2[i];
	v_cvt_scalef32_pk32_f32_fp6 v[0:31], v[50:55], 1.0
	v_readlane_b32 s12, v106, 13
	v_readlane_b32 s13, v109, 13
	v_pk_fma_f32 v[50:51], v[0:1], v[158:159], v[126:127] op_sel_hi:[1,0,1]
	v_mov_b32_e32 v1, s12
	v_mov_b32_e32 v0, s13
	v_pk_fma_f32 v[52:53], v[2:3], v[158:159], v[128:129] op_sel_hi:[1,0,1]
	v_pk_fma_f32 v[54:55], v[4:5], v[158:159], v[130:131] op_sel_hi:[1,0,1]
	v_pk_fma_f32 v[126:127], v[6:7], v[158:159], v[132:133] op_sel_hi:[1,0,1]
	v_pk_fma_f32 v[128:129], v[8:9], v[158:159], v[134:135] op_sel_hi:[1,0,1]
	v_pk_fma_f32 v[130:131], v[10:11], v[158:159], v[136:137] op_sel_hi:[1,0,1]
	v_pk_fma_f32 v[132:133], v[12:13], v[158:159], v[138:139] op_sel_hi:[1,0,1]
	v_pk_fma_f32 v[134:135], v[14:15], v[158:159], v[140:141] op_sel_hi:[1,0,1]
	v_pk_fma_f32 v[136:137], v[16:17], v[158:159], v[142:143] op_sel_hi:[1,0,1]
	v_pk_fma_f32 v[138:139], v[18:19], v[158:159], v[144:145] op_sel_hi:[1,0,1]
	v_pk_fma_f32 v[140:141], v[20:21], v[158:159], v[146:147] op_sel_hi:[1,0,1]
	v_pk_fma_f32 v[142:143], v[22:23], v[158:159], v[148:149] op_sel_hi:[1,0,1]
	v_pk_fma_f32 v[144:145], v[24:25], v[158:159], v[150:151] op_sel_hi:[1,0,1]
	v_pk_fma_f32 v[146:147], v[26:27], v[158:159], v[152:153] op_sel_hi:[1,0,1]
	v_pk_fma_f32 v[148:149], v[28:29], v[158:159], v[154:155] op_sel_hi:[1,0,1]
	v_pk_fma_f32 v[150:151], v[30:31], v[158:159], v[156:157] op_sel_hi:[1,0,1]
	v_cndmask_b32_e64 v152, v0, v1, s[0:1]
	s_waitcnt vmcnt(4)
	v_cvt_scalef32_pk32_f32_fp6 v[0:31], v[44:49], 1.0
	v_readlane_b32 s12, v106, 14
	v_readlane_b32 s13, v109, 14
	v_pk_fma_f32 v[44:45], v[0:1], v[152:153], v[50:51] op_sel_hi:[1,0,1]
	v_mov_b32_e32 v1, s12
	v_mov_b32_e32 v0, s13
	v_pk_fma_f32 v[46:47], v[2:3], v[152:153], v[52:53] op_sel_hi:[1,0,1]
	v_pk_fma_f32 v[48:49], v[4:5], v[152:153], v[54:55] op_sel_hi:[1,0,1]
	v_pk_fma_f32 v[50:51], v[6:7], v[152:153], v[126:127] op_sel_hi:[1,0,1]
	v_pk_fma_f32 v[52:53], v[8:9], v[152:153], v[128:129] op_sel_hi:[1,0,1]
	v_pk_fma_f32 v[54:55], v[10:11], v[152:153], v[130:131] op_sel_hi:[1,0,1]
	v_pk_fma_f32 v[126:127], v[12:13], v[152:153], v[132:133] op_sel_hi:[1,0,1]
	v_pk_fma_f32 v[128:129], v[14:15], v[152:153], v[134:135] op_sel_hi:[1,0,1]
	v_pk_fma_f32 v[130:131], v[16:17], v[152:153], v[136:137] op_sel_hi:[1,0,1]
	v_pk_fma_f32 v[132:133], v[18:19], v[152:153], v[138:139] op_sel_hi:[1,0,1]
	v_pk_fma_f32 v[134:135], v[20:21], v[152:153], v[140:141] op_sel_hi:[1,0,1]
	v_pk_fma_f32 v[136:137], v[22:23], v[152:153], v[142:143] op_sel_hi:[1,0,1]
	v_pk_fma_f32 v[138:139], v[24:25], v[152:153], v[144:145] op_sel_hi:[1,0,1]
	v_pk_fma_f32 v[140:141], v[26:27], v[152:153], v[146:147] op_sel_hi:[1,0,1]
	v_pk_fma_f32 v[142:143], v[28:29], v[152:153], v[148:149] op_sel_hi:[1,0,1]
	v_pk_fma_f32 v[144:145], v[30:31], v[152:153], v[150:151] op_sel_hi:[1,0,1]
	v_cndmask_b32_e64 v146, v0, v1, s[0:1]
	s_waitcnt vmcnt(1)
	v_cvt_scalef32_pk32_f32_fp6 v[0:31], v[38:43], 1.0
	v_readlane_b32 s12, v106, 15
	v_readlane_b32 s13, v109, 15
	v_pk_fma_f32 v[38:39], v[0:1], v[146:147], v[44:45] op_sel_hi:[1,0,1]
	v_mov_b32_e32 v1, s12
	v_mov_b32_e32 v0, s13
	v_readlane_b32 s12, v108, 16
	v_readlane_b32 s13, v107, 16
	v_pk_fma_f32 v[40:41], v[2:3], v[146:147], v[46:47] op_sel_hi:[1,0,1]
	v_pk_fma_f32 v[42:43], v[4:5], v[146:147], v[48:49] op_sel_hi:[1,0,1]
	v_pk_fma_f32 v[44:45], v[6:7], v[146:147], v[50:51] op_sel_hi:[1,0,1]
	v_pk_fma_f32 v[46:47], v[8:9], v[146:147], v[52:53] op_sel_hi:[1,0,1]
	v_pk_fma_f32 v[48:49], v[10:11], v[146:147], v[54:55] op_sel_hi:[1,0,1]
	v_pk_fma_f32 v[50:51], v[12:13], v[146:147], v[126:127] op_sel_hi:[1,0,1]
	v_pk_fma_f32 v[52:53], v[14:15], v[146:147], v[128:129] op_sel_hi:[1,0,1]
	v_pk_fma_f32 v[54:55], v[16:17], v[146:147], v[130:131] op_sel_hi:[1,0,1]
	v_pk_fma_f32 v[132:133], v[18:19], v[146:147], v[132:133] op_sel_hi:[1,0,1]
	v_pk_fma_f32 v[134:135], v[20:21], v[146:147], v[134:135] op_sel_hi:[1,0,1]
	v_pk_fma_f32 v[136:137], v[22:23], v[146:147], v[136:137] op_sel_hi:[1,0,1]
	v_pk_fma_f32 v[138:139], v[24:25], v[146:147], v[138:139] op_sel_hi:[1,0,1]
	v_pk_fma_f32 v[140:141], v[26:27], v[146:147], v[140:141] op_sel_hi:[1,0,1]
	v_pk_fma_f32 v[142:143], v[28:29], v[146:147], v[142:143] op_sel_hi:[1,0,1]
	v_pk_fma_f32 v[144:145], v[30:31], v[146:147], v[144:145] op_sel_hi:[1,0,1]
	v_cndmask_b32_e64 v146, v0, v1, s[0:1]
	v_mov_b32_e32 v0, s13
	v_mov_b32_e32 v1, s12
	v_cndmask_b32_e64 v0, v0, v1, s[0:1]
	v_mad_i64_i32 v[130:131], s[12:13], v0, s23, v[64:65]
	s_waitcnt vmcnt(0)
; DI void phase_peer_out(const Params& p, char* lds) {
;     ...
;     for (int kb = 0; kb < 8; ++kb) {
;       v6u qb[8];
; #pragma unroll
;       for (int k = 0; k < 8; ++k) {
;         const int e0 = __builtin_amdgcn_readlane(el[0], kb * 8 + k), e1 = __builtin_amdgcn_readlane(el[1], kb * 8 + k);
;         qb[k] = load6(V6 + (size_t)(hb ? e1 : e0) * 768);
;       }
; #pragma unroll
;       for (int k = 0; k < 8; ++k) {
;         const float c0 = __uint_as_float(__builtin_amdgcn_readlane(__float_as_uint(coefv[0]), kb * 8 + k)), c1 = __uint_as_float(__builtin_amdgcn_readlane(__float_as_uint(coefv[1]), kb * 8 + k));
;         const float cf = hb ? c1 : c0;
;         const f32x2 c2 = {cf, cf};
;         const v32f f = __builtin_amdgcn_cvt_scalef32_pk32_f32_fp6(qb[k], 1.0f);
; #pragma unroll
;         for (int i = 0; i < 16; ++i) o2[i] = f32x2{f[2 * i], f[2 * i + 1]} * c2 + o2[i];
	v_cvt_scalef32_pk32_f32_fp6 v[0:31], v[32:37], 1.0
	v_readlane_b32 s12, v108, 17
	v_readlane_b32 s13, v107, 17
	v_pk_fma_f32 v[150:151], v[0:1], v[146:147], v[38:39] op_sel_hi:[1,0,1]
	v_mov_b32_e32 v1, s12
	v_mov_b32_e32 v0, s13
	v_cndmask_b32_e64 v0, v0, v1, s[0:1]
	v_mad_i64_i32 v[0:1], s[12:13], v0, s23, v[64:65]
	v_readlane_b32 s12, v108, 18
	v_readlane_b32 s13, v107, 18
	global_load_dwordx4 v[126:129], v[130:131], off
	v_pk_fma_f32 v[168:169], v[18:19], v[146:147], v[132:133] op_sel_hi:[1,0,1]
	global_load_dwordx2 v[130:131], v[130:131], off offset:16
	v_pk_fma_f32 v[170:171], v[20:21], v[146:147], v[134:135] op_sel_hi:[1,0,1]
	v_pk_fma_f32 v[172:173], v[22:23], v[146:147], v[136:137] op_sel_hi:[1,0,1]
	global_load_dwordx2 v[136:137], v[0:1], off offset:16
	global_load_dwordx4 v[132:135], v[0:1], off
	v_mov_b32_e32 v0, s13
	v_mov_b32_e32 v1, s12
	v_cndmask_b32_e64 v0, v0, v1, s[0:1]
	v_mad_i64_i32 v[0:1], s[12:13], v0, s23, v[64:65]
	v_readlane_b32 s12, v108, 19
	v_readlane_b32 s13, v107, 19
	v_pk_fma_f32 v[152:153], v[2:3], v[146:147], v[40:41] op_sel_hi:[1,0,1]
	v_mov_b32_e32 v3, s12
	v_mov_b32_e32 v2, s13
	v_cndmask_b32_e64 v2, v2, v3, s[0:1]
	v_mad_i64_i32 v[2:3], s[12:13], v2, s23, v[64:65]
	v_readlane_b32 s12, v108, 20
	v_readlane_b32 s13, v107, 20
	v_pk_fma_f32 v[154:155], v[4:5], v[146:147], v[42:43] op_sel_hi:[1,0,1]
	v_pk_fma_f32 v[156:157], v[6:7], v[146:147], v[44:45] op_sel_hi:[1,0,1]
	v_pk_fma_f32 v[158:159], v[8:9], v[146:147], v[46:47] op_sel_hi:[1,0,1]
	v_pk_fma_f32 v[160:161], v[10:11], v[146:147], v[48:49] op_sel_hi:[1,0,1]
	v_pk_fma_f32 v[162:163], v[12:13], v[146:147], v[50:51] op_sel_hi:[1,0,1]
	v_pk_fma_f32 v[164:165], v[14:15], v[146:147], v[52:53] op_sel_hi:[1,0,1]
	v_pk_fma_f32 v[166:167], v[16:17], v[146:147], v[54:55] op_sel_hi:[1,0,1]
	v_pk_fma_f32 v[174:175], v[24:25], v[146:147], v[138:139] op_sel_hi:[1,0,1]
	v_pk_fma_f32 v[176:177], v[26:27], v[146:147], v[140:141] op_sel_hi:[1,0,1]
	v_pk_fma_f32 v[178:179], v[28:29], v[146:147], v[142:143] op_sel_hi:[1,0,1]
	v_pk_fma_f32 v[180:181], v[30:31], v[146:147], v[144:145] op_sel_hi:[1,0,1]
	global_load_dwordx4 v[138:141], v[0:1], off
	global_load_dwordx2 v[142:143], v[0:1], off offset:16
	global_load_dwordx4 v[144:147], v[2:3], off
	v_mov_b32_e32 v0, s13
	v_mov_b32_e32 v1, s12
	v_cndmask_b32_e64 v0, v0, v1, s[0:1]
	v_mad_i64_i32 v[0:1], s[12:13], v0, s23, v[64:65]
	v_readlane_b32 s12, v108, 21
	v_readlane_b32 s13, v107, 21
	global_load_dwordx2 v[148:149], v[2:3], off offset:16
	global_load_dwordx4 v[50:53], v[0:1], off
	v_mov_b32_e32 v2, s13
	v_mov_b32_e32 v3, s12
	v_cndmask_b32_e64 v2, v2, v3, s[0:1]
	v_mad_i64_i32 v[2:3], s[12:13], v2, s23, v[64:65]
	v_readlane_b32 s12, v108, 22
	v_readlane_b32 s13, v107, 22
	global_load_dwordx2 v[54:55], v[0:1], off offset:16
	global_load_dwordx4 v[44:47], v[2:3], off
	v_mov_b32_e32 v0, s13
	v_mov_b32_e32 v1, s12
	v_cndmask_b32_e64 v0, v0, v1, s[0:1]
	v_mad_i64_i32 v[0:1], s[12:13], v0, s23, v[64:65]
	v_readlane_b32 s12, v108, 23
	v_readlane_b32 s13, v107, 23
	global_load_dwordx2 v[48:49], v[2:3], off offset:16
	global_load_dwordx4 v[38:41], v[0:1], off
	v_mov_b32_e32 v2, s13
	v_mov_b32_e32 v3, s12
	v_cndmask_b32_e64 v2, v2, v3, s[0:1]
	v_mad_i64_i32 v[2:3], s[12:13], v2, s23, v[64:65]
	global_load_dwordx2 v[36:37], v[2:3], off offset:16
	global_load_dwordx2 v[42:43], v[0:1], off offset:16
	global_load_dwordx4 v[32:35], v[2:3], off
	v_readlane_b32 s12, v106, 16
	v_readlane_b32 s13, v109, 16
	s_nop 0
	v_mov_b32_e32 v1, s12
	v_mov_b32_e32 v0, s13
	v_cndmask_b32_e64 v182, v0, v1, s[0:1]
	v_readlane_b32 s12, v106, 17
	v_readlane_b32 s13, v109, 17
	s_waitcnt vmcnt(14)
	v_cvt_scalef32_pk32_f32_fp6 v[0:31], v[126:131], 1.0
	v_pk_fma_f32 v[126:127], v[0:1], v[182:183], v[150:151] op_sel_hi:[1,0,1]
	v_mov_b32_e32 v0, s13
	v_mov_b32_e32 v1, s12
	v_pk_fma_f32 v[128:129], v[2:3], v[182:183], v[152:153] op_sel_hi:[1,0,1]
	v_pk_fma_f32 v[130:131], v[4:5], v[182:183], v[154:155] op_sel_hi:[1,0,1]
	v_pk_fma_f32 v[150:151], v[6:7], v[182:183], v[156:157] op_sel_hi:[1,0,1]
	v_pk_fma_f32 v[152:153], v[8:9], v[182:183], v[158:159] op_sel_hi:[1,0,1]
	v_pk_fma_f32 v[154:155], v[10:11], v[182:183], v[160:161] op_sel_hi:[1,0,1]
	v_pk_fma_f32 v[156:157], v[12:13], v[182:183], v[162:163] op_sel_hi:[1,0,1]
	v_pk_fma_f32 v[158:159], v[14:15], v[182:183], v[164:165] op_sel_hi:[1,0,1]
	v_pk_fma_f32 v[160:161], v[16:17], v[182:183], v[166:167] op_sel_hi:[1,0,1]
	v_pk_fma_f32 v[162:163], v[18:19], v[182:183], v[168:169] op_sel_hi:[1,0,1]
	v_pk_fma_f32 v[164:165], v[20:21], v[182:183], v[170:171] op_sel_hi:[1,0,1]
	v_pk_fma_f32 v[166:167], v[22:23], v[182:183], v[172:173] op_sel_hi:[1,0,1]
	v_pk_fma_f32 v[168:169], v[24:25], v[182:183], v[174:175] op_sel_hi:[1,0,1]
	v_pk_fma_f32 v[170:171], v[26:27], v[182:183], v[176:177] op_sel_hi:[1,0,1]
	v_pk_fma_f32 v[172:173], v[28:29], v[182:183], v[178:179] op_sel_hi:[1,0,1]
	v_pk_fma_f32 v[174:175], v[30:31], v[182:183], v[180:181] op_sel_hi:[1,0,1]
	v_cndmask_b32_e64 v176, v0, v1, s[0:1]
	s_waitcnt vmcnt(12)
; DI void phase_peer_out(const Params& p, char* lds) {
;     ...
;       for (int k = 0; k < 8; ++k) {
;         const float c0 = __uint_as_float(__builtin_amdgcn_readlane(__float_as_uint(coefv[0]), kb * 8 + k)), c1 = __uint_as_float(__builtin_amdgcn_readlane(__float_as_uint(coefv[1]), kb * 8 + k));
;         const float cf = hb ? c1 : c0;
;         const f32x2 c2 = {cf, cf};
;         const v32f f = __builtin_amdgcn_cvt_scalef32_pk32_f32_fp6(qb[k], 1.0f);
; #pragma unroll
;         for (int i = 0; i < 16; ++i) o2[i] = f32x2{f[2 * i], f[2 * i + 1]} * c2 + o2[i];
	v_cvt_scalef32_pk32_f32_fp6 v[0:31], v[132:137], 1.0
	v_readlane_b32 s12, v106, 18
	v_readlane_b32 s13, v109, 18
	v_pk_fma_f32 v[126:127], v[0:1], v[176:177], v[126:127] op_sel_hi:[1,0,1]
	v_mov_b32_e32 v1, s12
	v_mov_b32_e32 v0, s13
	v_pk_fma_f32 v[128:129], v[2:3], v[176:177], v[128:129] op_sel_hi:[1,0,1]
	v_pk_fma_f32 v[130:131], v[4:5], v[176:177], v[130:131] op_sel_hi:[1,0,1]
	v_pk_fma_f32 v[132:133], v[6:7], v[176:177], v[150:151] op_sel_hi:[1,0,1]
	v_pk_fma_f32 v[134:135], v[8:9], v[176:177], v[152:153] op_sel_hi:[1,0,1]
	v_pk_fma_f32 v[136:137], v[10:11], v[176:177], v[154:155] op_sel_hi:[1,0,1]
	v_pk_fma_f32 v[150:151], v[12:13], v[176:177], v[156:157] op_sel_hi:[1,0,1]
	v_pk_fma_f32 v[152:153], v[14:15], v[176:177], v[158:159] op_sel_hi:[1,0,1]
	v_pk_fma_f32 v[154:155], v[16:17], v[176:177], v[160:161] op_sel_hi:[1,0,1]
	v_pk_fma_f32 v[156:157], v[18:19], v[176:177], v[162:163] op_sel_hi:[1,0,1]
	v_pk_fma_f32 v[158:159], v[20:21], v[176:177], v[164:165] op_sel_hi:[1,0,1]
	v_pk_fma_f32 v[160:161], v[22:23], v[176:177], v[166:167] op_sel_hi:[1,0,1]
	v_pk_fma_f32 v[162:163], v[24:25], v[176:177], v[168:169] op_sel_hi:[1,0,1]
	v_pk_fma_f32 v[164:165], v[26:27], v[176:177], v[170:171] op_sel_hi:[1,0,1]
	v_pk_fma_f32 v[166:167], v[28:29], v[176:177], v[172:173] op_sel_hi:[1,0,1]
	v_pk_fma_f32 v[168:169], v[30:31], v[176:177], v[174:175] op_sel_hi:[1,0,1]
	v_cndmask_b32_e64 v170, v0, v1, s[0:1]
	s_waitcnt vmcnt(10)
	v_cvt_scalef32_pk32_f32_fp6 v[0:31], v[138:143], 1.0
	v_readlane_b32 s12, v106, 19
	v_readlane_b32 s13, v109, 19
	v_pk_fma_f32 v[126:127], v[0:1], v[170:171], v[126:127] op_sel_hi:[1,0,1]
	v_mov_b32_e32 v1, s12
	v_mov_b32_e32 v0, s13
	v_pk_fma_f32 v[128:129], v[2:3], v[170:171], v[128:129] op_sel_hi:[1,0,1]
	v_pk_fma_f32 v[130:131], v[4:5], v[170:171], v[130:131] op_sel_hi:[1,0,1]
	v_pk_fma_f32 v[132:133], v[6:7], v[170:171], v[132:133] op_sel_hi:[1,0,1]
	v_pk_fma_f32 v[134:135], v[8:9], v[170:171], v[134:135] op_sel_hi:[1,0,1]
	v_pk_fma_f32 v[136:137], v[10:11], v[170:171], v[136:137] op_sel_hi:[1,0,1]
	v_pk_fma_f32 v[138:139], v[12:13], v[170:171], v[150:151] op_sel_hi:[1,0,1]
	v_pk_fma_f32 v[140:141], v[14:15], v[170:171], v[152:153] op_sel_hi:[1,0,1]
	v_pk_fma_f32 v[142:143], v[16:17], v[170:171], v[154:155] op_sel_hi:[1,0,1]
	v_pk_fma_f32 v[150:151], v[18:19], v[170:171], v[156:157] op_sel_hi:[1,0,1]
	v_pk_fma_f32 v[152:153], v[20:21], v[170:171], v[158:159] op_sel_hi:[1,0,1]
	v_pk_fma_f32 v[154:155], v[22:23], v[170:171], v[160:161] op_sel_hi:[1,0,1]
	v_pk_fma_f32 v[156:157], v[24:25], v[170:171], v[162:163] op_sel_hi:[1,0,1]
	v_pk_fma_f32 v[158:159], v[26:27], v[170:171], v[164:165] op_sel_hi:[1,0,1]
	v_pk_fma_f32 v[160:161], v[28:29], v[170:171], v[166:167] op_sel_hi:[1,0,1]
	v_pk_fma_f32 v[162:163], v[30:31], v[170:171], v[168:169] op_sel_hi:[1,0,1]
	v_cndmask_b32_e64 v164, v0, v1, s[0:1]
	s_waitcnt vmcnt(8)
	v_cvt_scalef32_pk32_f32_fp6 v[0:31], v[144:149], 1.0
	v_readlane_b32 s12, v106, 20
	v_readlane_b32 s13, v109, 20
	v_pk_fma_f32 v[126:127], v[0:1], v[164:165], v[126:127] op_sel_hi:[1,0,1]
	v_mov_b32_e32 v1, s12
	v_mov_b32_e32 v0, s13
	v_pk_fma_f32 v[128:129], v[2:3], v[164:165], v[128:129] op_sel_hi:[1,0,1]
	v_pk_fma_f32 v[130:131], v[4:5], v[164:165], v[130:131] op_sel_hi:[1,0,1]
	v_pk_fma_f32 v[132:133], v[6:7], v[164:165], v[132:133] op_sel_hi:[1,0,1]
	v_pk_fma_f32 v[134:135], v[8:9], v[164:165], v[134:135] op_sel_hi:[1,0,1]
	v_pk_fma_f32 v[136:137], v[10:11], v[164:165], v[136:137] op_sel_hi:[1,0,1]
	v_pk_fma_f32 v[138:139], v[12:13], v[164:165], v[138:139] op_sel_hi:[1,0,1]
	v_pk_fma_f32 v[140:141], v[14:15], v[164:165], v[140:141] op_sel_hi:[1,0,1]
	v_pk_fma_f32 v[142:143], v[16:17], v[164:165], v[142:143] op_sel_hi:[1,0,1]
	v_pk_fma_f32 v[144:145], v[18:19], v[164:165], v[150:151] op_sel_hi:[1,0,1]
	v_pk_fma_f32 v[146:147], v[20:21], v[164:165], v[152:153] op_sel_hi:[1,0,1]
	v_pk_fma_f32 v[148:149], v[22:23], v[164:165], v[154:155] op_sel_hi:[1,0,1]
	v_pk_fma_f32 v[150:151], v[24:25], v[164:165], v[156:157] op_sel_hi:[1,0,1]
	v_pk_fma_f32 v[152:153], v[26:27], v[164:165], v[158:159] op_sel_hi:[1,0,1]
	v_pk_fma_f32 v[154:155], v[28:29], v[164:165], v[160:161] op_sel_hi:[1,0,1]
	v_pk_fma_f32 v[156:157], v[30:31], v[164:165], v[162:163] op_sel_hi:[1,0,1]
	v_cndmask_b32_e64 v158, v0, v1, s[0:1]
	s_waitcnt vmcnt(6)
	v_cvt_scalef32_pk32_f32_fp6 v[0:31], v[50:55], 1.0
	v_readlane_b32 s12, v106, 21
	v_readlane_b32 s13, v109, 21
	v_pk_fma_f32 v[50:51], v[0:1], v[158:159], v[126:127] op_sel_hi:[1,0,1]
	v_mov_b32_e32 v1, s12
	v_mov_b32_e32 v0, s13
	v_pk_fma_f32 v[52:53], v[2:3], v[158:159], v[128:129] op_sel_hi:[1,0,1]
	v_pk_fma_f32 v[54:55], v[4:5], v[158:159], v[130:131] op_sel_hi:[1,0,1]
	v_pk_fma_f32 v[126:127], v[6:7], v[158:159], v[132:133] op_sel_hi:[1,0,1]
	v_pk_fma_f32 v[128:129], v[8:9], v[158:159], v[134:135] op_sel_hi:[1,0,1]
	v_pk_fma_f32 v[130:131], v[10:11], v[158:159], v[136:137] op_sel_hi:[1,0,1]
	v_pk_fma_f32 v[132:133], v[12:13], v[158:159], v[138:139] op_sel_hi:[1,0,1]
	v_pk_fma_f32 v[134:135], v[14:15], v[158:159], v[140:141] op_sel_hi:[1,0,1]
	v_pk_fma_f32 v[136:137], v[16:17], v[158:159], v[142:143] op_sel_hi:[1,0,1]
	v_pk_fma_f32 v[138:139], v[18:19], v[158:159], v[144:145] op_sel_hi:[1,0,1]
	v_pk_fma_f32 v[140:141], v[20:21], v[158:159], v[146:147] op_sel_hi:[1,0,1]
	v_pk_fma_f32 v[142:143], v[22:23], v[158:159], v[148:149] op_sel_hi:[1,0,1]
	v_pk_fma_f32 v[144:145], v[24:25], v[158:159], v[150:151] op_sel_hi:[1,0,1]
	v_pk_fma_f32 v[146:147], v[26:27], v[158:159], v[152:153] op_sel_hi:[1,0,1]
	v_pk_fma_f32 v[148:149], v[28:29], v[158:159], v[154:155] op_sel_hi:[1,0,1]
	v_pk_fma_f32 v[150:151], v[30:31], v[158:159], v[156:157] op_sel_hi:[1,0,1]
	v_cndmask_b32_e64 v152, v0, v1, s[0:1]
	s_waitcnt vmcnt(4)
; DI void phase_peer_out(const Params& p, char* lds) {
;     ...
;     for (int kb = 0; kb < 8; ++kb) {
;       v6u qb[8];
; #pragma unroll
;       for (int k = 0; k < 8; ++k) {
;         const int e0 = __builtin_amdgcn_readlane(el[0], kb * 8 + k), e1 = __builtin_amdgcn_readlane(el[1], kb * 8 + k);
;         qb[k] = load6(V6 + (size_t)(hb ? e1 : e0) * 768);
;       }
; #pragma unroll
;       for (int k = 0; k < 8; ++k) {
;         const float c0 = __uint_as_float(__builtin_amdgcn_readlane(__float_as_uint(coefv[0]), kb * 8 + k)), c1 = __uint_as_float(__builtin_amdgcn_readlane(__float_as_uint(coefv[1]), kb * 8 + k));
;         const float cf = hb ? c1 : c0;
;         const f32x2 c2 = {cf, cf};
;         const v32f f = __builtin_amdgcn_cvt_scalef32_pk32_f32_fp6(qb[k], 1.0f);
; #pragma unroll
;         for (int i = 0; i < 16; ++i) o2[i] = f32x2{f[2 * i], f[2 * i + 1]} * c2 + o2[i];
	v_cvt_scalef32_pk32_f32_fp6 v[0:31], v[44:49], 1.0
	v_readlane_b32 s12, v106, 22
	v_readlane_b32 s13, v109, 22
	v_pk_fma_f32 v[44:45], v[0:1], v[152:153], v[50:51] op_sel_hi:[1,0,1]
	v_mov_b32_e32 v1, s12
	v_mov_b32_e32 v0, s13
	v_pk_fma_f32 v[46:47], v[2:3], v[152:153], v[52:53] op_sel_hi:[1,0,1]
	v_pk_fma_f32 v[48:49], v[4:5], v[152:153], v[54:55] op_sel_hi:[1,0,1]
	v_pk_fma_f32 v[50:51], v[6:7], v[152:153], v[126:127] op_sel_hi:[1,0,1]
	v_pk_fma_f32 v[52:53], v[8:9], v[152:153], v[128:129] op_sel_hi:[1,0,1]
	v_pk_fma_f32 v[54:55], v[10:11], v[152:153], v[130:131] op_sel_hi:[1,0,1]
	v_pk_fma_f32 v[126:127], v[12:13], v[152:153], v[132:133] op_sel_hi:[1,0,1]
	v_pk_fma_f32 v[128:129], v[14:15], v[152:153], v[134:135] op_sel_hi:[1,0,1]
	v_pk_fma_f32 v[130:131], v[16:17], v[152:153], v[136:137] op_sel_hi:[1,0,1]
	v_pk_fma_f32 v[132:133], v[18:19], v[152:153], v[138:139] op_sel_hi:[1,0,1]
	v_pk_fma_f32 v[134:135], v[20:21], v[152:153], v[140:141] op_sel_hi:[1,0,1]
	v_pk_fma_f32 v[136:137], v[22:23], v[152:153], v[142:143] op_sel_hi:[1,0,1]
	v_pk_fma_f32 v[138:139], v[24:25], v[152:153], v[144:145] op_sel_hi:[1,0,1]
	v_pk_fma_f32 v[140:141], v[26:27], v[152:153], v[146:147] op_sel_hi:[1,0,1]
	v_pk_fma_f32 v[142:143], v[28:29], v[152:153], v[148:149] op_sel_hi:[1,0,1]
	v_pk_fma_f32 v[144:145], v[30:31], v[152:153], v[150:151] op_sel_hi:[1,0,1]
	v_cndmask_b32_e64 v146, v0, v1, s[0:1]
	s_waitcnt vmcnt(1)
	v_cvt_scalef32_pk32_f32_fp6 v[0:31], v[38:43], 1.0
	v_readlane_b32 s12, v106, 23
	v_readlane_b32 s13, v109, 23
	v_pk_fma_f32 v[38:39], v[0:1], v[146:147], v[44:45] op_sel_hi:[1,0,1]
	v_mov_b32_e32 v1, s12
	v_mov_b32_e32 v0, s13
	v_readlane_b32 s12, v108, 24
	v_readlane_b32 s13, v107, 24
	v_pk_fma_f32 v[40:41], v[2:3], v[146:147], v[46:47] op_sel_hi:[1,0,1]
	v_pk_fma_f32 v[42:43], v[4:5], v[146:147], v[48:49] op_sel_hi:[1,0,1]
	v_pk_fma_f32 v[44:45], v[6:7], v[146:147], v[50:51] op_sel_hi:[1,0,1]
	v_pk_fma_f32 v[46:47], v[8:9], v[146:147], v[52:53] op_sel_hi:[1,0,1]
	v_pk_fma_f32 v[48:49], v[10:11], v[146:147], v[54:55] op_sel_hi:[1,0,1]
	v_pk_fma_f32 v[50:51], v[12:13], v[146:147], v[126:127] op_sel_hi:[1,0,1]
	v_pk_fma_f32 v[52:53], v[14:15], v[146:147], v[128:129] op_sel_hi:[1,0,1]
	v_pk_fma_f32 v[54:55], v[16:17], v[146:147], v[130:131] op_sel_hi:[1,0,1]
	v_pk_fma_f32 v[132:133], v[18:19], v[146:147], v[132:133] op_sel_hi:[1,0,1]
	v_pk_fma_f32 v[134:135], v[20:21], v[146:147], v[134:135] op_sel_hi:[1,0,1]
	v_pk_fma_f32 v[136:137], v[22:23], v[146:147], v[136:137] op_sel_hi:[1,0,1]
	v_pk_fma_f32 v[138:139], v[24:25], v[146:147], v[138:139] op_sel_hi:[1,0,1]
	v_pk_fma_f32 v[140:141], v[26:27], v[146:147], v[140:141] op_sel_hi:[1,0,1]
	v_pk_fma_f32 v[142:143], v[28:29], v[146:147], v[142:143] op_sel_hi:[1,0,1]
	v_pk_fma_f32 v[144:145], v[30:31], v[146:147], v[144:145] op_sel_hi:[1,0,1]
	v_cndmask_b32_e64 v146, v0, v1, s[0:1]
	v_mov_b32_e32 v0, s13
	v_mov_b32_e32 v1, s12
	v_cndmask_b32_e64 v0, v0, v1, s[0:1]
	v_mad_i64_i32 v[130:131], s[12:13], v0, s23, v[64:65]
	s_waitcnt vmcnt(0)
	v_cvt_scalef32_pk32_f32_fp6 v[0:31], v[32:37], 1.0
	v_readlane_b32 s12, v108, 25
	v_readlane_b32 s13, v107, 25
	v_pk_fma_f32 v[150:151], v[0:1], v[146:147], v[38:39] op_sel_hi:[1,0,1]
	v_mov_b32_e32 v1, s12
	v_mov_b32_e32 v0, s13
	v_cndmask_b32_e64 v0, v0, v1, s[0:1]
	v_mad_i64_i32 v[0:1], s[12:13], v0, s23, v[64:65]
	v_readlane_b32 s12, v108, 26
	v_readlane_b32 s13, v107, 26
	global_load_dwordx4 v[126:129], v[130:131], off
	v_pk_fma_f32 v[168:169], v[18:19], v[146:147], v[132:133] op_sel_hi:[1,0,1]
	global_load_dwordx2 v[130:131], v[130:131], off offset:16
	v_pk_fma_f32 v[170:171], v[20:21], v[146:147], v[134:135] op_sel_hi:[1,0,1]
	v_pk_fma_f32 v[172:173], v[22:23], v[146:147], v[136:137] op_sel_hi:[1,0,1]
	global_load_dwordx2 v[136:137], v[0:1], off offset:16
	global_load_dwordx4 v[132:135], v[0:1], off
	v_mov_b32_e32 v0, s13
	v_mov_b32_e32 v1, s12
	v_cndmask_b32_e64 v0, v0, v1, s[0:1]
	v_mad_i64_i32 v[0:1], s[12:13], v0, s23, v[64:65]
	v_readlane_b32 s12, v108, 27
	v_readlane_b32 s13, v107, 27
	v_pk_fma_f32 v[152:153], v[2:3], v[146:147], v[40:41] op_sel_hi:[1,0,1]
	v_mov_b32_e32 v3, s12
	v_mov_b32_e32 v2, s13
	v_cndmask_b32_e64 v2, v2, v3, s[0:1]
	v_mad_i64_i32 v[2:3], s[12:13], v2, s23, v[64:65]
	v_readlane_b32 s12, v108, 28
	v_readlane_b32 s13, v107, 28
	v_pk_fma_f32 v[154:155], v[4:5], v[146:147], v[42:43] op_sel_hi:[1,0,1]
	v_pk_fma_f32 v[156:157], v[6:7], v[146:147], v[44:45] op_sel_hi:[1,0,1]
	v_pk_fma_f32 v[158:159], v[8:9], v[146:147], v[46:47] op_sel_hi:[1,0,1]
	v_pk_fma_f32 v[160:161], v[10:11], v[146:147], v[48:49] op_sel_hi:[1,0,1]
	v_pk_fma_f32 v[162:163], v[12:13], v[146:147], v[50:51] op_sel_hi:[1,0,1]
	v_pk_fma_f32 v[164:165], v[14:15], v[146:147], v[52:53] op_sel_hi:[1,0,1]
	v_pk_fma_f32 v[166:167], v[16:17], v[146:147], v[54:55] op_sel_hi:[1,0,1]
	v_pk_fma_f32 v[174:175], v[24:25], v[146:147], v[138:139] op_sel_hi:[1,0,1]
	v_pk_fma_f32 v[176:177], v[26:27], v[146:147], v[140:141] op_sel_hi:[1,0,1]
	v_pk_fma_f32 v[178:179], v[28:29], v[146:147], v[142:143] op_sel_hi:[1,0,1]
	v_pk_fma_f32 v[180:181], v[30:31], v[146:147], v[144:145] op_sel_hi:[1,0,1]
	global_load_dwordx4 v[138:141], v[0:1], off
	global_load_dwordx2 v[142:143], v[0:1], off offset:16
	global_load_dwordx4 v[144:147], v[2:3], off
	v_mov_b32_e32 v0, s13
	v_mov_b32_e32 v1, s12
	v_cndmask_b32_e64 v0, v0, v1, s[0:1]
	v_mad_i64_i32 v[0:1], s[12:13], v0, s23, v[64:65]
	v_readlane_b32 s12, v108, 29
	v_readlane_b32 s13, v107, 29
	global_load_dwordx2 v[148:149], v[2:3], off offset:16
	global_load_dwordx4 v[50:53], v[0:1], off
	v_mov_b32_e32 v2, s13
	v_mov_b32_e32 v3, s12
	v_cndmask_b32_e64 v2, v2, v3, s[0:1]
	v_mad_i64_i32 v[2:3], s[12:13], v2, s23, v[64:65]
	v_readlane_b32 s12, v108, 30
	v_readlane_b32 s13, v107, 30
	global_load_dwordx2 v[54:55], v[0:1], off offset:16
	global_load_dwordx4 v[44:47], v[2:3], off
	v_mov_b32_e32 v0, s13
	v_mov_b32_e32 v1, s12
	v_cndmask_b32_e64 v0, v0, v1, s[0:1]
	v_mad_i64_i32 v[0:1], s[12:13], v0, s23, v[64:65]
	v_readlane_b32 s12, v108, 31
	v_readlane_b32 s13, v107, 31
	global_load_dwordx2 v[48:49], v[2:3], off offset:16
	global_load_dwordx4 v[38:41], v[0:1], off
	v_mov_b32_e32 v2, s13
	v_mov_b32_e32 v3, s12
	v_cndmask_b32_e64 v2, v2, v3, s[0:1]
	v_mad_i64_i32 v[2:3], s[12:13], v2, s23, v[64:65]
	global_load_dwordx2 v[36:37], v[2:3], off offset:16
	global_load_dwordx2 v[42:43], v[0:1], off offset:16
	global_load_dwordx4 v[32:35], v[2:3], off
	v_readlane_b32 s12, v106, 24
	v_readlane_b32 s13, v109, 24
	s_nop 0
	v_mov_b32_e32 v1, s12
	v_mov_b32_e32 v0, s13
	v_cndmask_b32_e64 v182, v0, v1, s[0:1]
	v_readlane_b32 s12, v106, 25
	v_readlane_b32 s13, v109, 25
	s_waitcnt vmcnt(14)
; DI void phase_peer_out(const Params& p, char* lds) {
;     ...
;       for (int k = 0; k < 8; ++k) {
;         const float c0 = __uint_as_float(__builtin_amdgcn_readlane(__float_as_uint(coefv[0]), kb * 8 + k)), c1 = __uint_as_float(__builtin_amdgcn_readlane(__float_as_uint(coefv[1]), kb * 8 + k));
;         const float cf = hb ? c1 : c0;
;         const f32x2 c2 = {cf, cf};
;         const v32f f = __builtin_amdgcn_cvt_scalef32_pk32_f32_fp6(qb[k], 1.0f);
; #pragma unroll
;         for (int i = 0; i < 16; ++i) o2[i] = f32x2{f[2 * i], f[2 * i + 1]} * c2 + o2[i];
	v_cvt_scalef32_pk32_f32_fp6 v[0:31], v[126:131], 1.0
	v_pk_fma_f32 v[126:127], v[0:1], v[182:183], v[150:151] op_sel_hi:[1,0,1]
	v_mov_b32_e32 v0, s13
	v_mov_b32_e32 v1, s12
	v_pk_fma_f32 v[128:129], v[2:3], v[182:183], v[152:153] op_sel_hi:[1,0,1]
	v_pk_fma_f32 v[130:131], v[4:5], v[182:183], v[154:155] op_sel_hi:[1,0,1]
	v_pk_fma_f32 v[150:151], v[6:7], v[182:183], v[156:157] op_sel_hi:[1,0,1]
	v_pk_fma_f32 v[152:153], v[8:9], v[182:183], v[158:159] op_sel_hi:[1,0,1]
	v_pk_fma_f32 v[154:155], v[10:11], v[182:183], v[160:161] op_sel_hi:[1,0,1]
	v_pk_fma_f32 v[156:157], v[12:13], v[182:183], v[162:163] op_sel_hi:[1,0,1]
	v_pk_fma_f32 v[158:159], v[14:15], v[182:183], v[164:165] op_sel_hi:[1,0,1]
	v_pk_fma_f32 v[160:161], v[16:17], v[182:183], v[166:167] op_sel_hi:[1,0,1]
	v_pk_fma_f32 v[162:163], v[18:19], v[182:183], v[168:169] op_sel_hi:[1,0,1]
	v_pk_fma_f32 v[164:165], v[20:21], v[182:183], v[170:171] op_sel_hi:[1,0,1]
	v_pk_fma_f32 v[166:167], v[22:23], v[182:183], v[172:173] op_sel_hi:[1,0,1]
	v_pk_fma_f32 v[168:169], v[24:25], v[182:183], v[174:175] op_sel_hi:[1,0,1]
	v_pk_fma_f32 v[170:171], v[26:27], v[182:183], v[176:177] op_sel_hi:[1,0,1]
	v_pk_fma_f32 v[172:173], v[28:29], v[182:183], v[178:179] op_sel_hi:[1,0,1]
	v_pk_fma_f32 v[174:175], v[30:31], v[182:183], v[180:181] op_sel_hi:[1,0,1]
	v_cndmask_b32_e64 v176, v0, v1, s[0:1]
	s_waitcnt vmcnt(12)
	v_cvt_scalef32_pk32_f32_fp6 v[0:31], v[132:137], 1.0
	v_readlane_b32 s12, v106, 26
	v_readlane_b32 s13, v109, 26
	v_pk_fma_f32 v[126:127], v[0:1], v[176:177], v[126:127] op_sel_hi:[1,0,1]
	v_mov_b32_e32 v1, s12
	v_mov_b32_e32 v0, s13
	v_pk_fma_f32 v[128:129], v[2:3], v[176:177], v[128:129] op_sel_hi:[1,0,1]
	v_pk_fma_f32 v[130:131], v[4:5], v[176:177], v[130:131] op_sel_hi:[1,0,1]
	v_pk_fma_f32 v[132:133], v[6:7], v[176:177], v[150:151] op_sel_hi:[1,0,1]
	v_pk_fma_f32 v[134:135], v[8:9], v[176:177], v[152:153] op_sel_hi:[1,0,1]
	v_pk_fma_f32 v[136:137], v[10:11], v[176:177], v[154:155] op_sel_hi:[1,0,1]
	v_pk_fma_f32 v[150:151], v[12:13], v[176:177], v[156:157] op_sel_hi:[1,0,1]
	v_pk_fma_f32 v[152:153], v[14:15], v[176:177], v[158:159] op_sel_hi:[1,0,1]
	v_pk_fma_f32 v[154:155], v[16:17], v[176:177], v[160:161] op_sel_hi:[1,0,1]
	v_pk_fma_f32 v[156:157], v[18:19], v[176:177], v[162:163] op_sel_hi:[1,0,1]
	v_pk_fma_f32 v[158:159], v[20:21], v[176:177], v[164:165] op_sel_hi:[1,0,1]
	v_pk_fma_f32 v[160:161], v[22:23], v[176:177], v[166:167] op_sel_hi:[1,0,1]
	v_pk_fma_f32 v[162:163], v[24:25], v[176:177], v[168:169] op_sel_hi:[1,0,1]
	v_pk_fma_f32 v[164:165], v[26:27], v[176:177], v[170:171] op_sel_hi:[1,0,1]
	v_pk_fma_f32 v[166:167], v[28:29], v[176:177], v[172:173] op_sel_hi:[1,0,1]
	v_pk_fma_f32 v[168:169], v[30:31], v[176:177], v[174:175] op_sel_hi:[1,0,1]
	v_cndmask_b32_e64 v170, v0, v1, s[0:1]
	s_waitcnt vmcnt(10)
	v_cvt_scalef32_pk32_f32_fp6 v[0:31], v[138:143], 1.0
	v_readlane_b32 s12, v106, 27
	v_readlane_b32 s13, v109, 27
	v_pk_fma_f32 v[126:127], v[0:1], v[170:171], v[126:127] op_sel_hi:[1,0,1]
	v_mov_b32_e32 v1, s12
	v_mov_b32_e32 v0, s13
	v_pk_fma_f32 v[128:129], v[2:3], v[170:171], v[128:129] op_sel_hi:[1,0,1]
	v_pk_fma_f32 v[130:131], v[4:5], v[170:171], v[130:131] op_sel_hi:[1,0,1]
	v_pk_fma_f32 v[132:133], v[6:7], v[170:171], v[132:133] op_sel_hi:[1,0,1]
	v_pk_fma_f32 v[134:135], v[8:9], v[170:171], v[134:135] op_sel_hi:[1,0,1]
	v_pk_fma_f32 v[136:137], v[10:11], v[170:171], v[136:137] op_sel_hi:[1,0,1]
	v_pk_fma_f32 v[138:139], v[12:13], v[170:171], v[150:151] op_sel_hi:[1,0,1]
	v_pk_fma_f32 v[140:141], v[14:15], v[170:171], v[152:153] op_sel_hi:[1,0,1]
	v_pk_fma_f32 v[142:143], v[16:17], v[170:171], v[154:155] op_sel_hi:[1,0,1]
	v_pk_fma_f32 v[150:151], v[18:19], v[170:171], v[156:157] op_sel_hi:[1,0,1]
	v_pk_fma_f32 v[152:153], v[20:21], v[170:171], v[158:159] op_sel_hi:[1,0,1]
	v_pk_fma_f32 v[154:155], v[22:23], v[170:171], v[160:161] op_sel_hi:[1,0,1]
	v_pk_fma_f32 v[156:157], v[24:25], v[170:171], v[162:163] op_sel_hi:[1,0,1]
	v_pk_fma_f32 v[158:159], v[26:27], v[170:171], v[164:165] op_sel_hi:[1,0,1]
	v_pk_fma_f32 v[160:161], v[28:29], v[170:171], v[166:167] op_sel_hi:[1,0,1]
	v_pk_fma_f32 v[162:163], v[30:31], v[170:171], v[168:169] op_sel_hi:[1,0,1]
	v_cndmask_b32_e64 v164, v0, v1, s[0:1]
	s_waitcnt vmcnt(8)
	v_cvt_scalef32_pk32_f32_fp6 v[0:31], v[144:149], 1.0
	v_readlane_b32 s12, v106, 28
	v_readlane_b32 s13, v109, 28
	v_pk_fma_f32 v[126:127], v[0:1], v[164:165], v[126:127] op_sel_hi:[1,0,1]
	v_mov_b32_e32 v1, s12
	v_mov_b32_e32 v0, s13
	v_pk_fma_f32 v[128:129], v[2:3], v[164:165], v[128:129] op_sel_hi:[1,0,1]
	v_pk_fma_f32 v[130:131], v[4:5], v[164:165], v[130:131] op_sel_hi:[1,0,1]
	v_pk_fma_f32 v[132:133], v[6:7], v[164:165], v[132:133] op_sel_hi:[1,0,1]
	v_pk_fma_f32 v[134:135], v[8:9], v[164:165], v[134:135] op_sel_hi:[1,0,1]
	v_pk_fma_f32 v[136:137], v[10:11], v[164:165], v[136:137] op_sel_hi:[1,0,1]
	v_pk_fma_f32 v[138:139], v[12:13], v[164:165], v[138:139] op_sel_hi:[1,0,1]
	v_pk_fma_f32 v[140:141], v[14:15], v[164:165], v[140:141] op_sel_hi:[1,0,1]
	v_pk_fma_f32 v[142:143], v[16:17], v[164:165], v[142:143] op_sel_hi:[1,0,1]
	v_pk_fma_f32 v[144:145], v[18:19], v[164:165], v[150:151] op_sel_hi:[1,0,1]
	v_pk_fma_f32 v[146:147], v[20:21], v[164:165], v[152:153] op_sel_hi:[1,0,1]
	v_pk_fma_f32 v[148:149], v[22:23], v[164:165], v[154:155] op_sel_hi:[1,0,1]
	v_pk_fma_f32 v[150:151], v[24:25], v[164:165], v[156:157] op_sel_hi:[1,0,1]
	v_pk_fma_f32 v[152:153], v[26:27], v[164:165], v[158:159] op_sel_hi:[1,0,1]
	v_pk_fma_f32 v[154:155], v[28:29], v[164:165], v[160:161] op_sel_hi:[1,0,1]
	v_pk_fma_f32 v[156:157], v[30:31], v[164:165], v[162:163] op_sel_hi:[1,0,1]
	v_cndmask_b32_e64 v158, v0, v1, s[0:1]
	s_waitcnt vmcnt(6)
; DI void phase_peer_out(const Params& p, char* lds) {
;     ...
;       for (int k = 0; k < 8; ++k) {
;         const float c0 = __uint_as_float(__builtin_amdgcn_readlane(__float_as_uint(coefv[0]), kb * 8 + k)), c1 = __uint_as_float(__builtin_amdgcn_readlane(__float_as_uint(coefv[1]), kb * 8 + k));
;         const float cf = hb ? c1 : c0;
;         const f32x2 c2 = {cf, cf};
;         const v32f f = __builtin_amdgcn_cvt_scalef32_pk32_f32_fp6(qb[k], 1.0f);
; #pragma unroll
;         for (int i = 0; i < 16; ++i) o2[i] = f32x2{f[2 * i], f[2 * i + 1]} * c2 + o2[i];
	v_cvt_scalef32_pk32_f32_fp6 v[0:31], v[50:55], 1.0
	v_readlane_b32 s12, v106, 29
	v_readlane_b32 s13, v109, 29
	v_pk_fma_f32 v[50:51], v[0:1], v[158:159], v[126:127] op_sel_hi:[1,0,1]
	v_mov_b32_e32 v1, s12
	v_mov_b32_e32 v0, s13
	v_pk_fma_f32 v[52:53], v[2:3], v[158:159], v[128:129] op_sel_hi:[1,0,1]
	v_pk_fma_f32 v[54:55], v[4:5], v[158:159], v[130:131] op_sel_hi:[1,0,1]
	v_pk_fma_f32 v[126:127], v[6:7], v[158:159], v[132:133] op_sel_hi:[1,0,1]
	v_pk_fma_f32 v[128:129], v[8:9], v[158:159], v[134:135] op_sel_hi:[1,0,1]
	v_pk_fma_f32 v[130:131], v[10:11], v[158:159], v[136:137] op_sel_hi:[1,0,1]
	v_pk_fma_f32 v[132:133], v[12:13], v[158:159], v[138:139] op_sel_hi:[1,0,1]
	v_pk_fma_f32 v[134:135], v[14:15], v[158:159], v[140:141] op_sel_hi:[1,0,1]
	v_pk_fma_f32 v[136:137], v[16:17], v[158:159], v[142:143] op_sel_hi:[1,0,1]
	v_pk_fma_f32 v[138:139], v[18:19], v[158:159], v[144:145] op_sel_hi:[1,0,1]
	v_pk_fma_f32 v[140:141], v[20:21], v[158:159], v[146:147] op_sel_hi:[1,0,1]
	v_pk_fma_f32 v[142:143], v[22:23], v[158:159], v[148:149] op_sel_hi:[1,0,1]
	v_pk_fma_f32 v[144:145], v[24:25], v[158:159], v[150:151] op_sel_hi:[1,0,1]
	v_pk_fma_f32 v[146:147], v[26:27], v[158:159], v[152:153] op_sel_hi:[1,0,1]
	v_pk_fma_f32 v[148:149], v[28:29], v[158:159], v[154:155] op_sel_hi:[1,0,1]
	v_pk_fma_f32 v[150:151], v[30:31], v[158:159], v[156:157] op_sel_hi:[1,0,1]
	v_cndmask_b32_e64 v152, v0, v1, s[0:1]
	s_waitcnt vmcnt(4)
	v_cvt_scalef32_pk32_f32_fp6 v[0:31], v[44:49], 1.0
	v_readlane_b32 s12, v106, 30
	v_readlane_b32 s13, v109, 30
	v_pk_fma_f32 v[44:45], v[0:1], v[152:153], v[50:51] op_sel_hi:[1,0,1]
	v_mov_b32_e32 v1, s12
	v_mov_b32_e32 v0, s13
	v_pk_fma_f32 v[46:47], v[2:3], v[152:153], v[52:53] op_sel_hi:[1,0,1]
	v_pk_fma_f32 v[48:49], v[4:5], v[152:153], v[54:55] op_sel_hi:[1,0,1]
	v_pk_fma_f32 v[50:51], v[6:7], v[152:153], v[126:127] op_sel_hi:[1,0,1]
	v_pk_fma_f32 v[52:53], v[8:9], v[152:153], v[128:129] op_sel_hi:[1,0,1]
	v_pk_fma_f32 v[54:55], v[10:11], v[152:153], v[130:131] op_sel_hi:[1,0,1]
	v_pk_fma_f32 v[126:127], v[12:13], v[152:153], v[132:133] op_sel_hi:[1,0,1]
	v_pk_fma_f32 v[128:129], v[14:15], v[152:153], v[134:135] op_sel_hi:[1,0,1]
	v_pk_fma_f32 v[130:131], v[16:17], v[152:153], v[136:137] op_sel_hi:[1,0,1]
	v_pk_fma_f32 v[132:133], v[18:19], v[152:153], v[138:139] op_sel_hi:[1,0,1]
	v_pk_fma_f32 v[134:135], v[20:21], v[152:153], v[140:141] op_sel_hi:[1,0,1]
	v_pk_fma_f32 v[136:137], v[22:23], v[152:153], v[142:143] op_sel_hi:[1,0,1]
	v_pk_fma_f32 v[138:139], v[24:25], v[152:153], v[144:145] op_sel_hi:[1,0,1]
	v_pk_fma_f32 v[140:141], v[26:27], v[152:153], v[146:147] op_sel_hi:[1,0,1]
	v_pk_fma_f32 v[142:143], v[28:29], v[152:153], v[148:149] op_sel_hi:[1,0,1]
	v_pk_fma_f32 v[144:145], v[30:31], v[152:153], v[150:151] op_sel_hi:[1,0,1]
	v_cndmask_b32_e64 v146, v0, v1, s[0:1]
	s_waitcnt vmcnt(1)
	v_cvt_scalef32_pk32_f32_fp6 v[0:31], v[38:43], 1.0
	v_readlane_b32 s12, v106, 31
	v_readlane_b32 s13, v109, 31
	v_pk_fma_f32 v[38:39], v[0:1], v[146:147], v[44:45] op_sel_hi:[1,0,1]
	v_mov_b32_e32 v1, s12
	v_mov_b32_e32 v0, s13
	v_readlane_b32 s12, v108, 32
	v_readlane_b32 s13, v107, 32
	v_pk_fma_f32 v[40:41], v[2:3], v[146:147], v[46:47] op_sel_hi:[1,0,1]
	v_pk_fma_f32 v[42:43], v[4:5], v[146:147], v[48:49] op_sel_hi:[1,0,1]
	v_pk_fma_f32 v[44:45], v[6:7], v[146:147], v[50:51] op_sel_hi:[1,0,1]
	v_pk_fma_f32 v[46:47], v[8:9], v[146:147], v[52:53] op_sel_hi:[1,0,1]
	v_pk_fma_f32 v[48:49], v[10:11], v[146:147], v[54:55] op_sel_hi:[1,0,1]
	v_pk_fma_f32 v[50:51], v[12:13], v[146:147], v[126:127] op_sel_hi:[1,0,1]
	v_pk_fma_f32 v[52:53], v[14:15], v[146:147], v[128:129] op_sel_hi:[1,0,1]
	v_pk_fma_f32 v[54:55], v[16:17], v[146:147], v[130:131] op_sel_hi:[1,0,1]
	v_pk_fma_f32 v[132:133], v[18:19], v[146:147], v[132:133] op_sel_hi:[1,0,1]
	v_pk_fma_f32 v[134:135], v[20:21], v[146:147], v[134:135] op_sel_hi:[1,0,1]
	v_pk_fma_f32 v[136:137], v[22:23], v[146:147], v[136:137] op_sel_hi:[1,0,1]
	v_pk_fma_f32 v[138:139], v[24:25], v[146:147], v[138:139] op_sel_hi:[1,0,1]
	v_pk_fma_f32 v[140:141], v[26:27], v[146:147], v[140:141] op_sel_hi:[1,0,1]
	v_pk_fma_f32 v[142:143], v[28:29], v[146:147], v[142:143] op_sel_hi:[1,0,1]
	v_pk_fma_f32 v[144:145], v[30:31], v[146:147], v[144:145] op_sel_hi:[1,0,1]
	v_cndmask_b32_e64 v146, v0, v1, s[0:1]
	v_mov_b32_e32 v0, s13
	v_mov_b32_e32 v1, s12
	v_cndmask_b32_e64 v0, v0, v1, s[0:1]
	v_mad_i64_i32 v[130:131], s[12:13], v0, s23, v[64:65]
	s_waitcnt vmcnt(0)
; DI void phase_peer_out(const Params& p, char* lds) {
;     ...
;     for (int kb = 0; kb < 8; ++kb) {
;       v6u qb[8];
; #pragma unroll
;       for (int k = 0; k < 8; ++k) {
;         const int e0 = __builtin_amdgcn_readlane(el[0], kb * 8 + k), e1 = __builtin_amdgcn_readlane(el[1], kb * 8 + k);
;         qb[k] = load6(V6 + (size_t)(hb ? e1 : e0) * 768);
;       }
; #pragma unroll
;       for (int k = 0; k < 8; ++k) {
;         const float c0 = __uint_as_float(__builtin_amdgcn_readlane(__float_as_uint(coefv[0]), kb * 8 + k)), c1 = __uint_as_float(__builtin_amdgcn_readlane(__float_as_uint(coefv[1]), kb * 8 + k));
;         const float cf = hb ? c1 : c0;
;         const f32x2 c2 = {cf, cf};
;         const v32f f = __builtin_amdgcn_cvt_scalef32_pk32_f32_fp6(qb[k], 1.0f);
; #pragma unroll
;         for (int i = 0; i < 16; ++i) o2[i] = f32x2{f[2 * i], f[2 * i + 1]} * c2 + o2[i];
	v_cvt_scalef32_pk32_f32_fp6 v[0:31], v[32:37], 1.0
	v_readlane_b32 s12, v108, 33
	v_readlane_b32 s13, v107, 33
	v_pk_fma_f32 v[150:151], v[0:1], v[146:147], v[38:39] op_sel_hi:[1,0,1]
	v_mov_b32_e32 v1, s12
	v_mov_b32_e32 v0, s13
	v_cndmask_b32_e64 v0, v0, v1, s[0:1]
	v_mad_i64_i32 v[0:1], s[12:13], v0, s23, v[64:65]
	v_readlane_b32 s12, v108, 34
	v_readlane_b32 s13, v107, 34
	global_load_dwordx4 v[126:129], v[130:131], off
	v_pk_fma_f32 v[168:169], v[18:19], v[146:147], v[132:133] op_sel_hi:[1,0,1]
	global_load_dwordx2 v[130:131], v[130:131], off offset:16
	v_pk_fma_f32 v[170:171], v[20:21], v[146:147], v[134:135] op_sel_hi:[1,0,1]
	v_pk_fma_f32 v[172:173], v[22:23], v[146:147], v[136:137] op_sel_hi:[1,0,1]
	global_load_dwordx2 v[136:137], v[0:1], off offset:16
	global_load_dwordx4 v[132:135], v[0:1], off
	v_mov_b32_e32 v0, s13
	v_mov_b32_e32 v1, s12
	v_cndmask_b32_e64 v0, v0, v1, s[0:1]
	v_mad_i64_i32 v[0:1], s[12:13], v0, s23, v[64:65]
	v_readlane_b32 s12, v108, 35
	v_readlane_b32 s13, v107, 35
	v_pk_fma_f32 v[152:153], v[2:3], v[146:147], v[40:41] op_sel_hi:[1,0,1]
	v_mov_b32_e32 v3, s12
	v_mov_b32_e32 v2, s13
	v_cndmask_b32_e64 v2, v2, v3, s[0:1]
	v_mad_i64_i32 v[2:3], s[12:13], v2, s23, v[64:65]
	v_readlane_b32 s12, v108, 36
	v_readlane_b32 s13, v107, 36
	v_pk_fma_f32 v[154:155], v[4:5], v[146:147], v[42:43] op_sel_hi:[1,0,1]
	v_pk_fma_f32 v[156:157], v[6:7], v[146:147], v[44:45] op_sel_hi:[1,0,1]
	v_pk_fma_f32 v[158:159], v[8:9], v[146:147], v[46:47] op_sel_hi:[1,0,1]
	v_pk_fma_f32 v[160:161], v[10:11], v[146:147], v[48:49] op_sel_hi:[1,0,1]
	v_pk_fma_f32 v[162:163], v[12:13], v[146:147], v[50:51] op_sel_hi:[1,0,1]
	v_pk_fma_f32 v[164:165], v[14:15], v[146:147], v[52:53] op_sel_hi:[1,0,1]
	v_pk_fma_f32 v[166:167], v[16:17], v[146:147], v[54:55] op_sel_hi:[1,0,1]
	v_pk_fma_f32 v[174:175], v[24:25], v[146:147], v[138:139] op_sel_hi:[1,0,1]
	v_pk_fma_f32 v[176:177], v[26:27], v[146:147], v[140:141] op_sel_hi:[1,0,1]
	v_pk_fma_f32 v[178:179], v[28:29], v[146:147], v[142:143] op_sel_hi:[1,0,1]
	v_pk_fma_f32 v[180:181], v[30:31], v[146:147], v[144:145] op_sel_hi:[1,0,1]
	global_load_dwordx4 v[138:141], v[0:1], off
	global_load_dwordx2 v[142:143], v[0:1], off offset:16
	global_load_dwordx4 v[144:147], v[2:3], off
	v_mov_b32_e32 v0, s13
	v_mov_b32_e32 v1, s12
	v_cndmask_b32_e64 v0, v0, v1, s[0:1]
	v_mad_i64_i32 v[0:1], s[12:13], v0, s23, v[64:65]
	v_readlane_b32 s12, v108, 37
	v_readlane_b32 s13, v107, 37
	global_load_dwordx2 v[148:149], v[2:3], off offset:16
	global_load_dwordx4 v[50:53], v[0:1], off
	v_mov_b32_e32 v2, s13
	v_mov_b32_e32 v3, s12
	v_cndmask_b32_e64 v2, v2, v3, s[0:1]
	v_mad_i64_i32 v[2:3], s[12:13], v2, s23, v[64:65]
	v_readlane_b32 s12, v108, 38
	v_readlane_b32 s13, v107, 38
	global_load_dwordx2 v[54:55], v[0:1], off offset:16
	global_load_dwordx4 v[44:47], v[2:3], off
	v_mov_b32_e32 v0, s13
	v_mov_b32_e32 v1, s12
	v_cndmask_b32_e64 v0, v0, v1, s[0:1]
	v_mad_i64_i32 v[0:1], s[12:13], v0, s23, v[64:65]
	v_readlane_b32 s12, v108, 39
	v_readlane_b32 s13, v107, 39
	global_load_dwordx2 v[48:49], v[2:3], off offset:16
	global_load_dwordx4 v[38:41], v[0:1], off
	v_mov_b32_e32 v2, s13
	v_mov_b32_e32 v3, s12
	v_cndmask_b32_e64 v2, v2, v3, s[0:1]
	v_mad_i64_i32 v[2:3], s[12:13], v2, s23, v[64:65]
	global_load_dwordx2 v[36:37], v[2:3], off offset:16
	global_load_dwordx2 v[42:43], v[0:1], off offset:16
	global_load_dwordx4 v[32:35], v[2:3], off
	v_readlane_b32 s12, v106, 32
	v_readlane_b32 s13, v109, 32
	s_nop 0
	v_mov_b32_e32 v1, s12
	v_mov_b32_e32 v0, s13
	v_cndmask_b32_e64 v182, v0, v1, s[0:1]
	v_readlane_b32 s12, v106, 33
	v_readlane_b32 s13, v109, 33
	s_waitcnt vmcnt(14)
	v_cvt_scalef32_pk32_f32_fp6 v[0:31], v[126:131], 1.0
	v_pk_fma_f32 v[126:127], v[0:1], v[182:183], v[150:151] op_sel_hi:[1,0,1]
	v_mov_b32_e32 v0, s13
	v_mov_b32_e32 v1, s12
	v_pk_fma_f32 v[128:129], v[2:3], v[182:183], v[152:153] op_sel_hi:[1,0,1]
	v_pk_fma_f32 v[130:131], v[4:5], v[182:183], v[154:155] op_sel_hi:[1,0,1]
	v_pk_fma_f32 v[150:151], v[6:7], v[182:183], v[156:157] op_sel_hi:[1,0,1]
	v_pk_fma_f32 v[152:153], v[8:9], v[182:183], v[158:159] op_sel_hi:[1,0,1]
	v_pk_fma_f32 v[154:155], v[10:11], v[182:183], v[160:161] op_sel_hi:[1,0,1]
	v_pk_fma_f32 v[156:157], v[12:13], v[182:183], v[162:163] op_sel_hi:[1,0,1]
	v_pk_fma_f32 v[158:159], v[14:15], v[182:183], v[164:165] op_sel_hi:[1,0,1]
	v_pk_fma_f32 v[160:161], v[16:17], v[182:183], v[166:167] op_sel_hi:[1,0,1]
	v_pk_fma_f32 v[162:163], v[18:19], v[182:183], v[168:169] op_sel_hi:[1,0,1]
	v_pk_fma_f32 v[164:165], v[20:21], v[182:183], v[170:171] op_sel_hi:[1,0,1]
	v_pk_fma_f32 v[166:167], v[22:23], v[182:183], v[172:173] op_sel_hi:[1,0,1]
	v_pk_fma_f32 v[168:169], v[24:25], v[182:183], v[174:175] op_sel_hi:[1,0,1]
	v_pk_fma_f32 v[170:171], v[26:27], v[182:183], v[176:177] op_sel_hi:[1,0,1]
	v_pk_fma_f32 v[172:173], v[28:29], v[182:183], v[178:179] op_sel_hi:[1,0,1]
	v_pk_fma_f32 v[174:175], v[30:31], v[182:183], v[180:181] op_sel_hi:[1,0,1]
	v_cndmask_b32_e64 v176, v0, v1, s[0:1]
	s_waitcnt vmcnt(12)
; DI void phase_peer_out(const Params& p, char* lds) {
;     ...
;       for (int k = 0; k < 8; ++k) {
;         const float c0 = __uint_as_float(__builtin_amdgcn_readlane(__float_as_uint(coefv[0]), kb * 8 + k)), c1 = __uint_as_float(__builtin_amdgcn_readlane(__float_as_uint(coefv[1]), kb * 8 + k));
;         const float cf = hb ? c1 : c0;
;         const f32x2 c2 = {cf, cf};
;         const v32f f = __builtin_amdgcn_cvt_scalef32_pk32_f32_fp6(qb[k], 1.0f);
; #pragma unroll
;         for (int i = 0; i < 16; ++i) o2[i] = f32x2{f[2 * i], f[2 * i + 1]} * c2 + o2[i];
	v_cvt_scalef32_pk32_f32_fp6 v[0:31], v[132:137], 1.0
	v_readlane_b32 s12, v106, 34
	v_readlane_b32 s13, v109, 34
	v_pk_fma_f32 v[126:127], v[0:1], v[176:177], v[126:127] op_sel_hi:[1,0,1]
	v_mov_b32_e32 v1, s12
	v_mov_b32_e32 v0, s13
	v_pk_fma_f32 v[128:129], v[2:3], v[176:177], v[128:129] op_sel_hi:[1,0,1]
	v_pk_fma_f32 v[130:131], v[4:5], v[176:177], v[130:131] op_sel_hi:[1,0,1]
	v_pk_fma_f32 v[132:133], v[6:7], v[176:177], v[150:151] op_sel_hi:[1,0,1]
	v_pk_fma_f32 v[134:135], v[8:9], v[176:177], v[152:153] op_sel_hi:[1,0,1]
	v_pk_fma_f32 v[136:137], v[10:11], v[176:177], v[154:155] op_sel_hi:[1,0,1]
	v_pk_fma_f32 v[150:151], v[12:13], v[176:177], v[156:157] op_sel_hi:[1,0,1]
	v_pk_fma_f32 v[152:153], v[14:15], v[176:177], v[158:159] op_sel_hi:[1,0,1]
	v_pk_fma_f32 v[154:155], v[16:17], v[176:177], v[160:161] op_sel_hi:[1,0,1]
	v_pk_fma_f32 v[156:157], v[18:19], v[176:177], v[162:163] op_sel_hi:[1,0,1]
	v_pk_fma_f32 v[158:159], v[20:21], v[176:177], v[164:165] op_sel_hi:[1,0,1]
	v_pk_fma_f32 v[160:161], v[22:23], v[176:177], v[166:167] op_sel_hi:[1,0,1]
	v_pk_fma_f32 v[162:163], v[24:25], v[176:177], v[168:169] op_sel_hi:[1,0,1]
	v_pk_fma_f32 v[164:165], v[26:27], v[176:177], v[170:171] op_sel_hi:[1,0,1]
	v_pk_fma_f32 v[166:167], v[28:29], v[176:177], v[172:173] op_sel_hi:[1,0,1]
	v_pk_fma_f32 v[168:169], v[30:31], v[176:177], v[174:175] op_sel_hi:[1,0,1]
	v_cndmask_b32_e64 v170, v0, v1, s[0:1]
	s_waitcnt vmcnt(10)
	v_cvt_scalef32_pk32_f32_fp6 v[0:31], v[138:143], 1.0
	v_readlane_b32 s12, v106, 35
	v_readlane_b32 s13, v109, 35
	v_pk_fma_f32 v[126:127], v[0:1], v[170:171], v[126:127] op_sel_hi:[1,0,1]
	v_mov_b32_e32 v1, s12
	v_mov_b32_e32 v0, s13
	v_pk_fma_f32 v[128:129], v[2:3], v[170:171], v[128:129] op_sel_hi:[1,0,1]
	v_pk_fma_f32 v[130:131], v[4:5], v[170:171], v[130:131] op_sel_hi:[1,0,1]
	v_pk_fma_f32 v[132:133], v[6:7], v[170:171], v[132:133] op_sel_hi:[1,0,1]
	v_pk_fma_f32 v[134:135], v[8:9], v[170:171], v[134:135] op_sel_hi:[1,0,1]
	v_pk_fma_f32 v[136:137], v[10:11], v[170:171], v[136:137] op_sel_hi:[1,0,1]
	v_pk_fma_f32 v[138:139], v[12:13], v[170:171], v[150:151] op_sel_hi:[1,0,1]
	v_pk_fma_f32 v[140:141], v[14:15], v[170:171], v[152:153] op_sel_hi:[1,0,1]
	v_pk_fma_f32 v[142:143], v[16:17], v[170:171], v[154:155] op_sel_hi:[1,0,1]
	v_pk_fma_f32 v[150:151], v[18:19], v[170:171], v[156:157] op_sel_hi:[1,0,1]
	v_pk_fma_f32 v[152:153], v[20:21], v[170:171], v[158:159] op_sel_hi:[1,0,1]
	v_pk_fma_f32 v[154:155], v[22:23], v[170:171], v[160:161] op_sel_hi:[1,0,1]
	v_pk_fma_f32 v[156:157], v[24:25], v[170:171], v[162:163] op_sel_hi:[1,0,1]
	v_pk_fma_f32 v[158:159], v[26:27], v[170:171], v[164:165] op_sel_hi:[1,0,1]
	v_pk_fma_f32 v[160:161], v[28:29], v[170:171], v[166:167] op_sel_hi:[1,0,1]
	v_pk_fma_f32 v[162:163], v[30:31], v[170:171], v[168:169] op_sel_hi:[1,0,1]
	v_cndmask_b32_e64 v164, v0, v1, s[0:1]
	s_waitcnt vmcnt(8)
	v_cvt_scalef32_pk32_f32_fp6 v[0:31], v[144:149], 1.0
	v_readlane_b32 s12, v106, 36
	v_readlane_b32 s13, v109, 36
	v_pk_fma_f32 v[126:127], v[0:1], v[164:165], v[126:127] op_sel_hi:[1,0,1]
	v_mov_b32_e32 v1, s12
	v_mov_b32_e32 v0, s13
	v_pk_fma_f32 v[128:129], v[2:3], v[164:165], v[128:129] op_sel_hi:[1,0,1]
	v_pk_fma_f32 v[130:131], v[4:5], v[164:165], v[130:131] op_sel_hi:[1,0,1]
	v_pk_fma_f32 v[132:133], v[6:7], v[164:165], v[132:133] op_sel_hi:[1,0,1]
	v_pk_fma_f32 v[134:135], v[8:9], v[164:165], v[134:135] op_sel_hi:[1,0,1]
	v_pk_fma_f32 v[136:137], v[10:11], v[164:165], v[136:137] op_sel_hi:[1,0,1]
	v_pk_fma_f32 v[138:139], v[12:13], v[164:165], v[138:139] op_sel_hi:[1,0,1]
	v_pk_fma_f32 v[140:141], v[14:15], v[164:165], v[140:141] op_sel_hi:[1,0,1]
	v_pk_fma_f32 v[142:143], v[16:17], v[164:165], v[142:143] op_sel_hi:[1,0,1]
	v_pk_fma_f32 v[144:145], v[18:19], v[164:165], v[150:151] op_sel_hi:[1,0,1]
	v_pk_fma_f32 v[146:147], v[20:21], v[164:165], v[152:153] op_sel_hi:[1,0,1]
	v_pk_fma_f32 v[148:149], v[22:23], v[164:165], v[154:155] op_sel_hi:[1,0,1]
	v_pk_fma_f32 v[150:151], v[24:25], v[164:165], v[156:157] op_sel_hi:[1,0,1]
	v_pk_fma_f32 v[152:153], v[26:27], v[164:165], v[158:159] op_sel_hi:[1,0,1]
	v_pk_fma_f32 v[154:155], v[28:29], v[164:165], v[160:161] op_sel_hi:[1,0,1]
	v_pk_fma_f32 v[156:157], v[30:31], v[164:165], v[162:163] op_sel_hi:[1,0,1]
	v_cndmask_b32_e64 v158, v0, v1, s[0:1]
	s_waitcnt vmcnt(6)
	v_cvt_scalef32_pk32_f32_fp6 v[0:31], v[50:55], 1.0
	v_readlane_b32 s12, v106, 37
	v_readlane_b32 s13, v109, 37
	v_pk_fma_f32 v[50:51], v[0:1], v[158:159], v[126:127] op_sel_hi:[1,0,1]
	v_mov_b32_e32 v1, s12
	v_mov_b32_e32 v0, s13
	v_pk_fma_f32 v[52:53], v[2:3], v[158:159], v[128:129] op_sel_hi:[1,0,1]
	v_pk_fma_f32 v[54:55], v[4:5], v[158:159], v[130:131] op_sel_hi:[1,0,1]
	v_pk_fma_f32 v[126:127], v[6:7], v[158:159], v[132:133] op_sel_hi:[1,0,1]
	v_pk_fma_f32 v[128:129], v[8:9], v[158:159], v[134:135] op_sel_hi:[1,0,1]
	v_pk_fma_f32 v[130:131], v[10:11], v[158:159], v[136:137] op_sel_hi:[1,0,1]
	v_pk_fma_f32 v[132:133], v[12:13], v[158:159], v[138:139] op_sel_hi:[1,0,1]
	v_pk_fma_f32 v[134:135], v[14:15], v[158:159], v[140:141] op_sel_hi:[1,0,1]
	v_pk_fma_f32 v[136:137], v[16:17], v[158:159], v[142:143] op_sel_hi:[1,0,1]
	v_pk_fma_f32 v[138:139], v[18:19], v[158:159], v[144:145] op_sel_hi:[1,0,1]
	v_pk_fma_f32 v[140:141], v[20:21], v[158:159], v[146:147] op_sel_hi:[1,0,1]
	v_pk_fma_f32 v[142:143], v[22:23], v[158:159], v[148:149] op_sel_hi:[1,0,1]
	v_pk_fma_f32 v[144:145], v[24:25], v[158:159], v[150:151] op_sel_hi:[1,0,1]
	v_pk_fma_f32 v[146:147], v[26:27], v[158:159], v[152:153] op_sel_hi:[1,0,1]
	v_pk_fma_f32 v[148:149], v[28:29], v[158:159], v[154:155] op_sel_hi:[1,0,1]
	v_pk_fma_f32 v[150:151], v[30:31], v[158:159], v[156:157] op_sel_hi:[1,0,1]
	v_cndmask_b32_e64 v152, v0, v1, s[0:1]
	s_waitcnt vmcnt(4)
; DI void phase_peer_out(const Params& p, char* lds) {
;     ...
;     for (int kb = 0; kb < 8; ++kb) {
;       v6u qb[8];
; #pragma unroll
;       for (int k = 0; k < 8; ++k) {
;         const int e0 = __builtin_amdgcn_readlane(el[0], kb * 8 + k), e1 = __builtin_amdgcn_readlane(el[1], kb * 8 + k);
;         qb[k] = load6(V6 + (size_t)(hb ? e1 : e0) * 768);
;       }
; #pragma unroll
;       for (int k = 0; k < 8; ++k) {
;         const float c0 = __uint_as_float(__builtin_amdgcn_readlane(__float_as_uint(coefv[0]), kb * 8 + k)), c1 = __uint_as_float(__builtin_amdgcn_readlane(__float_as_uint(coefv[1]), kb * 8 + k));
;         const float cf = hb ? c1 : c0;
;         const f32x2 c2 = {cf, cf};
;         const v32f f = __builtin_amdgcn_cvt_scalef32_pk32_f32_fp6(qb[k], 1.0f);
; #pragma unroll
;         for (int i = 0; i < 16; ++i) o2[i] = f32x2{f[2 * i], f[2 * i + 1]} * c2 + o2[i];
	v_cvt_scalef32_pk32_f32_fp6 v[0:31], v[44:49], 1.0
	v_readlane_b32 s12, v106, 38
	v_readlane_b32 s13, v109, 38
	v_pk_fma_f32 v[44:45], v[0:1], v[152:153], v[50:51] op_sel_hi:[1,0,1]
	v_mov_b32_e32 v1, s12
	v_mov_b32_e32 v0, s13
	v_pk_fma_f32 v[46:47], v[2:3], v[152:153], v[52:53] op_sel_hi:[1,0,1]
	v_pk_fma_f32 v[48:49], v[4:5], v[152:153], v[54:55] op_sel_hi:[1,0,1]
	v_pk_fma_f32 v[50:51], v[6:7], v[152:153], v[126:127] op_sel_hi:[1,0,1]
	v_pk_fma_f32 v[52:53], v[8:9], v[152:153], v[128:129] op_sel_hi:[1,0,1]
	v_pk_fma_f32 v[54:55], v[10:11], v[152:153], v[130:131] op_sel_hi:[1,0,1]
	v_pk_fma_f32 v[126:127], v[12:13], v[152:153], v[132:133] op_sel_hi:[1,0,1]
	v_pk_fma_f32 v[128:129], v[14:15], v[152:153], v[134:135] op_sel_hi:[1,0,1]
	v_pk_fma_f32 v[130:131], v[16:17], v[152:153], v[136:137] op_sel_hi:[1,0,1]
	v_pk_fma_f32 v[132:133], v[18:19], v[152:153], v[138:139] op_sel_hi:[1,0,1]
	v_pk_fma_f32 v[134:135], v[20:21], v[152:153], v[140:141] op_sel_hi:[1,0,1]
	v_pk_fma_f32 v[136:137], v[22:23], v[152:153], v[142:143] op_sel_hi:[1,0,1]
	v_pk_fma_f32 v[138:139], v[24:25], v[152:153], v[144:145] op_sel_hi:[1,0,1]
	v_pk_fma_f32 v[140:141], v[26:27], v[152:153], v[146:147] op_sel_hi:[1,0,1]
	v_pk_fma_f32 v[142:143], v[28:29], v[152:153], v[148:149] op_sel_hi:[1,0,1]
	v_pk_fma_f32 v[144:145], v[30:31], v[152:153], v[150:151] op_sel_hi:[1,0,1]
	v_cndmask_b32_e64 v146, v0, v1, s[0:1]
	s_waitcnt vmcnt(1)
	v_cvt_scalef32_pk32_f32_fp6 v[0:31], v[38:43], 1.0
	v_readlane_b32 s12, v106, 39
	v_readlane_b32 s13, v109, 39
	v_pk_fma_f32 v[38:39], v[0:1], v[146:147], v[44:45] op_sel_hi:[1,0,1]
	v_mov_b32_e32 v1, s12
	v_mov_b32_e32 v0, s13
	v_readlane_b32 s12, v108, 40
	v_readlane_b32 s13, v107, 40
	v_pk_fma_f32 v[40:41], v[2:3], v[146:147], v[46:47] op_sel_hi:[1,0,1]
	v_pk_fma_f32 v[42:43], v[4:5], v[146:147], v[48:49] op_sel_hi:[1,0,1]
	v_pk_fma_f32 v[44:45], v[6:7], v[146:147], v[50:51] op_sel_hi:[1,0,1]
	v_pk_fma_f32 v[46:47], v[8:9], v[146:147], v[52:53] op_sel_hi:[1,0,1]
	v_pk_fma_f32 v[48:49], v[10:11], v[146:147], v[54:55] op_sel_hi:[1,0,1]
	v_pk_fma_f32 v[50:51], v[12:13], v[146:147], v[126:127] op_sel_hi:[1,0,1]
	v_pk_fma_f32 v[52:53], v[14:15], v[146:147], v[128:129] op_sel_hi:[1,0,1]
	v_pk_fma_f32 v[54:55], v[16:17], v[146:147], v[130:131] op_sel_hi:[1,0,1]
	v_pk_fma_f32 v[132:133], v[18:19], v[146:147], v[132:133] op_sel_hi:[1,0,1]
	v_pk_fma_f32 v[134:135], v[20:21], v[146:147], v[134:135] op_sel_hi:[1,0,1]
	v_pk_fma_f32 v[136:137], v[22:23], v[146:147], v[136:137] op_sel_hi:[1,0,1]
	v_pk_fma_f32 v[138:139], v[24:25], v[146:147], v[138:139] op_sel_hi:[1,0,1]
	v_pk_fma_f32 v[140:141], v[26:27], v[146:147], v[140:141] op_sel_hi:[1,0,1]
	v_pk_fma_f32 v[142:143], v[28:29], v[146:147], v[142:143] op_sel_hi:[1,0,1]
	v_pk_fma_f32 v[144:145], v[30:31], v[146:147], v[144:145] op_sel_hi:[1,0,1]
	v_cndmask_b32_e64 v146, v0, v1, s[0:1]
	v_mov_b32_e32 v0, s13
	v_mov_b32_e32 v1, s12
	v_cndmask_b32_e64 v0, v0, v1, s[0:1]
	v_mad_i64_i32 v[130:131], s[12:13], v0, s23, v[64:65]
	s_waitcnt vmcnt(0)
	v_cvt_scalef32_pk32_f32_fp6 v[0:31], v[32:37], 1.0
	v_readlane_b32 s12, v108, 41
	v_readlane_b32 s13, v107, 41
	v_pk_fma_f32 v[150:151], v[0:1], v[146:147], v[38:39] op_sel_hi:[1,0,1]
	v_mov_b32_e32 v1, s12
	v_mov_b32_e32 v0, s13
	v_cndmask_b32_e64 v0, v0, v1, s[0:1]
	v_mad_i64_i32 v[0:1], s[12:13], v0, s23, v[64:65]
	v_readlane_b32 s12, v108, 42
	v_readlane_b32 s13, v107, 42
	global_load_dwordx4 v[126:129], v[130:131], off
	v_pk_fma_f32 v[168:169], v[18:19], v[146:147], v[132:133] op_sel_hi:[1,0,1]
	global_load_dwordx2 v[130:131], v[130:131], off offset:16
	v_pk_fma_f32 v[170:171], v[20:21], v[146:147], v[134:135] op_sel_hi:[1,0,1]
	v_pk_fma_f32 v[172:173], v[22:23], v[146:147], v[136:137] op_sel_hi:[1,0,1]
	global_load_dwordx2 v[136:137], v[0:1], off offset:16
	global_load_dwordx4 v[132:135], v[0:1], off
	v_mov_b32_e32 v0, s13
	v_mov_b32_e32 v1, s12
	v_cndmask_b32_e64 v0, v0, v1, s[0:1]
	v_mad_i64_i32 v[0:1], s[12:13], v0, s23, v[64:65]
	v_readlane_b32 s12, v108, 43
	v_readlane_b32 s13, v107, 43
	v_pk_fma_f32 v[152:153], v[2:3], v[146:147], v[40:41] op_sel_hi:[1,0,1]
	v_mov_b32_e32 v3, s12
	v_mov_b32_e32 v2, s13
	v_cndmask_b32_e64 v2, v2, v3, s[0:1]
	v_mad_i64_i32 v[2:3], s[12:13], v2, s23, v[64:65]
	v_readlane_b32 s12, v108, 44
	v_readlane_b32 s13, v107, 44
	v_pk_fma_f32 v[154:155], v[4:5], v[146:147], v[42:43] op_sel_hi:[1,0,1]
	v_pk_fma_f32 v[156:157], v[6:7], v[146:147], v[44:45] op_sel_hi:[1,0,1]
	v_pk_fma_f32 v[158:159], v[8:9], v[146:147], v[46:47] op_sel_hi:[1,0,1]
	v_pk_fma_f32 v[160:161], v[10:11], v[146:147], v[48:49] op_sel_hi:[1,0,1]
	v_pk_fma_f32 v[162:163], v[12:13], v[146:147], v[50:51] op_sel_hi:[1,0,1]
	v_pk_fma_f32 v[164:165], v[14:15], v[146:147], v[52:53] op_sel_hi:[1,0,1]
	v_pk_fma_f32 v[166:167], v[16:17], v[146:147], v[54:55] op_sel_hi:[1,0,1]
	v_pk_fma_f32 v[174:175], v[24:25], v[146:147], v[138:139] op_sel_hi:[1,0,1]
	v_pk_fma_f32 v[176:177], v[26:27], v[146:147], v[140:141] op_sel_hi:[1,0,1]
	v_pk_fma_f32 v[178:179], v[28:29], v[146:147], v[142:143] op_sel_hi:[1,0,1]
	v_pk_fma_f32 v[180:181], v[30:31], v[146:147], v[144:145] op_sel_hi:[1,0,1]
	global_load_dwordx4 v[138:141], v[0:1], off
	global_load_dwordx2 v[142:143], v[0:1], off offset:16
	global_load_dwordx4 v[144:147], v[2:3], off
	v_mov_b32_e32 v0, s13
	v_mov_b32_e32 v1, s12
	v_cndmask_b32_e64 v0, v0, v1, s[0:1]
	v_mad_i64_i32 v[0:1], s[12:13], v0, s23, v[64:65]
	v_readlane_b32 s12, v108, 45
	v_readlane_b32 s13, v107, 45
	global_load_dwordx2 v[148:149], v[2:3], off offset:16
	global_load_dwordx4 v[50:53], v[0:1], off
	v_mov_b32_e32 v2, s13
	v_mov_b32_e32 v3, s12
	v_cndmask_b32_e64 v2, v2, v3, s[0:1]
	v_mad_i64_i32 v[2:3], s[12:13], v2, s23, v[64:65]
	v_readlane_b32 s12, v108, 46
	v_readlane_b32 s13, v107, 46
	global_load_dwordx2 v[54:55], v[0:1], off offset:16
	global_load_dwordx4 v[44:47], v[2:3], off
	v_mov_b32_e32 v0, s13
	v_mov_b32_e32 v1, s12
	v_cndmask_b32_e64 v0, v0, v1, s[0:1]
	v_mad_i64_i32 v[0:1], s[12:13], v0, s23, v[64:65]
	v_readlane_b32 s12, v108, 47
	v_readlane_b32 s13, v107, 47
	global_load_dwordx2 v[48:49], v[2:3], off offset:16
	global_load_dwordx4 v[38:41], v[0:1], off
	v_mov_b32_e32 v2, s13
	v_mov_b32_e32 v3, s12
	v_cndmask_b32_e64 v2, v2, v3, s[0:1]
	v_mad_i64_i32 v[2:3], s[12:13], v2, s23, v[64:65]
	global_load_dwordx2 v[36:37], v[2:3], off offset:16
	global_load_dwordx2 v[42:43], v[0:1], off offset:16
	global_load_dwordx4 v[32:35], v[2:3], off
	v_readlane_b32 s12, v106, 40
	v_readlane_b32 s13, v109, 40
	s_nop 0
	v_mov_b32_e32 v1, s12
	v_mov_b32_e32 v0, s13
	v_cndmask_b32_e64 v182, v0, v1, s[0:1]
	v_readlane_b32 s12, v106, 41
	v_readlane_b32 s13, v109, 41
	s_waitcnt vmcnt(14)
; DI void phase_peer_out(const Params& p, char* lds) {
;     ...
;       for (int k = 0; k < 8; ++k) {
;         const float c0 = __uint_as_float(__builtin_amdgcn_readlane(__float_as_uint(coefv[0]), kb * 8 + k)), c1 = __uint_as_float(__builtin_amdgcn_readlane(__float_as_uint(coefv[1]), kb * 8 + k));
;         const float cf = hb ? c1 : c0;
;         const f32x2 c2 = {cf, cf};
;         const v32f f = __builtin_amdgcn_cvt_scalef32_pk32_f32_fp6(qb[k], 1.0f);
; #pragma unroll
;         for (int i = 0; i < 16; ++i) o2[i] = f32x2{f[2 * i], f[2 * i + 1]} * c2 + o2[i];
	v_cvt_scalef32_pk32_f32_fp6 v[0:31], v[126:131], 1.0
	v_pk_fma_f32 v[126:127], v[0:1], v[182:183], v[150:151] op_sel_hi:[1,0,1]
	v_mov_b32_e32 v0, s13
	v_mov_b32_e32 v1, s12
	v_pk_fma_f32 v[128:129], v[2:3], v[182:183], v[152:153] op_sel_hi:[1,0,1]
	v_pk_fma_f32 v[130:131], v[4:5], v[182:183], v[154:155] op_sel_hi:[1,0,1]
	v_pk_fma_f32 v[150:151], v[6:7], v[182:183], v[156:157] op_sel_hi:[1,0,1]
	v_pk_fma_f32 v[152:153], v[8:9], v[182:183], v[158:159] op_sel_hi:[1,0,1]
	v_pk_fma_f32 v[154:155], v[10:11], v[182:183], v[160:161] op_sel_hi:[1,0,1]
	v_pk_fma_f32 v[156:157], v[12:13], v[182:183], v[162:163] op_sel_hi:[1,0,1]
	v_pk_fma_f32 v[158:159], v[14:15], v[182:183], v[164:165] op_sel_hi:[1,0,1]
	v_pk_fma_f32 v[160:161], v[16:17], v[182:183], v[166:167] op_sel_hi:[1,0,1]
	v_pk_fma_f32 v[162:163], v[18:19], v[182:183], v[168:169] op_sel_hi:[1,0,1]
	v_pk_fma_f32 v[164:165], v[20:21], v[182:183], v[170:171] op_sel_hi:[1,0,1]
	v_pk_fma_f32 v[166:167], v[22:23], v[182:183], v[172:173] op_sel_hi:[1,0,1]
	v_pk_fma_f32 v[168:169], v[24:25], v[182:183], v[174:175] op_sel_hi:[1,0,1]
	v_pk_fma_f32 v[170:171], v[26:27], v[182:183], v[176:177] op_sel_hi:[1,0,1]
	v_pk_fma_f32 v[172:173], v[28:29], v[182:183], v[178:179] op_sel_hi:[1,0,1]
	v_pk_fma_f32 v[174:175], v[30:31], v[182:183], v[180:181] op_sel_hi:[1,0,1]
	v_cndmask_b32_e64 v176, v0, v1, s[0:1]
	s_waitcnt vmcnt(12)
	v_cvt_scalef32_pk32_f32_fp6 v[0:31], v[132:137], 1.0
	v_readlane_b32 s12, v106, 42
	v_readlane_b32 s13, v109, 42
	v_pk_fma_f32 v[126:127], v[0:1], v[176:177], v[126:127] op_sel_hi:[1,0,1]
	v_mov_b32_e32 v1, s12
	v_mov_b32_e32 v0, s13
	v_pk_fma_f32 v[128:129], v[2:3], v[176:177], v[128:129] op_sel_hi:[1,0,1]
	v_pk_fma_f32 v[130:131], v[4:5], v[176:177], v[130:131] op_sel_hi:[1,0,1]
	v_pk_fma_f32 v[132:133], v[6:7], v[176:177], v[150:151] op_sel_hi:[1,0,1]
	v_pk_fma_f32 v[134:135], v[8:9], v[176:177], v[152:153] op_sel_hi:[1,0,1]
	v_pk_fma_f32 v[136:137], v[10:11], v[176:177], v[154:155] op_sel_hi:[1,0,1]
	v_pk_fma_f32 v[150:151], v[12:13], v[176:177], v[156:157] op_sel_hi:[1,0,1]
	v_pk_fma_f32 v[152:153], v[14:15], v[176:177], v[158:159] op_sel_hi:[1,0,1]
	v_pk_fma_f32 v[154:155], v[16:17], v[176:177], v[160:161] op_sel_hi:[1,0,1]
	v_pk_fma_f32 v[156:157], v[18:19], v[176:177], v[162:163] op_sel_hi:[1,0,1]
	v_pk_fma_f32 v[158:159], v[20:21], v[176:177], v[164:165] op_sel_hi:[1,0,1]
	v_pk_fma_f32 v[160:161], v[22:23], v[176:177], v[166:167] op_sel_hi:[1,0,1]
	v_pk_fma_f32 v[162:163], v[24:25], v[176:177], v[168:169] op_sel_hi:[1,0,1]
	v_pk_fma_f32 v[164:165], v[26:27], v[176:177], v[170:171] op_sel_hi:[1,0,1]
	v_pk_fma_f32 v[166:167], v[28:29], v[176:177], v[172:173] op_sel_hi:[1,0,1]
	v_pk_fma_f32 v[168:169], v[30:31], v[176:177], v[174:175] op_sel_hi:[1,0,1]
	v_cndmask_b32_e64 v170, v0, v1, s[0:1]
	s_waitcnt vmcnt(10)
	v_cvt_scalef32_pk32_f32_fp6 v[0:31], v[138:143], 1.0
	v_readlane_b32 s12, v106, 43
	v_readlane_b32 s13, v109, 43
	v_pk_fma_f32 v[126:127], v[0:1], v[170:171], v[126:127] op_sel_hi:[1,0,1]
	v_mov_b32_e32 v1, s12
	v_mov_b32_e32 v0, s13
	v_pk_fma_f32 v[128:129], v[2:3], v[170:171], v[128:129] op_sel_hi:[1,0,1]
	v_pk_fma_f32 v[130:131], v[4:5], v[170:171], v[130:131] op_sel_hi:[1,0,1]
	v_pk_fma_f32 v[132:133], v[6:7], v[170:171], v[132:133] op_sel_hi:[1,0,1]
	v_pk_fma_f32 v[134:135], v[8:9], v[170:171], v[134:135] op_sel_hi:[1,0,1]
	v_pk_fma_f32 v[136:137], v[10:11], v[170:171], v[136:137] op_sel_hi:[1,0,1]
	v_pk_fma_f32 v[138:139], v[12:13], v[170:171], v[150:151] op_sel_hi:[1,0,1]
	v_pk_fma_f32 v[140:141], v[14:15], v[170:171], v[152:153] op_sel_hi:[1,0,1]
	v_pk_fma_f32 v[142:143], v[16:17], v[170:171], v[154:155] op_sel_hi:[1,0,1]
	v_pk_fma_f32 v[150:151], v[18:19], v[170:171], v[156:157] op_sel_hi:[1,0,1]
	v_pk_fma_f32 v[152:153], v[20:21], v[170:171], v[158:159] op_sel_hi:[1,0,1]
	v_pk_fma_f32 v[154:155], v[22:23], v[170:171], v[160:161] op_sel_hi:[1,0,1]
	v_pk_fma_f32 v[156:157], v[24:25], v[170:171], v[162:163] op_sel_hi:[1,0,1]
	v_pk_fma_f32 v[158:159], v[26:27], v[170:171], v[164:165] op_sel_hi:[1,0,1]
	v_pk_fma_f32 v[160:161], v[28:29], v[170:171], v[166:167] op_sel_hi:[1,0,1]
	v_pk_fma_f32 v[162:163], v[30:31], v[170:171], v[168:169] op_sel_hi:[1,0,1]
	v_cndmask_b32_e64 v164, v0, v1, s[0:1]
	s_waitcnt vmcnt(8)
	v_cvt_scalef32_pk32_f32_fp6 v[0:31], v[144:149], 1.0
	v_readlane_b32 s12, v106, 44
	v_readlane_b32 s13, v109, 44
	v_pk_fma_f32 v[126:127], v[0:1], v[164:165], v[126:127] op_sel_hi:[1,0,1]
	v_mov_b32_e32 v1, s12
	v_mov_b32_e32 v0, s13
	v_pk_fma_f32 v[128:129], v[2:3], v[164:165], v[128:129] op_sel_hi:[1,0,1]
	v_pk_fma_f32 v[130:131], v[4:5], v[164:165], v[130:131] op_sel_hi:[1,0,1]
	v_pk_fma_f32 v[132:133], v[6:7], v[164:165], v[132:133] op_sel_hi:[1,0,1]
	v_pk_fma_f32 v[134:135], v[8:9], v[164:165], v[134:135] op_sel_hi:[1,0,1]
	v_pk_fma_f32 v[136:137], v[10:11], v[164:165], v[136:137] op_sel_hi:[1,0,1]
	v_pk_fma_f32 v[138:139], v[12:13], v[164:165], v[138:139] op_sel_hi:[1,0,1]
	v_pk_fma_f32 v[140:141], v[14:15], v[164:165], v[140:141] op_sel_hi:[1,0,1]
	v_pk_fma_f32 v[142:143], v[16:17], v[164:165], v[142:143] op_sel_hi:[1,0,1]
	v_pk_fma_f32 v[144:145], v[18:19], v[164:165], v[150:151] op_sel_hi:[1,0,1]
	v_pk_fma_f32 v[146:147], v[20:21], v[164:165], v[152:153] op_sel_hi:[1,0,1]
	v_pk_fma_f32 v[148:149], v[22:23], v[164:165], v[154:155] op_sel_hi:[1,0,1]
	v_pk_fma_f32 v[150:151], v[24:25], v[164:165], v[156:157] op_sel_hi:[1,0,1]
	v_pk_fma_f32 v[152:153], v[26:27], v[164:165], v[158:159] op_sel_hi:[1,0,1]
	v_pk_fma_f32 v[154:155], v[28:29], v[164:165], v[160:161] op_sel_hi:[1,0,1]
	v_pk_fma_f32 v[156:157], v[30:31], v[164:165], v[162:163] op_sel_hi:[1,0,1]
	v_cndmask_b32_e64 v158, v0, v1, s[0:1]
	s_waitcnt vmcnt(6)
; DI void phase_peer_out(const Params& p, char* lds) {
;     ...
;       for (int k = 0; k < 8; ++k) {
;         const float c0 = __uint_as_float(__builtin_amdgcn_readlane(__float_as_uint(coefv[0]), kb * 8 + k)), c1 = __uint_as_float(__builtin_amdgcn_readlane(__float_as_uint(coefv[1]), kb * 8 + k));
;         const float cf = hb ? c1 : c0;
;         const f32x2 c2 = {cf, cf};
;         const v32f f = __builtin_amdgcn_cvt_scalef32_pk32_f32_fp6(qb[k], 1.0f);
; #pragma unroll
;         for (int i = 0; i < 16; ++i) o2[i] = f32x2{f[2 * i], f[2 * i + 1]} * c2 + o2[i];
	v_cvt_scalef32_pk32_f32_fp6 v[0:31], v[50:55], 1.0
	v_readlane_b32 s12, v106, 45
	v_readlane_b32 s13, v109, 45
	v_pk_fma_f32 v[50:51], v[0:1], v[158:159], v[126:127] op_sel_hi:[1,0,1]
	v_mov_b32_e32 v1, s12
	v_mov_b32_e32 v0, s13
	v_pk_fma_f32 v[52:53], v[2:3], v[158:159], v[128:129] op_sel_hi:[1,0,1]
	v_pk_fma_f32 v[54:55], v[4:5], v[158:159], v[130:131] op_sel_hi:[1,0,1]
	v_pk_fma_f32 v[126:127], v[6:7], v[158:159], v[132:133] op_sel_hi:[1,0,1]
	v_pk_fma_f32 v[128:129], v[8:9], v[158:159], v[134:135] op_sel_hi:[1,0,1]
	v_pk_fma_f32 v[130:131], v[10:11], v[158:159], v[136:137] op_sel_hi:[1,0,1]
	v_pk_fma_f32 v[132:133], v[12:13], v[158:159], v[138:139] op_sel_hi:[1,0,1]
	v_pk_fma_f32 v[134:135], v[14:15], v[158:159], v[140:141] op_sel_hi:[1,0,1]
	v_pk_fma_f32 v[136:137], v[16:17], v[158:159], v[142:143] op_sel_hi:[1,0,1]
	v_pk_fma_f32 v[138:139], v[18:19], v[158:159], v[144:145] op_sel_hi:[1,0,1]
	v_pk_fma_f32 v[140:141], v[20:21], v[158:159], v[146:147] op_sel_hi:[1,0,1]
	v_pk_fma_f32 v[142:143], v[22:23], v[158:159], v[148:149] op_sel_hi:[1,0,1]
	v_pk_fma_f32 v[144:145], v[24:25], v[158:159], v[150:151] op_sel_hi:[1,0,1]
	v_pk_fma_f32 v[146:147], v[26:27], v[158:159], v[152:153] op_sel_hi:[1,0,1]
	v_pk_fma_f32 v[148:149], v[28:29], v[158:159], v[154:155] op_sel_hi:[1,0,1]
	v_pk_fma_f32 v[150:151], v[30:31], v[158:159], v[156:157] op_sel_hi:[1,0,1]
	v_cndmask_b32_e64 v152, v0, v1, s[0:1]
	s_waitcnt vmcnt(4)
	v_cvt_scalef32_pk32_f32_fp6 v[0:31], v[44:49], 1.0
	v_readlane_b32 s12, v106, 46
	v_readlane_b32 s13, v109, 46
	v_pk_fma_f32 v[44:45], v[0:1], v[152:153], v[50:51] op_sel_hi:[1,0,1]
	v_mov_b32_e32 v1, s12
	v_mov_b32_e32 v0, s13
	v_pk_fma_f32 v[46:47], v[2:3], v[152:153], v[52:53] op_sel_hi:[1,0,1]
	v_pk_fma_f32 v[48:49], v[4:5], v[152:153], v[54:55] op_sel_hi:[1,0,1]
	v_pk_fma_f32 v[50:51], v[6:7], v[152:153], v[126:127] op_sel_hi:[1,0,1]
	v_pk_fma_f32 v[52:53], v[8:9], v[152:153], v[128:129] op_sel_hi:[1,0,1]
	v_pk_fma_f32 v[54:55], v[10:11], v[152:153], v[130:131] op_sel_hi:[1,0,1]
	v_pk_fma_f32 v[126:127], v[12:13], v[152:153], v[132:133] op_sel_hi:[1,0,1]
	v_pk_fma_f32 v[128:129], v[14:15], v[152:153], v[134:135] op_sel_hi:[1,0,1]
	v_pk_fma_f32 v[130:131], v[16:17], v[152:153], v[136:137] op_sel_hi:[1,0,1]
	v_pk_fma_f32 v[132:133], v[18:19], v[152:153], v[138:139] op_sel_hi:[1,0,1]
	v_pk_fma_f32 v[134:135], v[20:21], v[152:153], v[140:141] op_sel_hi:[1,0,1]
	v_pk_fma_f32 v[136:137], v[22:23], v[152:153], v[142:143] op_sel_hi:[1,0,1]
	v_pk_fma_f32 v[138:139], v[24:25], v[152:153], v[144:145] op_sel_hi:[1,0,1]
	v_pk_fma_f32 v[140:141], v[26:27], v[152:153], v[146:147] op_sel_hi:[1,0,1]
	v_pk_fma_f32 v[142:143], v[28:29], v[152:153], v[148:149] op_sel_hi:[1,0,1]
	v_pk_fma_f32 v[144:145], v[30:31], v[152:153], v[150:151] op_sel_hi:[1,0,1]
	v_cndmask_b32_e64 v146, v0, v1, s[0:1]
	s_waitcnt vmcnt(1)
	v_cvt_scalef32_pk32_f32_fp6 v[0:31], v[38:43], 1.0
	v_readlane_b32 s12, v106, 47
	v_readlane_b32 s13, v109, 47
	v_pk_fma_f32 v[38:39], v[0:1], v[146:147], v[44:45] op_sel_hi:[1,0,1]
	v_mov_b32_e32 v1, s12
	v_mov_b32_e32 v0, s13
	v_readlane_b32 s12, v108, 48
	v_readlane_b32 s13, v107, 48
	v_pk_fma_f32 v[40:41], v[2:3], v[146:147], v[46:47] op_sel_hi:[1,0,1]
	v_pk_fma_f32 v[42:43], v[4:5], v[146:147], v[48:49] op_sel_hi:[1,0,1]
	v_pk_fma_f32 v[44:45], v[6:7], v[146:147], v[50:51] op_sel_hi:[1,0,1]
	v_pk_fma_f32 v[46:47], v[8:9], v[146:147], v[52:53] op_sel_hi:[1,0,1]
	v_pk_fma_f32 v[48:49], v[10:11], v[146:147], v[54:55] op_sel_hi:[1,0,1]
	v_pk_fma_f32 v[50:51], v[12:13], v[146:147], v[126:127] op_sel_hi:[1,0,1]
	v_pk_fma_f32 v[52:53], v[14:15], v[146:147], v[128:129] op_sel_hi:[1,0,1]
	v_pk_fma_f32 v[54:55], v[16:17], v[146:147], v[130:131] op_sel_hi:[1,0,1]
	v_pk_fma_f32 v[132:133], v[18:19], v[146:147], v[132:133] op_sel_hi:[1,0,1]
	v_pk_fma_f32 v[134:135], v[20:21], v[146:147], v[134:135] op_sel_hi:[1,0,1]
	v_pk_fma_f32 v[136:137], v[22:23], v[146:147], v[136:137] op_sel_hi:[1,0,1]
	v_pk_fma_f32 v[138:139], v[24:25], v[146:147], v[138:139] op_sel_hi:[1,0,1]
	v_pk_fma_f32 v[140:141], v[26:27], v[146:147], v[140:141] op_sel_hi:[1,0,1]
	v_pk_fma_f32 v[142:143], v[28:29], v[146:147], v[142:143] op_sel_hi:[1,0,1]
	v_pk_fma_f32 v[144:145], v[30:31], v[146:147], v[144:145] op_sel_hi:[1,0,1]
	v_cndmask_b32_e64 v146, v0, v1, s[0:1]
	v_mov_b32_e32 v0, s13
	v_mov_b32_e32 v1, s12
	v_cndmask_b32_e64 v0, v0, v1, s[0:1]
	v_mad_i64_i32 v[130:131], s[12:13], v0, s23, v[64:65]
	s_waitcnt vmcnt(0)
; DI void phase_peer_out(const Params& p, char* lds) {
;     ...
;     for (int kb = 0; kb < 8; ++kb) {
;       v6u qb[8];
; #pragma unroll
;       for (int k = 0; k < 8; ++k) {
;         const int e0 = __builtin_amdgcn_readlane(el[0], kb * 8 + k), e1 = __builtin_amdgcn_readlane(el[1], kb * 8 + k);
;         qb[k] = load6(V6 + (size_t)(hb ? e1 : e0) * 768);
;       }
; #pragma unroll
;       for (int k = 0; k < 8; ++k) {
;         const float c0 = __uint_as_float(__builtin_amdgcn_readlane(__float_as_uint(coefv[0]), kb * 8 + k)), c1 = __uint_as_float(__builtin_amdgcn_readlane(__float_as_uint(coefv[1]), kb * 8 + k));
;         const float cf = hb ? c1 : c0;
;         const f32x2 c2 = {cf, cf};
;         const v32f f = __builtin_amdgcn_cvt_scalef32_pk32_f32_fp6(qb[k], 1.0f);
; #pragma unroll
;         for (int i = 0; i < 16; ++i) o2[i] = f32x2{f[2 * i], f[2 * i + 1]} * c2 + o2[i];
	v_cvt_scalef32_pk32_f32_fp6 v[0:31], v[32:37], 1.0
	v_readlane_b32 s12, v108, 49
	v_readlane_b32 s13, v107, 49
	v_pk_fma_f32 v[150:151], v[0:1], v[146:147], v[38:39] op_sel_hi:[1,0,1]
	v_mov_b32_e32 v1, s12
	v_mov_b32_e32 v0, s13
	v_cndmask_b32_e64 v0, v0, v1, s[0:1]
	v_mad_i64_i32 v[0:1], s[12:13], v0, s23, v[64:65]
	v_readlane_b32 s12, v108, 50
	v_readlane_b32 s13, v107, 50
	global_load_dwordx4 v[126:129], v[130:131], off
	v_pk_fma_f32 v[168:169], v[18:19], v[146:147], v[132:133] op_sel_hi:[1,0,1]
	global_load_dwordx2 v[130:131], v[130:131], off offset:16
	v_pk_fma_f32 v[170:171], v[20:21], v[146:147], v[134:135] op_sel_hi:[1,0,1]
	v_pk_fma_f32 v[172:173], v[22:23], v[146:147], v[136:137] op_sel_hi:[1,0,1]
	global_load_dwordx2 v[136:137], v[0:1], off offset:16
	global_load_dwordx4 v[132:135], v[0:1], off
	v_mov_b32_e32 v0, s13
	v_mov_b32_e32 v1, s12
	v_cndmask_b32_e64 v0, v0, v1, s[0:1]
	v_mad_i64_i32 v[0:1], s[12:13], v0, s23, v[64:65]
	v_readlane_b32 s12, v108, 51
	v_readlane_b32 s13, v107, 51
	v_pk_fma_f32 v[152:153], v[2:3], v[146:147], v[40:41] op_sel_hi:[1,0,1]
	v_mov_b32_e32 v3, s12
	v_mov_b32_e32 v2, s13
	v_cndmask_b32_e64 v2, v2, v3, s[0:1]
	v_mad_i64_i32 v[2:3], s[12:13], v2, s23, v[64:65]
	v_readlane_b32 s12, v108, 52
	v_readlane_b32 s13, v107, 52
	v_pk_fma_f32 v[154:155], v[4:5], v[146:147], v[42:43] op_sel_hi:[1,0,1]
	v_pk_fma_f32 v[156:157], v[6:7], v[146:147], v[44:45] op_sel_hi:[1,0,1]
	v_pk_fma_f32 v[158:159], v[8:9], v[146:147], v[46:47] op_sel_hi:[1,0,1]
	v_pk_fma_f32 v[160:161], v[10:11], v[146:147], v[48:49] op_sel_hi:[1,0,1]
	v_pk_fma_f32 v[162:163], v[12:13], v[146:147], v[50:51] op_sel_hi:[1,0,1]
	v_pk_fma_f32 v[164:165], v[14:15], v[146:147], v[52:53] op_sel_hi:[1,0,1]
	v_pk_fma_f32 v[166:167], v[16:17], v[146:147], v[54:55] op_sel_hi:[1,0,1]
	v_pk_fma_f32 v[174:175], v[24:25], v[146:147], v[138:139] op_sel_hi:[1,0,1]
	v_pk_fma_f32 v[176:177], v[26:27], v[146:147], v[140:141] op_sel_hi:[1,0,1]
	v_pk_fma_f32 v[178:179], v[28:29], v[146:147], v[142:143] op_sel_hi:[1,0,1]
	v_pk_fma_f32 v[180:181], v[30:31], v[146:147], v[144:145] op_sel_hi:[1,0,1]
	global_load_dwordx4 v[138:141], v[0:1], off
	global_load_dwordx2 v[142:143], v[0:1], off offset:16
	global_load_dwordx4 v[144:147], v[2:3], off
	v_mov_b32_e32 v0, s13
	v_mov_b32_e32 v1, s12
	v_cndmask_b32_e64 v0, v0, v1, s[0:1]
	v_mad_i64_i32 v[0:1], s[12:13], v0, s23, v[64:65]
	v_readlane_b32 s12, v108, 53
	v_readlane_b32 s13, v107, 53
	global_load_dwordx2 v[148:149], v[2:3], off offset:16
	global_load_dwordx4 v[50:53], v[0:1], off
	v_mov_b32_e32 v2, s13
	v_mov_b32_e32 v3, s12
	v_cndmask_b32_e64 v2, v2, v3, s[0:1]
	v_mad_i64_i32 v[2:3], s[12:13], v2, s23, v[64:65]
	v_readlane_b32 s12, v108, 54
	v_readlane_b32 s13, v107, 54
	global_load_dwordx2 v[54:55], v[0:1], off offset:16
	global_load_dwordx4 v[44:47], v[2:3], off
	v_mov_b32_e32 v0, s13
	v_mov_b32_e32 v1, s12
	v_cndmask_b32_e64 v0, v0, v1, s[0:1]
	v_mad_i64_i32 v[0:1], s[12:13], v0, s23, v[64:65]
	v_readlane_b32 s12, v108, 55
	v_readlane_b32 s13, v107, 55
	global_load_dwordx2 v[48:49], v[2:3], off offset:16
	global_load_dwordx4 v[38:41], v[0:1], off
	v_mov_b32_e32 v2, s13
	v_mov_b32_e32 v3, s12
	v_cndmask_b32_e64 v2, v2, v3, s[0:1]
	v_mad_i64_i32 v[2:3], s[12:13], v2, s23, v[64:65]
	global_load_dwordx2 v[36:37], v[2:3], off offset:16
	global_load_dwordx2 v[42:43], v[0:1], off offset:16
	global_load_dwordx4 v[32:35], v[2:3], off
	v_readlane_b32 s12, v106, 48
	v_readlane_b32 s13, v109, 48
	s_nop 0
	v_mov_b32_e32 v1, s12
	v_mov_b32_e32 v0, s13
	v_cndmask_b32_e64 v182, v0, v1, s[0:1]
	v_readlane_b32 s12, v106, 49
	v_readlane_b32 s13, v109, 49
	s_waitcnt vmcnt(14)
	v_cvt_scalef32_pk32_f32_fp6 v[0:31], v[126:131], 1.0
	v_pk_fma_f32 v[126:127], v[0:1], v[182:183], v[150:151] op_sel_hi:[1,0,1]
	v_mov_b32_e32 v0, s13
	v_mov_b32_e32 v1, s12
	v_pk_fma_f32 v[128:129], v[2:3], v[182:183], v[152:153] op_sel_hi:[1,0,1]
	v_pk_fma_f32 v[130:131], v[4:5], v[182:183], v[154:155] op_sel_hi:[1,0,1]
	v_pk_fma_f32 v[150:151], v[6:7], v[182:183], v[156:157] op_sel_hi:[1,0,1]
	v_pk_fma_f32 v[152:153], v[8:9], v[182:183], v[158:159] op_sel_hi:[1,0,1]
	v_pk_fma_f32 v[154:155], v[10:11], v[182:183], v[160:161] op_sel_hi:[1,0,1]
	v_pk_fma_f32 v[156:157], v[12:13], v[182:183], v[162:163] op_sel_hi:[1,0,1]
	v_pk_fma_f32 v[158:159], v[14:15], v[182:183], v[164:165] op_sel_hi:[1,0,1]
	v_pk_fma_f32 v[160:161], v[16:17], v[182:183], v[166:167] op_sel_hi:[1,0,1]
	v_pk_fma_f32 v[162:163], v[18:19], v[182:183], v[168:169] op_sel_hi:[1,0,1]
	v_pk_fma_f32 v[164:165], v[20:21], v[182:183], v[170:171] op_sel_hi:[1,0,1]
	v_pk_fma_f32 v[166:167], v[22:23], v[182:183], v[172:173] op_sel_hi:[1,0,1]
	v_pk_fma_f32 v[168:169], v[24:25], v[182:183], v[174:175] op_sel_hi:[1,0,1]
	v_pk_fma_f32 v[170:171], v[26:27], v[182:183], v[176:177] op_sel_hi:[1,0,1]
	v_pk_fma_f32 v[172:173], v[28:29], v[182:183], v[178:179] op_sel_hi:[1,0,1]
	v_pk_fma_f32 v[174:175], v[30:31], v[182:183], v[180:181] op_sel_hi:[1,0,1]
	v_cndmask_b32_e64 v176, v0, v1, s[0:1]
	s_waitcnt vmcnt(12)
; DI void phase_peer_out(const Params& p, char* lds) {
;     ...
;       for (int k = 0; k < 8; ++k) {
;         const float c0 = __uint_as_float(__builtin_amdgcn_readlane(__float_as_uint(coefv[0]), kb * 8 + k)), c1 = __uint_as_float(__builtin_amdgcn_readlane(__float_as_uint(coefv[1]), kb * 8 + k));
;         const float cf = hb ? c1 : c0;
;         const f32x2 c2 = {cf, cf};
;         const v32f f = __builtin_amdgcn_cvt_scalef32_pk32_f32_fp6(qb[k], 1.0f);
; #pragma unroll
;         for (int i = 0; i < 16; ++i) o2[i] = f32x2{f[2 * i], f[2 * i + 1]} * c2 + o2[i];
	v_cvt_scalef32_pk32_f32_fp6 v[0:31], v[132:137], 1.0
	v_readlane_b32 s12, v106, 50
	v_readlane_b32 s13, v109, 50
	v_pk_fma_f32 v[126:127], v[0:1], v[176:177], v[126:127] op_sel_hi:[1,0,1]
	v_mov_b32_e32 v1, s12
	v_mov_b32_e32 v0, s13
	v_pk_fma_f32 v[128:129], v[2:3], v[176:177], v[128:129] op_sel_hi:[1,0,1]
	v_pk_fma_f32 v[130:131], v[4:5], v[176:177], v[130:131] op_sel_hi:[1,0,1]
	v_pk_fma_f32 v[132:133], v[6:7], v[176:177], v[150:151] op_sel_hi:[1,0,1]
	v_pk_fma_f32 v[134:135], v[8:9], v[176:177], v[152:153] op_sel_hi:[1,0,1]
	v_pk_fma_f32 v[136:137], v[10:11], v[176:177], v[154:155] op_sel_hi:[1,0,1]
	v_pk_fma_f32 v[150:151], v[12:13], v[176:177], v[156:157] op_sel_hi:[1,0,1]
	v_pk_fma_f32 v[152:153], v[14:15], v[176:177], v[158:159] op_sel_hi:[1,0,1]
	v_pk_fma_f32 v[154:155], v[16:17], v[176:177], v[160:161] op_sel_hi:[1,0,1]
	v_pk_fma_f32 v[156:157], v[18:19], v[176:177], v[162:163] op_sel_hi:[1,0,1]
	v_pk_fma_f32 v[158:159], v[20:21], v[176:177], v[164:165] op_sel_hi:[1,0,1]
	v_pk_fma_f32 v[160:161], v[22:23], v[176:177], v[166:167] op_sel_hi:[1,0,1]
	v_pk_fma_f32 v[162:163], v[24:25], v[176:177], v[168:169] op_sel_hi:[1,0,1]
	v_pk_fma_f32 v[164:165], v[26:27], v[176:177], v[170:171] op_sel_hi:[1,0,1]
	v_pk_fma_f32 v[166:167], v[28:29], v[176:177], v[172:173] op_sel_hi:[1,0,1]
	v_pk_fma_f32 v[168:169], v[30:31], v[176:177], v[174:175] op_sel_hi:[1,0,1]
	v_cndmask_b32_e64 v170, v0, v1, s[0:1]
	s_waitcnt vmcnt(10)
	v_cvt_scalef32_pk32_f32_fp6 v[0:31], v[138:143], 1.0
	v_readlane_b32 s12, v106, 51
	v_readlane_b32 s13, v109, 51
	v_pk_fma_f32 v[126:127], v[0:1], v[170:171], v[126:127] op_sel_hi:[1,0,1]
	v_mov_b32_e32 v1, s12
	v_mov_b32_e32 v0, s13
	v_pk_fma_f32 v[128:129], v[2:3], v[170:171], v[128:129] op_sel_hi:[1,0,1]
	v_pk_fma_f32 v[130:131], v[4:5], v[170:171], v[130:131] op_sel_hi:[1,0,1]
	v_pk_fma_f32 v[132:133], v[6:7], v[170:171], v[132:133] op_sel_hi:[1,0,1]
	v_pk_fma_f32 v[134:135], v[8:9], v[170:171], v[134:135] op_sel_hi:[1,0,1]
	v_pk_fma_f32 v[136:137], v[10:11], v[170:171], v[136:137] op_sel_hi:[1,0,1]
	v_pk_fma_f32 v[138:139], v[12:13], v[170:171], v[150:151] op_sel_hi:[1,0,1]
	v_pk_fma_f32 v[140:141], v[14:15], v[170:171], v[152:153] op_sel_hi:[1,0,1]
	v_pk_fma_f32 v[142:143], v[16:17], v[170:171], v[154:155] op_sel_hi:[1,0,1]
	v_pk_fma_f32 v[150:151], v[18:19], v[170:171], v[156:157] op_sel_hi:[1,0,1]
	v_pk_fma_f32 v[152:153], v[20:21], v[170:171], v[158:159] op_sel_hi:[1,0,1]
	v_pk_fma_f32 v[154:155], v[22:23], v[170:171], v[160:161] op_sel_hi:[1,0,1]
	v_pk_fma_f32 v[156:157], v[24:25], v[170:171], v[162:163] op_sel_hi:[1,0,1]
	v_pk_fma_f32 v[158:159], v[26:27], v[170:171], v[164:165] op_sel_hi:[1,0,1]
	v_pk_fma_f32 v[160:161], v[28:29], v[170:171], v[166:167] op_sel_hi:[1,0,1]
	v_pk_fma_f32 v[162:163], v[30:31], v[170:171], v[168:169] op_sel_hi:[1,0,1]
	v_cndmask_b32_e64 v164, v0, v1, s[0:1]
	s_waitcnt vmcnt(8)
	v_cvt_scalef32_pk32_f32_fp6 v[0:31], v[144:149], 1.0
	v_readlane_b32 s12, v106, 52
	v_readlane_b32 s13, v109, 52
	v_pk_fma_f32 v[126:127], v[0:1], v[164:165], v[126:127] op_sel_hi:[1,0,1]
	v_mov_b32_e32 v1, s12
	v_mov_b32_e32 v0, s13
	v_pk_fma_f32 v[128:129], v[2:3], v[164:165], v[128:129] op_sel_hi:[1,0,1]
	v_pk_fma_f32 v[130:131], v[4:5], v[164:165], v[130:131] op_sel_hi:[1,0,1]
	v_pk_fma_f32 v[132:133], v[6:7], v[164:165], v[132:133] op_sel_hi:[1,0,1]
	v_pk_fma_f32 v[134:135], v[8:9], v[164:165], v[134:135] op_sel_hi:[1,0,1]
	v_pk_fma_f32 v[136:137], v[10:11], v[164:165], v[136:137] op_sel_hi:[1,0,1]
	v_pk_fma_f32 v[138:139], v[12:13], v[164:165], v[138:139] op_sel_hi:[1,0,1]
	v_pk_fma_f32 v[140:141], v[14:15], v[164:165], v[140:141] op_sel_hi:[1,0,1]
	v_pk_fma_f32 v[142:143], v[16:17], v[164:165], v[142:143] op_sel_hi:[1,0,1]
	v_pk_fma_f32 v[144:145], v[18:19], v[164:165], v[150:151] op_sel_hi:[1,0,1]
	v_pk_fma_f32 v[146:147], v[20:21], v[164:165], v[152:153] op_sel_hi:[1,0,1]
	v_pk_fma_f32 v[148:149], v[22:23], v[164:165], v[154:155] op_sel_hi:[1,0,1]
	v_pk_fma_f32 v[150:151], v[24:25], v[164:165], v[156:157] op_sel_hi:[1,0,1]
	v_pk_fma_f32 v[152:153], v[26:27], v[164:165], v[158:159] op_sel_hi:[1,0,1]
	v_pk_fma_f32 v[154:155], v[28:29], v[164:165], v[160:161] op_sel_hi:[1,0,1]
	v_pk_fma_f32 v[156:157], v[30:31], v[164:165], v[162:163] op_sel_hi:[1,0,1]
	v_cndmask_b32_e64 v158, v0, v1, s[0:1]
	s_waitcnt vmcnt(6)
	v_cvt_scalef32_pk32_f32_fp6 v[0:31], v[50:55], 1.0
	v_readlane_b32 s12, v106, 53
	v_readlane_b32 s13, v109, 53
	v_pk_fma_f32 v[50:51], v[0:1], v[158:159], v[126:127] op_sel_hi:[1,0,1]
	v_mov_b32_e32 v1, s12
	v_mov_b32_e32 v0, s13
	v_pk_fma_f32 v[52:53], v[2:3], v[158:159], v[128:129] op_sel_hi:[1,0,1]
	v_pk_fma_f32 v[54:55], v[4:5], v[158:159], v[130:131] op_sel_hi:[1,0,1]
	v_pk_fma_f32 v[126:127], v[6:7], v[158:159], v[132:133] op_sel_hi:[1,0,1]
	v_pk_fma_f32 v[128:129], v[8:9], v[158:159], v[134:135] op_sel_hi:[1,0,1]
	v_pk_fma_f32 v[130:131], v[10:11], v[158:159], v[136:137] op_sel_hi:[1,0,1]
	v_pk_fma_f32 v[132:133], v[12:13], v[158:159], v[138:139] op_sel_hi:[1,0,1]
	v_pk_fma_f32 v[134:135], v[14:15], v[158:159], v[140:141] op_sel_hi:[1,0,1]
	v_pk_fma_f32 v[136:137], v[16:17], v[158:159], v[142:143] op_sel_hi:[1,0,1]
	v_pk_fma_f32 v[138:139], v[18:19], v[158:159], v[144:145] op_sel_hi:[1,0,1]
	v_pk_fma_f32 v[140:141], v[20:21], v[158:159], v[146:147] op_sel_hi:[1,0,1]
	v_pk_fma_f32 v[142:143], v[22:23], v[158:159], v[148:149] op_sel_hi:[1,0,1]
	v_pk_fma_f32 v[144:145], v[24:25], v[158:159], v[150:151] op_sel_hi:[1,0,1]
	v_pk_fma_f32 v[146:147], v[26:27], v[158:159], v[152:153] op_sel_hi:[1,0,1]
	v_pk_fma_f32 v[148:149], v[28:29], v[158:159], v[154:155] op_sel_hi:[1,0,1]
	v_pk_fma_f32 v[150:151], v[30:31], v[158:159], v[156:157] op_sel_hi:[1,0,1]
	v_cndmask_b32_e64 v152, v0, v1, s[0:1]
	s_waitcnt vmcnt(4)
; DI void phase_peer_out(const Params& p, char* lds) {
;     ...
;     for (int kb = 0; kb < 8; ++kb) {
;       v6u qb[8];
; #pragma unroll
;       for (int k = 0; k < 8; ++k) {
;         const int e0 = __builtin_amdgcn_readlane(el[0], kb * 8 + k), e1 = __builtin_amdgcn_readlane(el[1], kb * 8 + k);
;         qb[k] = load6(V6 + (size_t)(hb ? e1 : e0) * 768);
;       }
; #pragma unroll
;       for (int k = 0; k < 8; ++k) {
;         const float c0 = __uint_as_float(__builtin_amdgcn_readlane(__float_as_uint(coefv[0]), kb * 8 + k)), c1 = __uint_as_float(__builtin_amdgcn_readlane(__float_as_uint(coefv[1]), kb * 8 + k));
;         const float cf = hb ? c1 : c0;
;         const f32x2 c2 = {cf, cf};
;         const v32f f = __builtin_amdgcn_cvt_scalef32_pk32_f32_fp6(qb[k], 1.0f);
; #pragma unroll
;         for (int i = 0; i < 16; ++i) o2[i] = f32x2{f[2 * i], f[2 * i + 1]} * c2 + o2[i];
	v_cvt_scalef32_pk32_f32_fp6 v[0:31], v[44:49], 1.0
	v_readlane_b32 s12, v106, 54
	v_readlane_b32 s13, v109, 54
	v_pk_fma_f32 v[44:45], v[0:1], v[152:153], v[50:51] op_sel_hi:[1,0,1]
	v_mov_b32_e32 v1, s12
	v_mov_b32_e32 v0, s13
	v_pk_fma_f32 v[46:47], v[2:3], v[152:153], v[52:53] op_sel_hi:[1,0,1]
	v_pk_fma_f32 v[48:49], v[4:5], v[152:153], v[54:55] op_sel_hi:[1,0,1]
	v_pk_fma_f32 v[50:51], v[6:7], v[152:153], v[126:127] op_sel_hi:[1,0,1]
	v_pk_fma_f32 v[52:53], v[8:9], v[152:153], v[128:129] op_sel_hi:[1,0,1]
	v_pk_fma_f32 v[54:55], v[10:11], v[152:153], v[130:131] op_sel_hi:[1,0,1]
	v_pk_fma_f32 v[126:127], v[12:13], v[152:153], v[132:133] op_sel_hi:[1,0,1]
	v_pk_fma_f32 v[128:129], v[14:15], v[152:153], v[134:135] op_sel_hi:[1,0,1]
	v_pk_fma_f32 v[130:131], v[16:17], v[152:153], v[136:137] op_sel_hi:[1,0,1]
	v_pk_fma_f32 v[132:133], v[18:19], v[152:153], v[138:139] op_sel_hi:[1,0,1]
	v_pk_fma_f32 v[134:135], v[20:21], v[152:153], v[140:141] op_sel_hi:[1,0,1]
	v_pk_fma_f32 v[136:137], v[22:23], v[152:153], v[142:143] op_sel_hi:[1,0,1]
	v_pk_fma_f32 v[138:139], v[24:25], v[152:153], v[144:145] op_sel_hi:[1,0,1]
	v_pk_fma_f32 v[140:141], v[26:27], v[152:153], v[146:147] op_sel_hi:[1,0,1]
	v_pk_fma_f32 v[142:143], v[28:29], v[152:153], v[148:149] op_sel_hi:[1,0,1]
	v_pk_fma_f32 v[144:145], v[30:31], v[152:153], v[150:151] op_sel_hi:[1,0,1]
	v_cndmask_b32_e64 v146, v0, v1, s[0:1]
	s_waitcnt vmcnt(1)
	v_cvt_scalef32_pk32_f32_fp6 v[0:31], v[38:43], 1.0
	v_readlane_b32 s12, v106, 55
	v_readlane_b32 s13, v109, 55
	v_pk_fma_f32 v[38:39], v[0:1], v[146:147], v[44:45] op_sel_hi:[1,0,1]
	v_mov_b32_e32 v1, s12
	v_mov_b32_e32 v0, s13
	v_readlane_b32 s12, v108, 56
	v_readlane_b32 s13, v107, 56
	v_pk_fma_f32 v[40:41], v[2:3], v[146:147], v[46:47] op_sel_hi:[1,0,1]
	v_pk_fma_f32 v[42:43], v[4:5], v[146:147], v[48:49] op_sel_hi:[1,0,1]
	v_pk_fma_f32 v[44:45], v[6:7], v[146:147], v[50:51] op_sel_hi:[1,0,1]
	v_pk_fma_f32 v[46:47], v[8:9], v[146:147], v[52:53] op_sel_hi:[1,0,1]
	v_pk_fma_f32 v[48:49], v[10:11], v[146:147], v[54:55] op_sel_hi:[1,0,1]
	v_pk_fma_f32 v[50:51], v[12:13], v[146:147], v[126:127] op_sel_hi:[1,0,1]
	v_pk_fma_f32 v[52:53], v[14:15], v[146:147], v[128:129] op_sel_hi:[1,0,1]
	v_pk_fma_f32 v[54:55], v[16:17], v[146:147], v[130:131] op_sel_hi:[1,0,1]
	v_pk_fma_f32 v[132:133], v[18:19], v[146:147], v[132:133] op_sel_hi:[1,0,1]
	v_pk_fma_f32 v[134:135], v[20:21], v[146:147], v[134:135] op_sel_hi:[1,0,1]
	v_pk_fma_f32 v[136:137], v[22:23], v[146:147], v[136:137] op_sel_hi:[1,0,1]
	v_pk_fma_f32 v[138:139], v[24:25], v[146:147], v[138:139] op_sel_hi:[1,0,1]
	v_pk_fma_f32 v[140:141], v[26:27], v[146:147], v[140:141] op_sel_hi:[1,0,1]
	v_pk_fma_f32 v[142:143], v[28:29], v[146:147], v[142:143] op_sel_hi:[1,0,1]
	v_pk_fma_f32 v[144:145], v[30:31], v[146:147], v[144:145] op_sel_hi:[1,0,1]
	v_cndmask_b32_e64 v146, v0, v1, s[0:1]
	v_mov_b32_e32 v0, s13
	v_mov_b32_e32 v1, s12
	v_cndmask_b32_e64 v0, v0, v1, s[0:1]
	v_mad_i64_i32 v[130:131], s[12:13], v0, s23, v[64:65]
	s_waitcnt vmcnt(0)
	v_cvt_scalef32_pk32_f32_fp6 v[0:31], v[32:37], 1.0
	v_readlane_b32 s12, v108, 57
	v_readlane_b32 s13, v107, 57
	v_pk_fma_f32 v[150:151], v[0:1], v[146:147], v[38:39] op_sel_hi:[1,0,1]
	v_mov_b32_e32 v1, s12
	v_mov_b32_e32 v0, s13
	v_cndmask_b32_e64 v0, v0, v1, s[0:1]
	v_mad_i64_i32 v[0:1], s[12:13], v0, s23, v[64:65]
	v_readlane_b32 s12, v108, 58
	v_readlane_b32 s13, v107, 58
	global_load_dwordx4 v[126:129], v[130:131], off
	v_pk_fma_f32 v[168:169], v[18:19], v[146:147], v[132:133] op_sel_hi:[1,0,1]
	global_load_dwordx2 v[130:131], v[130:131], off offset:16
	v_pk_fma_f32 v[170:171], v[20:21], v[146:147], v[134:135] op_sel_hi:[1,0,1]
	v_pk_fma_f32 v[172:173], v[22:23], v[146:147], v[136:137] op_sel_hi:[1,0,1]
	global_load_dwordx2 v[136:137], v[0:1], off offset:16
	global_load_dwordx4 v[132:135], v[0:1], off
	v_mov_b32_e32 v0, s13
	v_mov_b32_e32 v1, s12
	v_cndmask_b32_e64 v0, v0, v1, s[0:1]
	v_mad_i64_i32 v[0:1], s[12:13], v0, s23, v[64:65]
	v_readlane_b32 s12, v108, 59
	v_readlane_b32 s13, v107, 59
	v_pk_fma_f32 v[152:153], v[2:3], v[146:147], v[40:41] op_sel_hi:[1,0,1]
	v_mov_b32_e32 v3, s12
	v_mov_b32_e32 v2, s13
	v_cndmask_b32_e64 v2, v2, v3, s[0:1]
	v_mad_i64_i32 v[2:3], s[12:13], v2, s23, v[64:65]
	v_readlane_b32 s12, v108, 60
	v_readlane_b32 s13, v107, 60
	v_pk_fma_f32 v[154:155], v[4:5], v[146:147], v[42:43] op_sel_hi:[1,0,1]
	v_pk_fma_f32 v[156:157], v[6:7], v[146:147], v[44:45] op_sel_hi:[1,0,1]
	v_pk_fma_f32 v[158:159], v[8:9], v[146:147], v[46:47] op_sel_hi:[1,0,1]
	v_pk_fma_f32 v[160:161], v[10:11], v[146:147], v[48:49] op_sel_hi:[1,0,1]
	v_pk_fma_f32 v[162:163], v[12:13], v[146:147], v[50:51] op_sel_hi:[1,0,1]
	v_pk_fma_f32 v[164:165], v[14:15], v[146:147], v[52:53] op_sel_hi:[1,0,1]
	v_pk_fma_f32 v[166:167], v[16:17], v[146:147], v[54:55] op_sel_hi:[1,0,1]
	v_pk_fma_f32 v[174:175], v[24:25], v[146:147], v[138:139] op_sel_hi:[1,0,1]
	v_pk_fma_f32 v[176:177], v[26:27], v[146:147], v[140:141] op_sel_hi:[1,0,1]
	v_pk_fma_f32 v[178:179], v[28:29], v[146:147], v[142:143] op_sel_hi:[1,0,1]
	v_pk_fma_f32 v[180:181], v[30:31], v[146:147], v[144:145] op_sel_hi:[1,0,1]
	global_load_dwordx4 v[138:141], v[0:1], off
	global_load_dwordx2 v[142:143], v[0:1], off offset:16
	global_load_dwordx4 v[144:147], v[2:3], off
	v_mov_b32_e32 v0, s13
	v_mov_b32_e32 v1, s12
	v_cndmask_b32_e64 v0, v0, v1, s[0:1]
	v_mad_i64_i32 v[0:1], s[12:13], v0, s23, v[64:65]
	v_readlane_b32 s12, v108, 61
	v_readlane_b32 s13, v107, 61
	global_load_dwordx2 v[148:149], v[2:3], off offset:16
	global_load_dwordx4 v[50:53], v[0:1], off
	v_mov_b32_e32 v2, s13
	v_mov_b32_e32 v3, s12
	v_cndmask_b32_e64 v2, v2, v3, s[0:1]
	v_mad_i64_i32 v[2:3], s[12:13], v2, s23, v[64:65]
	v_readlane_b32 s12, v108, 62
	v_readlane_b32 s13, v107, 62
	global_load_dwordx2 v[54:55], v[0:1], off offset:16
	global_load_dwordx4 v[44:47], v[2:3], off
	v_mov_b32_e32 v0, s13
	v_mov_b32_e32 v1, s12
	v_cndmask_b32_e64 v0, v0, v1, s[0:1]
	v_mad_i64_i32 v[0:1], s[12:13], v0, s23, v[64:65]
	v_readlane_b32 s12, v108, 63
	v_readlane_b32 s13, v107, 63
	global_load_dwordx2 v[48:49], v[2:3], off offset:16
	global_load_dwordx4 v[38:41], v[0:1], off
	v_mov_b32_e32 v2, s13
	v_mov_b32_e32 v3, s12
	v_cndmask_b32_e64 v2, v2, v3, s[0:1]
	v_mad_i64_i32 v[2:3], s[12:13], v2, s23, v[64:65]
	global_load_dwordx2 v[36:37], v[2:3], off offset:16
	global_load_dwordx2 v[42:43], v[0:1], off offset:16
	global_load_dwordx4 v[32:35], v[2:3], off
	v_readlane_b32 s12, v106, 56
	v_readlane_b32 s13, v109, 56
	s_nop 0
	v_mov_b32_e32 v1, s12
	v_mov_b32_e32 v0, s13
	v_cndmask_b32_e64 v108, v0, v1, s[0:1]
	v_readlane_b32 s12, v106, 57
	v_readlane_b32 s13, v109, 57
	s_waitcnt vmcnt(14)
; DI void phase_peer_out(const Params& p, char* lds) {
;     ...
;       for (int k = 0; k < 8; ++k) {
;         const float c0 = __uint_as_float(__builtin_amdgcn_readlane(__float_as_uint(coefv[0]), kb * 8 + k)), c1 = __uint_as_float(__builtin_amdgcn_readlane(__float_as_uint(coefv[1]), kb * 8 + k));
;         const float cf = hb ? c1 : c0;
;         const f32x2 c2 = {cf, cf};
;         const v32f f = __builtin_amdgcn_cvt_scalef32_pk32_f32_fp6(qb[k], 1.0f);
; #pragma unroll
;         for (int i = 0; i < 16; ++i) o2[i] = f32x2{f[2 * i], f[2 * i + 1]} * c2 + o2[i];
	v_cvt_scalef32_pk32_f32_fp6 v[0:31], v[126:131], 1.0
	v_pk_fma_f32 v[126:127], v[0:1], v[108:109], v[150:151] op_sel_hi:[1,0,1]
	v_mov_b32_e32 v0, s13
	v_mov_b32_e32 v1, s12
	v_pk_fma_f32 v[128:129], v[2:3], v[108:109], v[152:153] op_sel_hi:[1,0,1]
	v_pk_fma_f32 v[130:131], v[4:5], v[108:109], v[154:155] op_sel_hi:[1,0,1]
	v_pk_fma_f32 v[150:151], v[6:7], v[108:109], v[156:157] op_sel_hi:[1,0,1]
	v_pk_fma_f32 v[152:153], v[8:9], v[108:109], v[158:159] op_sel_hi:[1,0,1]
	v_pk_fma_f32 v[154:155], v[10:11], v[108:109], v[160:161] op_sel_hi:[1,0,1]
	v_pk_fma_f32 v[156:157], v[12:13], v[108:109], v[162:163] op_sel_hi:[1,0,1]
	v_pk_fma_f32 v[158:159], v[14:15], v[108:109], v[164:165] op_sel_hi:[1,0,1]
	v_pk_fma_f32 v[160:161], v[16:17], v[108:109], v[166:167] op_sel_hi:[1,0,1]
	v_pk_fma_f32 v[162:163], v[18:19], v[108:109], v[168:169] op_sel_hi:[1,0,1]
	v_pk_fma_f32 v[164:165], v[20:21], v[108:109], v[170:171] op_sel_hi:[1,0,1]
	v_pk_fma_f32 v[166:167], v[22:23], v[108:109], v[172:173] op_sel_hi:[1,0,1]
	v_pk_fma_f32 v[168:169], v[24:25], v[108:109], v[174:175] op_sel_hi:[1,0,1]
	v_pk_fma_f32 v[170:171], v[26:27], v[108:109], v[176:177] op_sel_hi:[1,0,1]
	v_pk_fma_f32 v[172:173], v[28:29], v[108:109], v[178:179] op_sel_hi:[1,0,1]
	v_pk_fma_f32 v[174:175], v[30:31], v[108:109], v[180:181] op_sel_hi:[1,0,1]
	v_cndmask_b32_e64 v108, v0, v1, s[0:1]
	s_waitcnt vmcnt(12)
	v_cvt_scalef32_pk32_f32_fp6 v[0:31], v[132:137], 1.0
	v_readlane_b32 s12, v106, 58
	v_readlane_b32 s13, v109, 58
	v_pk_fma_f32 v[126:127], v[0:1], v[108:109], v[126:127] op_sel_hi:[1,0,1]
	v_mov_b32_e32 v1, s12
	v_mov_b32_e32 v0, s13
	v_pk_fma_f32 v[128:129], v[2:3], v[108:109], v[128:129] op_sel_hi:[1,0,1]
	v_pk_fma_f32 v[130:131], v[4:5], v[108:109], v[130:131] op_sel_hi:[1,0,1]
	v_pk_fma_f32 v[132:133], v[6:7], v[108:109], v[150:151] op_sel_hi:[1,0,1]
	v_pk_fma_f32 v[134:135], v[8:9], v[108:109], v[152:153] op_sel_hi:[1,0,1]
	v_pk_fma_f32 v[136:137], v[10:11], v[108:109], v[154:155] op_sel_hi:[1,0,1]
	v_pk_fma_f32 v[150:151], v[12:13], v[108:109], v[156:157] op_sel_hi:[1,0,1]
	v_pk_fma_f32 v[152:153], v[14:15], v[108:109], v[158:159] op_sel_hi:[1,0,1]
	v_pk_fma_f32 v[154:155], v[16:17], v[108:109], v[160:161] op_sel_hi:[1,0,1]
	v_pk_fma_f32 v[156:157], v[18:19], v[108:109], v[162:163] op_sel_hi:[1,0,1]
	v_pk_fma_f32 v[158:159], v[20:21], v[108:109], v[164:165] op_sel_hi:[1,0,1]
	v_pk_fma_f32 v[160:161], v[22:23], v[108:109], v[166:167] op_sel_hi:[1,0,1]
	v_pk_fma_f32 v[162:163], v[24:25], v[108:109], v[168:169] op_sel_hi:[1,0,1]
	v_pk_fma_f32 v[164:165], v[26:27], v[108:109], v[170:171] op_sel_hi:[1,0,1]
	v_pk_fma_f32 v[166:167], v[28:29], v[108:109], v[172:173] op_sel_hi:[1,0,1]
	v_pk_fma_f32 v[168:169], v[30:31], v[108:109], v[174:175] op_sel_hi:[1,0,1]
	v_cndmask_b32_e64 v108, v0, v1, s[0:1]
	s_waitcnt vmcnt(10)
	v_cvt_scalef32_pk32_f32_fp6 v[0:31], v[138:143], 1.0
	v_readlane_b32 s12, v106, 59
	v_readlane_b32 s13, v109, 59
	v_pk_fma_f32 v[126:127], v[0:1], v[108:109], v[126:127] op_sel_hi:[1,0,1]
	v_mov_b32_e32 v1, s12
	v_mov_b32_e32 v0, s13
	v_pk_fma_f32 v[128:129], v[2:3], v[108:109], v[128:129] op_sel_hi:[1,0,1]
	v_pk_fma_f32 v[130:131], v[4:5], v[108:109], v[130:131] op_sel_hi:[1,0,1]
	v_pk_fma_f32 v[132:133], v[6:7], v[108:109], v[132:133] op_sel_hi:[1,0,1]
	v_pk_fma_f32 v[134:135], v[8:9], v[108:109], v[134:135] op_sel_hi:[1,0,1]
	v_pk_fma_f32 v[136:137], v[10:11], v[108:109], v[136:137] op_sel_hi:[1,0,1]
	v_pk_fma_f32 v[138:139], v[12:13], v[108:109], v[150:151] op_sel_hi:[1,0,1]
	v_pk_fma_f32 v[140:141], v[14:15], v[108:109], v[152:153] op_sel_hi:[1,0,1]
	v_pk_fma_f32 v[142:143], v[16:17], v[108:109], v[154:155] op_sel_hi:[1,0,1]
	v_pk_fma_f32 v[150:151], v[18:19], v[108:109], v[156:157] op_sel_hi:[1,0,1]
	v_pk_fma_f32 v[152:153], v[20:21], v[108:109], v[158:159] op_sel_hi:[1,0,1]
	v_pk_fma_f32 v[154:155], v[22:23], v[108:109], v[160:161] op_sel_hi:[1,0,1]
	v_pk_fma_f32 v[156:157], v[24:25], v[108:109], v[162:163] op_sel_hi:[1,0,1]
	v_pk_fma_f32 v[158:159], v[26:27], v[108:109], v[164:165] op_sel_hi:[1,0,1]
	v_pk_fma_f32 v[160:161], v[28:29], v[108:109], v[166:167] op_sel_hi:[1,0,1]
	v_pk_fma_f32 v[162:163], v[30:31], v[108:109], v[168:169] op_sel_hi:[1,0,1]
	v_cndmask_b32_e64 v108, v0, v1, s[0:1]
	s_waitcnt vmcnt(8)
	v_cvt_scalef32_pk32_f32_fp6 v[0:31], v[144:149], 1.0
	v_readlane_b32 s12, v106, 60
	v_readlane_b32 s13, v109, 60
	v_pk_fma_f32 v[126:127], v[0:1], v[108:109], v[126:127] op_sel_hi:[1,0,1]
	v_mov_b32_e32 v1, s12
	v_mov_b32_e32 v0, s13
	v_pk_fma_f32 v[128:129], v[2:3], v[108:109], v[128:129] op_sel_hi:[1,0,1]
	v_pk_fma_f32 v[130:131], v[4:5], v[108:109], v[130:131] op_sel_hi:[1,0,1]
	v_pk_fma_f32 v[132:133], v[6:7], v[108:109], v[132:133] op_sel_hi:[1,0,1]
	v_pk_fma_f32 v[134:135], v[8:9], v[108:109], v[134:135] op_sel_hi:[1,0,1]
	v_pk_fma_f32 v[136:137], v[10:11], v[108:109], v[136:137] op_sel_hi:[1,0,1]
	v_pk_fma_f32 v[138:139], v[12:13], v[108:109], v[138:139] op_sel_hi:[1,0,1]
	v_pk_fma_f32 v[140:141], v[14:15], v[108:109], v[140:141] op_sel_hi:[1,0,1]
	v_pk_fma_f32 v[142:143], v[16:17], v[108:109], v[142:143] op_sel_hi:[1,0,1]
	v_pk_fma_f32 v[144:145], v[18:19], v[108:109], v[150:151] op_sel_hi:[1,0,1]
	v_pk_fma_f32 v[146:147], v[20:21], v[108:109], v[152:153] op_sel_hi:[1,0,1]
	v_pk_fma_f32 v[148:149], v[22:23], v[108:109], v[154:155] op_sel_hi:[1,0,1]
	v_pk_fma_f32 v[150:151], v[24:25], v[108:109], v[156:157] op_sel_hi:[1,0,1]
	v_pk_fma_f32 v[152:153], v[26:27], v[108:109], v[158:159] op_sel_hi:[1,0,1]
	v_pk_fma_f32 v[154:155], v[28:29], v[108:109], v[160:161] op_sel_hi:[1,0,1]
	v_pk_fma_f32 v[156:157], v[30:31], v[108:109], v[162:163] op_sel_hi:[1,0,1]
	v_cndmask_b32_e64 v108, v0, v1, s[0:1]
	s_waitcnt vmcnt(6)
; DI void phase_peer_out(const Params& p, char* lds) {
;     ...
;       for (int k = 0; k < 8; ++k) {
;         const float c0 = __uint_as_float(__builtin_amdgcn_readlane(__float_as_uint(coefv[0]), kb * 8 + k)), c1 = __uint_as_float(__builtin_amdgcn_readlane(__float_as_uint(coefv[1]), kb * 8 + k));
;         const float cf = hb ? c1 : c0;
;         const f32x2 c2 = {cf, cf};
;         const v32f f = __builtin_amdgcn_cvt_scalef32_pk32_f32_fp6(qb[k], 1.0f);
; #pragma unroll
;         for (int i = 0; i < 16; ++i) o2[i] = f32x2{f[2 * i], f[2 * i + 1]} * c2 + o2[i];
;       }
;     }
;     float s = 0.f;
; #pragma unroll
;     for (int i = 0; i < 16; ++i) {
;       o2[i].x += __shfl_xor(o2[i].x, 32); o2[i].y += __shfl_xor(o2[i].y, 32);
;       o2[i] = x2[i] * f32x2{ALPHA, ALPHA} + o2[i]; s += o2[i].x + o2[i].y;
	v_cvt_scalef32_pk32_f32_fp6 v[0:31], v[50:55], 1.0
	v_readlane_b32 s12, v106, 61
	v_readlane_b32 s13, v109, 61
	v_pk_fma_f32 v[50:51], v[0:1], v[108:109], v[126:127] op_sel_hi:[1,0,1]
	v_mov_b32_e32 v1, s12
	v_mov_b32_e32 v0, s13
	v_pk_fma_f32 v[52:53], v[2:3], v[108:109], v[128:129] op_sel_hi:[1,0,1]
	v_pk_fma_f32 v[54:55], v[4:5], v[108:109], v[130:131] op_sel_hi:[1,0,1]
	v_pk_fma_f32 v[126:127], v[6:7], v[108:109], v[132:133] op_sel_hi:[1,0,1]
	v_pk_fma_f32 v[128:129], v[8:9], v[108:109], v[134:135] op_sel_hi:[1,0,1]
	v_pk_fma_f32 v[130:131], v[10:11], v[108:109], v[136:137] op_sel_hi:[1,0,1]
	v_pk_fma_f32 v[132:133], v[12:13], v[108:109], v[138:139] op_sel_hi:[1,0,1]
	v_pk_fma_f32 v[134:135], v[14:15], v[108:109], v[140:141] op_sel_hi:[1,0,1]
	v_pk_fma_f32 v[136:137], v[16:17], v[108:109], v[142:143] op_sel_hi:[1,0,1]
	v_pk_fma_f32 v[138:139], v[18:19], v[108:109], v[144:145] op_sel_hi:[1,0,1]
	v_pk_fma_f32 v[140:141], v[20:21], v[108:109], v[146:147] op_sel_hi:[1,0,1]
	v_pk_fma_f32 v[142:143], v[22:23], v[108:109], v[148:149] op_sel_hi:[1,0,1]
	v_pk_fma_f32 v[144:145], v[24:25], v[108:109], v[150:151] op_sel_hi:[1,0,1]
	v_pk_fma_f32 v[146:147], v[26:27], v[108:109], v[152:153] op_sel_hi:[1,0,1]
	v_pk_fma_f32 v[148:149], v[28:29], v[108:109], v[154:155] op_sel_hi:[1,0,1]
	v_pk_fma_f32 v[150:151], v[30:31], v[108:109], v[156:157] op_sel_hi:[1,0,1]
	v_cndmask_b32_e64 v108, v0, v1, s[0:1]
	s_waitcnt vmcnt(4)
	v_cvt_scalef32_pk32_f32_fp6 v[0:31], v[44:49], 1.0
	v_readlane_b32 s12, v106, 62
	v_readlane_b32 s13, v109, 62
	v_pk_fma_f32 v[44:45], v[0:1], v[108:109], v[50:51] op_sel_hi:[1,0,1]
	v_mov_b32_e32 v1, s12
	v_mov_b32_e32 v0, s13
	v_pk_fma_f32 v[46:47], v[2:3], v[108:109], v[52:53] op_sel_hi:[1,0,1]
	v_pk_fma_f32 v[48:49], v[4:5], v[108:109], v[54:55] op_sel_hi:[1,0,1]
	v_pk_fma_f32 v[50:51], v[6:7], v[108:109], v[126:127] op_sel_hi:[1,0,1]
	v_pk_fma_f32 v[52:53], v[8:9], v[108:109], v[128:129] op_sel_hi:[1,0,1]
	v_pk_fma_f32 v[54:55], v[10:11], v[108:109], v[130:131] op_sel_hi:[1,0,1]
	v_pk_fma_f32 v[126:127], v[12:13], v[108:109], v[132:133] op_sel_hi:[1,0,1]
	v_pk_fma_f32 v[128:129], v[14:15], v[108:109], v[134:135] op_sel_hi:[1,0,1]
	v_pk_fma_f32 v[130:131], v[16:17], v[108:109], v[136:137] op_sel_hi:[1,0,1]
	v_pk_fma_f32 v[132:133], v[18:19], v[108:109], v[138:139] op_sel_hi:[1,0,1]
	v_pk_fma_f32 v[134:135], v[20:21], v[108:109], v[140:141] op_sel_hi:[1,0,1]
	v_pk_fma_f32 v[136:137], v[22:23], v[108:109], v[142:143] op_sel_hi:[1,0,1]
	v_pk_fma_f32 v[138:139], v[24:25], v[108:109], v[144:145] op_sel_hi:[1,0,1]
	v_pk_fma_f32 v[140:141], v[26:27], v[108:109], v[146:147] op_sel_hi:[1,0,1]
	v_pk_fma_f32 v[142:143], v[28:29], v[108:109], v[148:149] op_sel_hi:[1,0,1]
	v_pk_fma_f32 v[144:145], v[30:31], v[108:109], v[150:151] op_sel_hi:[1,0,1]
	v_cndmask_b32_e64 v108, v0, v1, s[0:1]
	s_waitcnt vmcnt(1)
	v_cvt_scalef32_pk32_f32_fp6 v[0:31], v[38:43], 1.0
	v_readlane_b32 s12, v106, 63
	v_readlane_b32 s13, v109, 63
	v_pk_fma_f32 v[38:39], v[0:1], v[108:109], v[44:45] op_sel_hi:[1,0,1]
	v_mov_b32_e32 v1, s12
	v_mov_b32_e32 v0, s13
	v_pk_fma_f32 v[40:41], v[2:3], v[108:109], v[46:47] op_sel_hi:[1,0,1]
	v_pk_fma_f32 v[42:43], v[4:5], v[108:109], v[48:49] op_sel_hi:[1,0,1]
	v_pk_fma_f32 v[44:45], v[6:7], v[108:109], v[50:51] op_sel_hi:[1,0,1]
	v_pk_fma_f32 v[46:47], v[8:9], v[108:109], v[52:53] op_sel_hi:[1,0,1]
	v_pk_fma_f32 v[48:49], v[10:11], v[108:109], v[54:55] op_sel_hi:[1,0,1]
	v_pk_fma_f32 v[50:51], v[12:13], v[108:109], v[126:127] op_sel_hi:[1,0,1]
	v_pk_fma_f32 v[52:53], v[14:15], v[108:109], v[128:129] op_sel_hi:[1,0,1]
	v_pk_fma_f32 v[54:55], v[16:17], v[108:109], v[130:131] op_sel_hi:[1,0,1]
	v_pk_fma_f32 v[126:127], v[18:19], v[108:109], v[132:133] op_sel_hi:[1,0,1]
	v_pk_fma_f32 v[128:129], v[20:21], v[108:109], v[134:135] op_sel_hi:[1,0,1]
	v_pk_fma_f32 v[130:131], v[22:23], v[108:109], v[136:137] op_sel_hi:[1,0,1]
	v_pk_fma_f32 v[132:133], v[24:25], v[108:109], v[138:139] op_sel_hi:[1,0,1]
	v_pk_fma_f32 v[134:135], v[26:27], v[108:109], v[140:141] op_sel_hi:[1,0,1]
	v_pk_fma_f32 v[136:137], v[28:29], v[108:109], v[142:143] op_sel_hi:[1,0,1]
	v_pk_fma_f32 v[138:139], v[30:31], v[108:109], v[144:145] op_sel_hi:[1,0,1]
	v_cndmask_b32_e64 v106, v0, v1, s[0:1]
	s_waitcnt vmcnt(0)
	v_cvt_scalef32_pk32_f32_fp6 v[0:31], v[32:37], 1.0
	v_pk_fma_f32 v[0:1], v[0:1], v[106:107], v[38:39] op_sel_hi:[1,0,1]
	v_pk_fma_f32 v[32:33], v[8:9], v[106:107], v[46:47] op_sel_hi:[1,0,1]
	ds_bpermute_b32 v8, v113, v0
	ds_bpermute_b32 v9, v113, v1
	v_pk_fma_f32 v[2:3], v[2:3], v[106:107], v[40:41] op_sel_hi:[1,0,1]
	v_pk_fma_f32 v[34:35], v[10:11], v[106:107], v[48:49] op_sel_hi:[1,0,1]
	ds_bpermute_b32 v10, v113, v2
	ds_bpermute_b32 v11, v113, v3
	s_waitcnt lgkmcnt(2)
	v_pk_add_f32 v[0:1], v[0:1], v[8:9]
	v_pk_fma_f32 v[36:37], v[12:13], v[106:107], v[50:51] op_sel_hi:[1,0,1]
	v_pk_fma_f32 v[12:13], v[94:95], s[20:21], v[0:1] op_sel_hi:[1,0,1]
	v_pk_fma_f32 v[4:5], v[4:5], v[106:107], v[42:43] op_sel_hi:[1,0,1]
	v_add_f32_e32 v0, v12, v13
	v_add_f32_e32 v8, 0, v0
	s_waitcnt lgkmcnt(0)
	v_pk_add_f32 v[0:1], v[2:3], v[10:11]
	v_pk_fma_f32 v[38:39], v[14:15], v[106:107], v[52:53] op_sel_hi:[1,0,1]
	v_pk_fma_f32 v[14:15], v[92:93], s[20:21], v[0:1] op_sel_hi:[1,0,1]
	ds_bpermute_b32 v0, v113, v4
	ds_bpermute_b32 v1, v113, v5
	v_pk_fma_f32 v[6:7], v[6:7], v[106:107], v[44:45] op_sel_hi:[1,0,1]
	v_add_f32_e32 v2, v14, v15
	v_add_f32_e32 v10, v2, v8
	ds_bpermute_b32 v2, v113, v6
	ds_bpermute_b32 v3, v113, v7
	s_waitcnt lgkmcnt(2)
; DI void phase_peer_out(const Params& p, char* lds) {
;     ...
;     for (int i = 0; i < 16; ++i) {
;       o2[i].x += __shfl_xor(o2[i].x, 32); o2[i].y += __shfl_xor(o2[i].y, 32);
;       o2[i] = x2[i] * f32x2{ALPHA, ALPHA} + o2[i]; s += o2[i].x + o2[i].y;
;     }
;     for (int o = 16; o; o >>= 1) s += __shfl_xor(s, o);
	v_pk_add_f32 v[0:1], v[4:5], v[0:1]
	v_pk_fma_f32 v[40:41], v[22:23], v[106:107], v[130:131] op_sel_hi:[1,0,1]
	v_pk_fma_f32 v[8:9], v[86:87], s[20:21], v[0:1] op_sel_hi:[1,0,1]
	v_pk_fma_f32 v[16:17], v[16:17], v[106:107], v[54:55] op_sel_hi:[1,0,1]
	v_add_f32_e32 v0, v8, v9
	v_add_f32_e32 v4, v0, v10
	s_waitcnt lgkmcnt(0)
	v_pk_add_f32 v[0:1], v[6:7], v[2:3]
	ds_bpermute_b32 v3, v113, v35
	v_pk_fma_f32 v[10:11], v[100:101], s[20:21], v[0:1] op_sel_hi:[1,0,1]
	ds_bpermute_b32 v0, v113, v32
	ds_bpermute_b32 v1, v113, v33
	v_add_f32_e32 v2, v10, v11
	v_add_f32_e32 v6, v2, v4
	ds_bpermute_b32 v2, v113, v34
	v_pk_fma_f32 v[42:43], v[26:27], v[106:107], v[134:135] op_sel_hi:[1,0,1]
	s_waitcnt lgkmcnt(1)
	v_pk_add_f32 v[0:1], v[32:33], v[0:1]
	v_pk_fma_f32 v[18:19], v[18:19], v[106:107], v[126:127] op_sel_hi:[1,0,1]
	v_pk_fma_f32 v[4:5], v[104:105], s[20:21], v[0:1] op_sel_hi:[1,0,1]
	v_pk_fma_f32 v[46:47], v[30:31], v[106:107], v[138:139] op_sel_hi:[1,0,1]
	v_add_f32_e32 v0, v4, v5
	v_add_f32_e32 v22, v0, v6
	s_waitcnt lgkmcnt(0)
	v_pk_add_f32 v[0:1], v[34:35], v[2:3]
	ds_bpermute_b32 v3, v113, v39
	v_pk_fma_f32 v[6:7], v[102:103], s[20:21], v[0:1] op_sel_hi:[1,0,1]
	ds_bpermute_b32 v0, v113, v36
	ds_bpermute_b32 v1, v113, v37
	v_add_f32_e32 v2, v6, v7
	v_add_f32_e32 v22, v2, v22
	ds_bpermute_b32 v2, v113, v38
	v_pk_fma_f32 v[44:45], v[28:29], v[106:107], v[136:137] op_sel_hi:[1,0,1]
	s_waitcnt lgkmcnt(1)
	v_pk_add_f32 v[0:1], v[36:37], v[0:1]
	v_pk_fma_f32 v[20:21], v[20:21], v[106:107], v[128:129] op_sel_hi:[1,0,1]
	v_pk_fma_f32 v[0:1], v[98:99], s[20:21], v[0:1] op_sel_hi:[1,0,1]
	s_waitcnt lgkmcnt(0)
	v_pk_add_f32 v[2:3], v[38:39], v[2:3]
	v_add_f32_e32 v23, v0, v1
	v_add_f32_e32 v26, v22, v23
	ds_bpermute_b32 v22, v113, v16
	ds_bpermute_b32 v23, v113, v17
	v_pk_fma_f32 v[2:3], v[96:97], s[20:21], v[2:3] op_sel_hi:[1,0,1]
	v_pk_fma_f32 v[24:25], v[24:25], v[106:107], v[132:133] op_sel_hi:[1,0,1]
	v_add_f32_e32 v27, v2, v3
	v_add_f32_e32 v30, v26, v27
	ds_bpermute_b32 v26, v113, v18
	ds_bpermute_b32 v27, v113, v19
	s_waitcnt lgkmcnt(2)
	v_pk_add_f32 v[16:17], v[16:17], v[22:23]
	ds_bpermute_b32 v33, v113, v47
	v_pk_fma_f32 v[28:29], v[90:91], s[20:21], v[16:17] op_sel_hi:[1,0,1]
	s_nop 0
	v_add_f32_e32 v16, v28, v29
	v_add_f32_e32 v22, v30, v16
	s_waitcnt lgkmcnt(1)
	v_pk_add_f32 v[16:17], v[18:19], v[26:27]
	ds_bpermute_b32 v18, v113, v40
	v_pk_fma_f32 v[30:31], v[88:89], s[20:21], v[16:17] op_sel_hi:[1,0,1]
	ds_bpermute_b32 v16, v113, v20
	ds_bpermute_b32 v17, v113, v21
	ds_bpermute_b32 v19, v113, v41
	v_add_f32_e32 v23, v30, v31
	v_add_f32_e32 v32, v22, v23
	s_waitcnt lgkmcnt(1)
	v_pk_add_f32 v[16:17], v[20:21], v[16:17]
	s_nop 0
	v_pk_fma_f32 v[22:23], v[84:85], s[20:21], v[16:17] op_sel_hi:[1,0,1]
	s_waitcnt lgkmcnt(0)
	v_pk_add_f32 v[16:17], v[40:41], v[18:19]
	v_mov_b32_e32 v18, v23
	v_pk_fma_f32 v[26:27], v[82:83], s[20:21], v[16:17] op_sel_hi:[1,0,1]
	v_mov_b32_e32 v16, v22
	v_mov_b32_e32 v17, v26
	v_mov_b32_e32 v19, v27
	v_pk_add_f32 v[16:17], v[16:17], v[18:19]
	ds_bpermute_b32 v18, v113, v24
	ds_bpermute_b32 v19, v113, v25
	ds_bpermute_b32 v20, v113, v42
	ds_bpermute_b32 v21, v113, v43
	v_add_f32_e32 v16, v32, v16
	v_add_f32_e32 v34, v16, v17
	s_waitcnt lgkmcnt(2)
	v_pk_add_f32 v[16:17], v[24:25], v[18:19]
	ds_bpermute_b32 v32, v113, v46
	v_pk_fma_f32 v[18:19], v[78:79], s[20:21], v[16:17] op_sel_hi:[1,0,1]
	s_waitcnt lgkmcnt(1)
	v_pk_add_f32 v[16:17], v[42:43], v[20:21]
	v_mov_b32_e32 v20, v19
	v_pk_fma_f32 v[24:25], v[76:77], s[20:21], v[16:17] op_sel_hi:[1,0,1]
	v_mov_b32_e32 v16, v18
	v_mov_b32_e32 v17, v24
	v_mov_b32_e32 v21, v25
	v_pk_add_f32 v[16:17], v[16:17], v[20:21]
	ds_bpermute_b32 v20, v113, v44
	ds_bpermute_b32 v21, v113, v45
	v_add_f32_e32 v16, v34, v16
	v_add_f32_e32 v36, v16, v17
	v_mov_b32_e32 v43, v22
	s_waitcnt lgkmcnt(0)
	v_pk_add_f32 v[16:17], v[44:45], v[20:21]
	v_pk_add_f32 v[20:21], v[46:47], v[32:33]
	v_pk_fma_f32 v[16:17], v[74:75], s[20:21], v[16:17] op_sel_hi:[1,0,1]
	v_pk_fma_f32 v[20:21], v[80:81], s[20:21], v[20:21] op_sel_hi:[1,0,1]
	v_mov_b32_e32 v32, v16
	v_mov_b32_e32 v33, v20
	v_mov_b32_e32 v34, v17
	v_mov_b32_e32 v35, v21
	v_pk_add_f32 v[32:33], v[32:33], v[34:35]
	v_mov_b32_e32 v44, v27
	v_add_f32_e32 v32, v36, v32
	v_add_f32_e32 v32, v32, v33
	ds_bpermute_b32 v33, v118, v32
	v_mov_b32_e32 v45, v23
	s_waitcnt lgkmcnt(0)
	v_add_f32_e32 v32, v32, v33
	ds_bpermute_b32 v33, v114, v32
	s_waitcnt lgkmcnt(0)
	v_add_f32_e32 v32, v32, v33
	ds_bpermute_b32 v33, v115, v32
	s_waitcnt lgkmcnt(0)
	v_add_f32_e32 v32, v32, v33
	ds_bpermute_b32 v33, v116, v32
	s_waitcnt lgkmcnt(0)
	v_add_f32_e32 v32, v32, v33
	ds_bpermute_b32 v33, v117, v32
	s_waitcnt lgkmcnt(0)
; DI void phase_peer_out(const Params& p, char* lds) {
;     ...
;     for (int o = 16; o; o >>= 1) s += __shfl_xor(s, o);
;     const float mu = s * (1.f / 1024.f);
;     float q = 0.f;
; #pragma unroll
;     for (int i = 0; i < 16; ++i) { const float a = o2[i].x - mu, bq = o2[i].y - mu; q += a * a + bq * bq; }
;     for (int o = 16; o; o >>= 1) q += __shfl_xor(q, o);
;     const float rstd = rsqrtf(q * (1.f / 1024.f) + LN_EPS);
;     float* orow = p.out + (size_t)t * 1024 + 32 * l5 + 16 * hb;
; #pragma unroll
;     for (int q4 = 0; q4 < 4; ++q4) {
;       const float4 gg = *(const float4*)(g3 + 32 * l5 + 16 * hb + 4 * q4), bb = *(const float4*)(b3 + 32 * l5 + 16 * hb + 4 * q4);
;       const f32x2 a0 = hb ? o2[8 + 2 * q4] : o2[2 * q4], a1 = hb ? o2[8 + 2 * q4 + 1] : o2[2 * q4 + 1];
;       float4 o;
;       o.x = (a0.x - mu) * rstd * gg.x + bb.x; o.y = (a0.y - mu) * rstd * gg.y + bb.y;
;       o.z = (a1.x - mu) * rstd * gg.z + bb.z; o.w = (a1.y - mu) * rstd * gg.w + bb.w;
;       *(float4*)(orow + 4 * q4) = o;
;     }
	v_add_f32_e32 v33, v32, v33
	v_fmamk_f32 v35, v33, 0xba800000, v13
	v_fmamk_f32 v34, v33, 0xba800000, v12
	v_mul_f32_e32 v35, v35, v35
	v_fmamk_f32 v36, v33, 0xba800000, v15
	v_fmac_f32_e32 v35, v34, v34
	v_fmamk_f32 v34, v33, 0xba800000, v14
	v_mul_f32_e32 v36, v36, v36
	v_fmac_f32_e32 v36, v34, v34
	v_add_f32_e32 v34, v35, v36
	v_fmamk_f32 v36, v33, 0xba800000, v9
	v_fmamk_f32 v35, v33, 0xba800000, v8
	v_mul_f32_e32 v36, v36, v36
	v_fmac_f32_e32 v36, v35, v35
	v_add_f32_e32 v34, v36, v34
	v_fmamk_f32 v36, v33, 0xba800000, v11
	v_fmamk_f32 v35, v33, 0xba800000, v10
	v_mul_f32_e32 v36, v36, v36
	v_fmac_f32_e32 v36, v35, v35
	v_add_f32_e32 v34, v36, v34
	v_fmamk_f32 v36, v33, 0xba800000, v5
	v_fmamk_f32 v35, v33, 0xba800000, v4
	v_mul_f32_e32 v36, v36, v36
	v_fmac_f32_e32 v36, v35, v35
	v_add_f32_e32 v34, v36, v34
	v_fmamk_f32 v36, v33, 0xba800000, v7
	v_fmamk_f32 v35, v33, 0xba800000, v6
	v_mul_f32_e32 v36, v36, v36
	v_fmac_f32_e32 v36, v35, v35
	v_add_f32_e32 v34, v36, v34
	v_fmamk_f32 v36, v33, 0xba800000, v1
	v_fmamk_f32 v35, v33, 0xba800000, v0
	v_mul_f32_e32 v36, v36, v36
	v_fmac_f32_e32 v36, v35, v35
	v_add_f32_e32 v34, v36, v34
	v_fmamk_f32 v36, v33, 0xba800000, v3
	v_fmamk_f32 v35, v33, 0xba800000, v2
	v_mul_f32_e32 v36, v36, v36
	v_fmac_f32_e32 v36, v35, v35
	v_add_f32_e32 v34, v36, v34
	v_fmamk_f32 v36, v33, 0xba800000, v29
	v_fmamk_f32 v35, v33, 0xba800000, v28
	v_mul_f32_e32 v36, v36, v36
	v_fmac_f32_e32 v36, v35, v35
	v_mul_f32_e32 v32, 0x3a800000, v33
	v_add_f32_e32 v42, v36, v34
	v_fmamk_f32 v34, v33, 0xba800000, v30
	v_fmamk_f32 v33, v33, 0xba800000, v31
	v_mul_f32_e32 v33, v33, v33
	v_fmac_f32_e32 v33, v34, v34
	v_add_f32_e32 v33, v33, v42
	v_mov_b32_e32 v42, v26
	v_pk_add_f32 v[44:45], v[44:45], v[32:33] op_sel_hi:[1,0] neg_lo:[0,1] neg_hi:[0,1]
	v_pk_add_f32 v[42:43], v[42:43], v[32:33] op_sel_hi:[1,0] neg_lo:[0,1] neg_hi:[0,1]
	v_pk_mul_f32 v[44:45], v[44:45], v[44:45]
	v_cndmask_b32_e64 v13, v29, v13, s[0:1]
	v_pk_fma_f32 v[42:43], v[42:43], v[42:43], v[44:45]
	v_mov_b32_e32 v44, v25
	v_add_f32_e32 v33, v43, v33
	v_add_f32_e32 v33, v42, v33
	v_mov_b32_e32 v45, v19
	v_mov_b32_e32 v42, v24
	v_mov_b32_e32 v43, v18
	v_pk_add_f32 v[44:45], v[44:45], v[32:33] op_sel_hi:[1,0] neg_lo:[0,1] neg_hi:[0,1]
	v_pk_add_f32 v[42:43], v[42:43], v[32:33] op_sel_hi:[1,0] neg_lo:[0,1] neg_hi:[0,1]
	v_pk_mul_f32 v[44:45], v[44:45], v[44:45]
	v_cndmask_b32_e64 v12, v28, v12, s[0:1]
	v_pk_fma_f32 v[42:43], v[42:43], v[42:43], v[44:45]
	v_mov_b32_e32 v44, v21
	v_add_f32_e32 v33, v43, v33
	v_add_f32_e32 v33, v42, v33
	v_mov_b32_e32 v45, v17
	v_mov_b32_e32 v42, v20
	v_mov_b32_e32 v43, v16
	v_pk_add_f32 v[44:45], v[44:45], v[32:33] op_sel_hi:[1,0] neg_lo:[0,1] neg_hi:[0,1]
	v_pk_add_f32 v[42:43], v[42:43], v[32:33] op_sel_hi:[1,0] neg_lo:[0,1] neg_hi:[0,1]
	v_pk_mul_f32 v[44:45], v[44:45], v[44:45]
	v_cndmask_b32_e64 v15, v31, v15, s[0:1]
	v_pk_fma_f32 v[42:43], v[42:43], v[42:43], v[44:45]
	v_cndmask_b32_e64 v14, v30, v14, s[0:1]
	v_add_f32_e32 v33, v43, v33
	v_add_f32_e32 v33, v42, v33
	ds_bpermute_b32 v42, v118, v33
	v_lshlrev_b64 v[44:45], 12, v[60:61]
	v_lshl_add_u64 v[44:45], v[72:73], 0, v[44:45]
	v_cndmask_b32_e64 v9, v23, v9, s[0:1]
	v_cndmask_b32_e64 v8, v22, v8, s[0:1]
	s_waitcnt lgkmcnt(0)
	v_add_f32_e32 v33, v33, v42
	ds_bpermute_b32 v42, v114, v33
	v_cndmask_b32_e64 v11, v27, v11, s[0:1]
	v_cndmask_b32_e64 v10, v26, v10, s[0:1]
	v_cndmask_b32_e64 v5, v19, v5, s[0:1]
	v_cndmask_b32_e64 v4, v18, v4, s[0:1]
	s_waitcnt lgkmcnt(0)
	v_add_f32_e32 v33, v33, v42
	ds_bpermute_b32 v42, v115, v33
	v_cndmask_b32_e64 v7, v25, v7, s[0:1]
	v_cndmask_b32_e64 v6, v24, v6, s[0:1]
	v_cndmask_b32_e64 v1, v17, v1, s[0:1]
	v_cndmask_b32_e64 v0, v16, v0, s[0:1]
	s_waitcnt lgkmcnt(0)
	v_add_f32_e32 v33, v33, v42
	ds_bpermute_b32 v42, v116, v33
	v_cndmask_b32_e64 v3, v21, v3, s[0:1]
	v_cndmask_b32_e64 v2, v20, v2, s[0:1]
	v_add_u32_e32 v60, s53, v60
	s_waitcnt lgkmcnt(0)
	v_add_f32_e32 v33, v33, v42
	ds_bpermute_b32 v42, v117, v33
	s_waitcnt lgkmcnt(0)
	v_add_f32_e32 v33, v33, v42
	v_fmamk_f32 v33, v33, 0x3a800000, v123
	v_mul_f32_e32 v42, 0x4b800000, v33
	v_cmp_gt_f32_e64 s[12:13], s35, v33
	s_nop 1
	v_cndmask_b32_e64 v33, v33, v42, s[12:13]
	v_rsq_f32_e32 v33, v33
	s_nop 0
	v_mul_f32_e32 v42, 0x45800000, v33
	v_cndmask_b32_e64 v42, v33, v42, s[12:13]
	v_pk_add_f32 v[12:13], v[12:13], v[32:33] op_sel_hi:[1,0] neg_lo:[0,1] neg_hi:[0,1]
	v_pk_add_f32 v[14:15], v[14:15], v[32:33] op_sel_hi:[1,0] neg_lo:[0,1] neg_hi:[0,1]
	v_pk_mul_f32 v[12:13], v[12:13], v[42:43] op_sel_hi:[1,0]
	v_pk_mul_f32 v[14:15], v[14:15], v[42:43] op_sel_hi:[1,0]
	v_pk_add_f32 v[8:9], v[8:9], v[32:33] op_sel_hi:[1,0] neg_lo:[0,1] neg_hi:[0,1]
	v_pk_fma_f32 v[12:13], v[184:185], v[12:13], v[200:201]
	v_pk_fma_f32 v[14:15], v[186:187], v[14:15], v[202:203]
	global_store_dwordx4 v[44:45], v[12:15], off nt
	v_pk_add_f32 v[10:11], v[10:11], v[32:33] op_sel_hi:[1,0] neg_lo:[0,1] neg_hi:[0,1]
	v_pk_mul_f32 v[8:9], v[8:9], v[42:43] op_sel_hi:[1,0]
	v_pk_mul_f32 v[10:11], v[10:11], v[42:43] op_sel_hi:[1,0]
	v_pk_add_f32 v[4:5], v[4:5], v[32:33] op_sel_hi:[1,0] neg_lo:[0,1] neg_hi:[0,1]
	v_pk_add_f32 v[6:7], v[6:7], v[32:33] op_sel_hi:[1,0] neg_lo:[0,1] neg_hi:[0,1]
	v_pk_mul_f32 v[4:5], v[4:5], v[42:43] op_sel_hi:[1,0]
	v_pk_mul_f32 v[6:7], v[6:7], v[42:43] op_sel_hi:[1,0]
	v_pk_add_f32 v[0:1], v[0:1], v[32:33] op_sel_hi:[1,0] neg_lo:[0,1] neg_hi:[0,1]
	v_pk_add_f32 v[2:3], v[2:3], v[32:33] op_sel_hi:[1,0] neg_lo:[0,1] neg_hi:[0,1]
	v_pk_mul_f32 v[0:1], v[0:1], v[42:43] op_sel_hi:[1,0]
	v_pk_mul_f32 v[2:3], v[2:3], v[42:43] op_sel_hi:[1,0]
	v_cmp_lt_i32_e64 s[12:13], s36, v60
	s_or_b64 s[18:19], s[12:13], s[18:19]
	v_pk_fma_f32 v[8:9], v[188:189], v[8:9], v[204:205]
	v_pk_fma_f32 v[10:11], v[190:191], v[10:11], v[206:207]
	global_store_dwordx4 v[44:45], v[8:11], off offset:16 nt
	v_pk_fma_f32 v[4:5], v[192:193], v[4:5], v[208:209]
	v_pk_fma_f32 v[6:7], v[194:195], v[6:7], v[210:211]
	global_store_dwordx4 v[44:45], v[4:7], off offset:32 nt
	v_pk_fma_f32 v[0:1], v[0:1], v[196:197], v[212:213]
	v_pk_fma_f32 v[2:3], v[2:3], v[198:199], v[214:215]
	global_store_dwordx4 v[44:45], v[0:3], off offset:48 nt
	s_andn2_b64 exec, exec, s[18:19]
	s_cbranch_execz .LBB0_1211
